# no closing grid sync; near-diagonal bias lookups in cmp pass1/pass2 and window loops: eight LDS reads issued together (masked lanes read a -inf slot) instead of eight exec-masked read-and-wait blocks
# speedup vs baseline: 1.0140x; 1.0079x over previous
.LBB0_1260:
	s_add_i32 s16, s13, 1
	s_waitcnt vmcnt(0)
	v_mfma_f32_16x16x32_bf16 v[52:55], v[48:51], v[12:15], 0
	s_min_i32 s48, s16, s12
	s_lshl_b64 s[4:5], s[48:49], 12
	v_lshl_add_u64 v[68:69], v[84:85], 0, s[4:5]
	global_load_dwordx4 v[64:67], v[68:69], off
	global_load_dwordx4 v[60:63], v[68:69], off offset:1024
	v_mfma_f32_16x16x32_bf16 v[76:79], v[44:47], v[16:19], v[52:55]
	global_load_dwordx4 v[56:59], v[68:69], off offset:2048
	s_nop 1
	global_load_dwordx4 v[52:55], v[68:69], off offset:3072
	s_add_i32 s4, s15, 0x200
	s_cmpk_lt_i32 s4, 0x7f
	v_mfma_f32_16x16x32_bf16 v[68:71], v[2:5], v[12:15], 0
	s_cselect_b64 s[10:11], -1, 0
	s_cmpk_gt_i32 s4, 0x7e
	s_mov_b64 s[6:7], -1
	v_mfma_f32_16x16x32_bf16 v[72:75], v[6:9], v[16:19], v[68:71]
	s_cbranch_scc1 .LBB0_1278
	v_add_u32_e32 v95, s15, v94
	s_nop 1
	v_add_u32_e32 v70, 0x3f0, v95
	v_mov_b32_e32 v190, 0x25ffc
	v_cmp_lt_i32_e32 vcc, -1, v70
	v_mov_b32_e32 v69, 0xff800000
	v_mov_b32_e32 v68, 0xff800000
	ds_write_b32 v190, v68
	v_min_u32_e32 v68, 0x7f, v70
	v_lshl_add_u32 v68, v68, 2, s87
	v_cndmask_b32_e32 v68, v190, v68, vcc
	ds_read_b32 v68, v68
	v_add_u32_e32 v70, 0x3e0, v95
	v_cmp_lt_i32_e32 vcc, -1, v70
	v_min_u32_e32 v69, 0x7f, v70
	v_lshl_add_u32 v69, v69, 2, s87
	v_cndmask_b32_e32 v69, v190, v69, vcc
	ds_read_b32 v69, v69
	v_add_u32_e32 v80, 0x3d0, v95
	v_cmp_lt_i32_e32 vcc, -1, v80
	v_mov_b32_e32 v71, 0xff800000
	v_mov_b32_e32 v70, 0xff800000
	v_min_u32_e32 v70, 0x7f, v80
	v_lshl_add_u32 v70, v70, 2, s87
	v_cndmask_b32_e32 v70, v190, v70, vcc
	ds_read_b32 v70, v70
	v_add_u32_e32 v80, 0x3c0, v95
	v_cmp_lt_i32_e32 vcc, -1, v80
	v_min_u32_e32 v71, 0x7f, v80
	v_lshl_add_u32 v71, v71, 2, s87
	v_cndmask_b32_e32 v71, v190, v71, vcc
	ds_read_b32 v71, v71
	v_add_u32_e32 v82, 0x2f0, v95
	v_cmp_lt_i32_e32 vcc, -1, v82
	v_mov_b32_e32 v81, 0xff800000
	v_mov_b32_e32 v80, 0xff800000
	v_min_u32_e32 v80, 0x7f, v82
	v_lshl_add_u32 v80, v80, 2, s87
	v_cndmask_b32_e32 v80, v190, v80, vcc
	ds_read_b32 v80, v80
	v_add_u32_e32 v82, 0x2e0, v95
	v_cmp_lt_i32_e32 vcc, -1, v82
	v_min_u32_e32 v81, 0x7f, v82
	v_lshl_add_u32 v81, v81, 2, s87
	v_cndmask_b32_e32 v81, v190, v81, vcc
	ds_read_b32 v81, v81
	v_add_u32_e32 v96, 0x2d0, v95
	v_cmp_lt_i32_e32 vcc, -1, v96
	v_mov_b32_e32 v83, 0xff800000
	v_mov_b32_e32 v82, 0xff800000
	v_min_u32_e32 v82, 0x7f, v96
	v_lshl_add_u32 v82, v82, 2, s87
	v_cndmask_b32_e32 v82, v190, v82, vcc
	ds_read_b32 v82, v82
	v_add_u32_e32 v95, 0x2c0, v95
	v_cmp_lt_i32_e32 vcc, -1, v95
	v_min_u32_e32 v83, 0x7f, v95
	v_lshl_add_u32 v83, v83, 2, s87
	v_cndmask_b32_e32 v83, v190, v83, vcc
	ds_read_b32 v83, v83
	s_waitcnt lgkmcnt(0)
	v_add_f32_e32 v68, v76, v68
	v_mul_f32_e32 v68, 0x3fb8aa3b, v68
	v_add_f32_e32 v69, v77, v69
	v_mul_f32_e32 v69, 0x3fb8aa3b, v69
	v_add_f32_e32 v70, v78, v70
	v_mul_f32_e32 v70, 0x3fb8aa3b, v70
	v_add_f32_e32 v71, v79, v71
	v_mul_f32_e32 v71, 0x3fb8aa3b, v71
	v_add_f32_e32 v80, v72, v80
	v_mul_f32_e32 v80, 0x3fb8aa3b, v80
	v_add_f32_e32 v81, v73, v81
	v_mul_f32_e32 v81, 0x3fb8aa3b, v81
	v_add_f32_e32 v82, v74, v82
	v_mul_f32_e32 v82, 0x3fb8aa3b, v82
	v_add_f32_e32 v83, v75, v83
	v_mul_f32_e32 v83, 0x3fb8aa3b, v83
	s_mov_b64 s[6:7], 0

.LBB0_1280:
	s_nop 4
	v_max_f32_e32 v72, v69, v69
	v_max_f32_e32 v73, v68, v68
	v_max_f32_e32 v72, v73, v72
	v_max_f32_e32 v73, v71, v71
	v_max_f32_e32 v74, v70, v70
	v_max_f32_e32 v73, v74, v73
	v_max_f32_e32 v74, v83, v83
	v_max_f32_e32 v75, v82, v82
	v_max_f32_e32 v74, v75, v74
	v_max3_f32 v74, v80, v81, v74
	v_max3_f32 v72, v72, v73, v74
	v_mov_b32_e32 v73, v72
	s_nop 1
	v_permlane16_swap_b32 v72, v73
	s_nop 1
	s_andn2_b64 vcc, exec, s[10:11]
	v_max_f32_e32 v73, v73, v73
	v_max_f32_e32 v72, v72, v72
	v_max_f32_e32 v72, v72, v73
	v_mov_b32_e32 v73, v72
	s_nop 1
	v_permlane32_swap_b32 v72, v73
	s_nop 1
	s_nop 0
	v_max3_f32 v95, v111, v72, v73
	v_sub_f32_e32 v68, v68, v95
	v_exp_f32_e32 v68, v68
	v_sub_f32_e32 v69, v69, v95
	v_exp_f32_e32 v69, v69
	v_sub_f32_e32 v70, v70, v95
	v_exp_f32_e32 v70, v70
	v_sub_f32_e32 v71, v71, v95
	v_exp_f32_e32 v71, v71
	v_sub_f32_e32 v72, v80, v95
	v_add_f32_e32 v68, 0, v68
	v_exp_f32_e32 v72, v72
	v_add_f32_e32 v68, v69, v68
	v_add_f32_e32 v68, v70, v68
	v_add_f32_e32 v68, v71, v68
	v_add_f32_e32 v72, v72, v68
	v_sub_f32_e32 v68, v81, v95
	v_exp_f32_e32 v73, v68
	v_sub_f32_e32 v68, v82, v95
	v_exp_f32_e32 v74, v68
	v_sub_f32_e32 v75, v83, v95
	v_mfma_f32_16x16x32_bf16 v[68:71], v[48:51], v[20:23], 0
	v_exp_f32_e32 v75, v75
	v_add_f32_e32 v72, v73, v72
	v_add_f32_e32 v72, v74, v72
	v_mfma_f32_16x16x32_bf16 v[76:79], v[44:47], v[24:27], v[68:71]
	v_add_f32_e32 v72, v75, v72
	v_mov_b32_e32 v73, v72
	s_nop 1
	v_permlane16_swap_b32 v72, v73
	s_nop 1
	v_mfma_f32_16x16x32_bf16 v[68:71], v[2:5], v[20:23], 0
	v_add_f32_e32 v104, v72, v73
	v_mov_b32_e32 v106, v104
	s_nop 1
	v_permlane32_swap_b32 v104, v106
	s_nop 1
	v_mfma_f32_16x16x32_bf16 v[72:75], v[6:9], v[24:27], v[68:71]
	s_nop 4
	v_cndmask_b32_e64 v68, 0, 1, s[10:11]
	v_cmp_ne_u32_e64 s[6:7], 1, v68
	s_mov_b64 s[10:11], -1
	s_cbranch_vccnz .LBB0_1298
	v_add_u32_e32 v96, s15, v94
	v_add_u32_e32 v70, 0x3f0, v96
	v_mov_b32_e32 v190, 0x25dfc
	v_cmp_lt_i32_e32 vcc, -1, v70
	v_mov_b32_e32 v69, 0xff800000
	v_mov_b32_e32 v68, 0xff800000
	ds_write_b32 v190, v68 offset:512
	v_min_u32_e32 v68, 0x7f, v70
	v_lshl_add_u32 v68, v68, 2, s87
	v_cndmask_b32_e32 v68, v190, v68, vcc
	ds_read_b32 v68, v68 offset:512
	v_add_u32_e32 v70, 0x3e0, v96
	v_cmp_lt_i32_e32 vcc, -1, v70
	v_min_u32_e32 v69, 0x7f, v70
	v_lshl_add_u32 v69, v69, 2, s87
	v_cndmask_b32_e32 v69, v190, v69, vcc
	ds_read_b32 v69, v69 offset:512
	v_add_u32_e32 v80, 0x3d0, v96
	v_cmp_lt_i32_e32 vcc, -1, v80
	v_mov_b32_e32 v71, 0xff800000
	v_mov_b32_e32 v70, 0xff800000
	v_min_u32_e32 v70, 0x7f, v80
	v_lshl_add_u32 v70, v70, 2, s87
	v_cndmask_b32_e32 v70, v190, v70, vcc
	ds_read_b32 v70, v70 offset:512
	v_add_u32_e32 v80, 0x3c0, v96
	v_cmp_lt_i32_e32 vcc, -1, v80
	v_min_u32_e32 v71, 0x7f, v80
	v_lshl_add_u32 v71, v71, 2, s87
	v_cndmask_b32_e32 v71, v190, v71, vcc
	ds_read_b32 v71, v71 offset:512
	v_add_u32_e32 v82, 0x2f0, v96
	v_cmp_lt_i32_e32 vcc, -1, v82
	v_mov_b32_e32 v81, 0xff800000
	v_mov_b32_e32 v80, 0xff800000
	v_min_u32_e32 v80, 0x7f, v82
	v_lshl_add_u32 v80, v80, 2, s87
	v_cndmask_b32_e32 v80, v190, v80, vcc
	ds_read_b32 v80, v80 offset:512
	v_add_u32_e32 v82, 0x2e0, v96
	v_cmp_lt_i32_e32 vcc, -1, v82
	v_min_u32_e32 v81, 0x7f, v82
	v_lshl_add_u32 v81, v81, 2, s87
	v_cndmask_b32_e32 v81, v190, v81, vcc
	ds_read_b32 v81, v81 offset:512
	v_add_u32_e32 v97, 0x2d0, v96
	v_cmp_lt_i32_e32 vcc, -1, v97
	v_mov_b32_e32 v83, 0xff800000
	v_mov_b32_e32 v82, 0xff800000
	v_min_u32_e32 v82, 0x7f, v97
	v_lshl_add_u32 v82, v82, 2, s87
	v_cndmask_b32_e32 v82, v190, v82, vcc
	ds_read_b32 v82, v82 offset:512
	v_add_u32_e32 v96, 0x2c0, v96
	v_cmp_lt_i32_e32 vcc, -1, v96
	v_min_u32_e32 v83, 0x7f, v96
	v_lshl_add_u32 v83, v83, 2, s87
	v_cndmask_b32_e32 v83, v190, v83, vcc
	ds_read_b32 v83, v83 offset:512
	s_waitcnt lgkmcnt(0)
	v_add_f32_e32 v68, v76, v68
	v_mul_f32_e32 v68, 0x3fb8aa3b, v68
	v_add_f32_e32 v69, v77, v69
	v_mul_f32_e32 v69, 0x3fb8aa3b, v69
	v_add_f32_e32 v70, v78, v70
	v_mul_f32_e32 v70, 0x3fb8aa3b, v70
	v_add_f32_e32 v71, v79, v71
	v_mul_f32_e32 v71, 0x3fb8aa3b, v71
	v_add_f32_e32 v80, v72, v80
	v_mul_f32_e32 v80, 0x3fb8aa3b, v80
	v_add_f32_e32 v81, v73, v81
	v_mul_f32_e32 v81, 0x3fb8aa3b, v81
	v_add_f32_e32 v82, v74, v82
	v_mul_f32_e32 v82, 0x3fb8aa3b, v82
	v_add_f32_e32 v83, v75, v83
	v_mul_f32_e32 v83, 0x3fb8aa3b, v83
	s_mov_b64 s[10:11], 0

.LBB0_1300:
	v_max_f32_e32 v72, v69, v69
	v_max_f32_e32 v73, v68, v68
	v_max_f32_e32 v72, v73, v72
	v_max_f32_e32 v73, v71, v71
	v_max_f32_e32 v74, v70, v70
	v_max_f32_e32 v73, v74, v73
	v_max_f32_e32 v74, v83, v83
	v_max_f32_e32 v75, v82, v82
	v_max_f32_e32 v74, v75, v74
	v_max3_f32 v74, v80, v81, v74
	v_max3_f32 v72, v72, v73, v74
	v_mov_b32_e32 v73, v72
	s_nop 1
	v_permlane16_swap_b32 v72, v73
	s_nop 1
	s_and_b64 vcc, exec, s[6:7]
	v_max_f32_e32 v73, v73, v73
	v_max_f32_e32 v72, v72, v72
	v_max_f32_e32 v72, v72, v73
	v_mov_b32_e32 v73, v72
	s_nop 1
	v_permlane32_swap_b32 v72, v73
	s_nop 1
	s_mov_b64 s[10:11], -1
	v_max3_f32 v96, v112, v72, v73
	v_sub_f32_e32 v68, v68, v96
	v_exp_f32_e32 v68, v68
	v_sub_f32_e32 v69, v69, v96
	v_exp_f32_e32 v69, v69
	v_sub_f32_e32 v70, v70, v96
	v_exp_f32_e32 v70, v70
	v_sub_f32_e32 v71, v71, v96
	v_exp_f32_e32 v71, v71
	v_sub_f32_e32 v72, v80, v96
	v_add_f32_e32 v68, 0, v68
	v_exp_f32_e32 v72, v72
	v_add_f32_e32 v68, v69, v68
	v_add_f32_e32 v68, v70, v68
	v_add_f32_e32 v68, v71, v68
	v_add_f32_e32 v72, v72, v68
	v_sub_f32_e32 v68, v81, v96
	v_exp_f32_e32 v73, v68
	v_sub_f32_e32 v68, v82, v96
	v_exp_f32_e32 v74, v68
	v_sub_f32_e32 v75, v83, v96
	v_mfma_f32_16x16x32_bf16 v[68:71], v[48:51], v[28:31], 0
	v_exp_f32_e32 v75, v75
	v_add_f32_e32 v72, v73, v72
	v_add_f32_e32 v72, v74, v72
	v_mfma_f32_16x16x32_bf16 v[76:79], v[44:47], v[32:35], v[68:71]
	v_add_f32_e32 v72, v75, v72
	v_mov_b32_e32 v73, v72
	s_nop 1
	v_permlane16_swap_b32 v72, v73
	s_nop 1
	v_mfma_f32_16x16x32_bf16 v[68:71], v[2:5], v[28:31], 0
	v_add_f32_e32 v105, v72, v73
	v_mov_b32_e32 v107, v105
	s_nop 1
	v_permlane32_swap_b32 v105, v107
	s_nop 1
	v_mfma_f32_16x16x32_bf16 v[72:75], v[6:9], v[32:35], v[68:71]
	s_cbranch_vccnz .LBB0_1318
	v_add_u32_e32 v97, s15, v94
	s_nop 2
	v_add_u32_e32 v70, 0x3f0, v97
	v_mov_b32_e32 v190, 0x25bfc
	v_cmp_lt_i32_e32 vcc, -1, v70
	v_mov_b32_e32 v69, 0xff800000
	v_mov_b32_e32 v68, 0xff800000
	ds_write_b32 v190, v68 offset:1024
	v_min_u32_e32 v68, 0x7f, v70
	v_lshl_add_u32 v68, v68, 2, s87
	v_cndmask_b32_e32 v68, v190, v68, vcc
	ds_read_b32 v68, v68 offset:1024
	v_add_u32_e32 v70, 0x3e0, v97
	v_cmp_lt_i32_e32 vcc, -1, v70
	v_min_u32_e32 v69, 0x7f, v70
	v_lshl_add_u32 v69, v69, 2, s87
	v_cndmask_b32_e32 v69, v190, v69, vcc
	ds_read_b32 v69, v69 offset:1024
	v_add_u32_e32 v80, 0x3d0, v97
	v_cmp_lt_i32_e32 vcc, -1, v80
	v_mov_b32_e32 v71, 0xff800000
	v_mov_b32_e32 v70, 0xff800000
	v_min_u32_e32 v70, 0x7f, v80
	v_lshl_add_u32 v70, v70, 2, s87
	v_cndmask_b32_e32 v70, v190, v70, vcc
	ds_read_b32 v70, v70 offset:1024
	v_add_u32_e32 v80, 0x3c0, v97
	v_cmp_lt_i32_e32 vcc, -1, v80
	v_min_u32_e32 v71, 0x7f, v80
	v_lshl_add_u32 v71, v71, 2, s87
	v_cndmask_b32_e32 v71, v190, v71, vcc
	ds_read_b32 v71, v71 offset:1024
	v_add_u32_e32 v82, 0x2f0, v97
	v_cmp_lt_i32_e32 vcc, -1, v82
	v_mov_b32_e32 v81, 0xff800000
	v_mov_b32_e32 v80, 0xff800000
	v_min_u32_e32 v80, 0x7f, v82
	v_lshl_add_u32 v80, v80, 2, s87
	v_cndmask_b32_e32 v80, v190, v80, vcc
	ds_read_b32 v80, v80 offset:1024
	v_add_u32_e32 v82, 0x2e0, v97
	v_cmp_lt_i32_e32 vcc, -1, v82
	v_min_u32_e32 v81, 0x7f, v82
	v_lshl_add_u32 v81, v81, 2, s87
	v_cndmask_b32_e32 v81, v190, v81, vcc
	ds_read_b32 v81, v81 offset:1024
	v_add_u32_e32 v103, 0x2d0, v97
	v_cmp_lt_i32_e32 vcc, -1, v103
	v_mov_b32_e32 v83, 0xff800000
	v_mov_b32_e32 v82, 0xff800000
	v_min_u32_e32 v82, 0x7f, v103
	v_lshl_add_u32 v82, v82, 2, s87
	v_cndmask_b32_e32 v82, v190, v82, vcc
	ds_read_b32 v82, v82 offset:1024
	v_add_u32_e32 v97, 0x2c0, v97
	v_cmp_lt_i32_e32 vcc, -1, v97
	v_min_u32_e32 v83, 0x7f, v97
	v_lshl_add_u32 v83, v83, 2, s87
	v_cndmask_b32_e32 v83, v190, v83, vcc
	ds_read_b32 v83, v83 offset:1024
	s_waitcnt lgkmcnt(0)
	v_add_f32_e32 v68, v76, v68
	v_mul_f32_e32 v68, 0x3fb8aa3b, v68
	v_add_f32_e32 v69, v77, v69
	v_mul_f32_e32 v69, 0x3fb8aa3b, v69
	v_add_f32_e32 v70, v78, v70
	v_mul_f32_e32 v70, 0x3fb8aa3b, v70
	v_add_f32_e32 v71, v79, v71
	v_mul_f32_e32 v71, 0x3fb8aa3b, v71
	v_add_f32_e32 v80, v72, v80
	v_mul_f32_e32 v80, 0x3fb8aa3b, v80
	v_add_f32_e32 v81, v73, v81
	v_mul_f32_e32 v81, 0x3fb8aa3b, v81
	v_add_f32_e32 v82, v74, v82
	v_mul_f32_e32 v82, 0x3fb8aa3b, v82
	v_add_f32_e32 v83, v75, v83
	v_mul_f32_e32 v83, 0x3fb8aa3b, v83
	s_mov_b64 s[10:11], 0

.LBB0_1320:
	s_nop 4
	v_max_f32_e32 v72, v69, v69
	v_max_f32_e32 v73, v68, v68
	v_max_f32_e32 v72, v73, v72
	v_max_f32_e32 v73, v71, v71
	v_max_f32_e32 v74, v70, v70
	v_max_f32_e32 v73, v74, v73
	v_max_f32_e32 v74, v83, v83
	v_max_f32_e32 v75, v82, v82
	v_max_f32_e32 v74, v75, v74
	v_max3_f32 v74, v80, v81, v74
	v_max3_f32 v72, v72, v73, v74
	v_mov_b32_e32 v73, v72
	s_nop 1
	v_permlane16_swap_b32 v72, v73
	s_nop 1
	v_mfma_f32_16x16x32_bf16 v[48:51], v[48:51], v[36:39], 0
	v_max_f32_e32 v73, v73, v73
	v_max_f32_e32 v72, v72, v72
	v_max_f32_e32 v72, v72, v73
	v_mov_b32_e32 v73, v72
	s_nop 1
	v_permlane32_swap_b32 v72, v73
	s_nop 1
	v_mfma_f32_16x16x32_bf16 v[2:5], v[2:5], v[36:39], 0
	v_max3_f32 v97, v113, v72, v73
	v_sub_f32_e32 v68, v68, v97
	v_exp_f32_e32 v68, v68
	v_sub_f32_e32 v69, v69, v97
	v_exp_f32_e32 v69, v69
	v_sub_f32_e32 v70, v70, v97
	v_exp_f32_e32 v70, v70
	v_sub_f32_e32 v71, v71, v97
	v_exp_f32_e32 v71, v71
	v_add_f32_e32 v68, 0, v68
	v_sub_f32_e32 v72, v80, v97
	v_exp_f32_e32 v72, v72
	v_add_f32_e32 v68, v69, v68
	v_sub_f32_e32 v69, v81, v97
	v_add_f32_e32 v68, v70, v68
	v_exp_f32_e32 v69, v69
	v_sub_f32_e32 v70, v82, v97
	v_add_f32_e32 v68, v71, v68
	v_exp_f32_e32 v70, v70
	v_sub_f32_e32 v71, v83, v97
	v_exp_f32_e32 v71, v71
	v_add_f32_e32 v68, v72, v68
	v_add_f32_e32 v68, v69, v68
	v_add_f32_e32 v68, v70, v68
	v_mfma_f32_16x16x32_bf16 v[44:47], v[44:47], v[40:43], v[48:51]
	s_and_b64 vcc, exec, s[6:7]
	s_mov_b64 s[6:7], -1
	s_nop 0
	v_add_f32_e32 v48, v71, v68
	v_mfma_f32_16x16x32_bf16 v[6:9], v[6:9], v[40:43], v[2:5]
	v_mov_b32_e32 v49, v48
	s_nop 1
	v_permlane16_swap_b32 v48, v49
	s_nop 1
	s_nop 0
	v_add_f32_e32 v68, v48, v49
	v_mov_b32_e32 v69, v68
	s_nop 1
	v_permlane32_swap_b32 v68, v69
	s_nop 1
	s_cbranch_vccnz .LBB0_1338
	v_add_u32_e32 v70, s15, v94
	v_add_u32_e32 v4, 0x3f0, v70
	v_mov_b32_e32 v190, 0x259fc
	v_cmp_lt_i32_e32 vcc, -1, v4
	v_mov_b32_e32 v3, 0xff800000
	v_mov_b32_e32 v2, 0xff800000
	ds_write_b32 v190, v2 offset:1536
	v_min_u32_e32 v2, 0x7f, v4
	v_lshl_add_u32 v2, v2, 2, s87
	v_cndmask_b32_e32 v2, v190, v2, vcc
	ds_read_b32 v2, v2 offset:1536
	v_add_u32_e32 v4, 0x3e0, v70
	v_cmp_lt_i32_e32 vcc, -1, v4
	v_min_u32_e32 v3, 0x7f, v4
	v_lshl_add_u32 v3, v3, 2, s87
	v_cndmask_b32_e32 v3, v190, v3, vcc
	ds_read_b32 v3, v3 offset:1536
	v_add_u32_e32 v48, 0x3d0, v70
	v_cmp_lt_i32_e32 vcc, -1, v48
	v_mov_b32_e32 v5, 0xff800000
	v_mov_b32_e32 v4, 0xff800000
	v_min_u32_e32 v4, 0x7f, v48
	v_lshl_add_u32 v4, v4, 2, s87
	v_cndmask_b32_e32 v4, v190, v4, vcc
	ds_read_b32 v4, v4 offset:1536
	v_add_u32_e32 v48, 0x3c0, v70
	v_cmp_lt_i32_e32 vcc, -1, v48
	v_min_u32_e32 v5, 0x7f, v48
	v_lshl_add_u32 v5, v5, 2, s87
	v_cndmask_b32_e32 v5, v190, v5, vcc
	ds_read_b32 v5, v5 offset:1536
	v_add_u32_e32 v50, 0x2f0, v70
	v_cmp_lt_i32_e32 vcc, -1, v50
	v_mov_b32_e32 v49, 0xff800000
	v_mov_b32_e32 v48, 0xff800000
	v_min_u32_e32 v48, 0x7f, v50
	v_lshl_add_u32 v48, v48, 2, s87
	v_cndmask_b32_e32 v48, v190, v48, vcc
	ds_read_b32 v48, v48 offset:1536
	v_add_u32_e32 v50, 0x2e0, v70
	v_cmp_lt_i32_e32 vcc, -1, v50
	v_min_u32_e32 v49, 0x7f, v50
	v_lshl_add_u32 v49, v49, 2, s87
	v_cndmask_b32_e32 v49, v190, v49, vcc
	ds_read_b32 v49, v49 offset:1536
	v_add_u32_e32 v71, 0x2d0, v70
	v_cmp_lt_i32_e32 vcc, -1, v71
	v_mov_b32_e32 v51, 0xff800000
	v_mov_b32_e32 v50, 0xff800000
	v_min_u32_e32 v50, 0x7f, v71
	v_lshl_add_u32 v50, v50, 2, s87
	v_cndmask_b32_e32 v50, v190, v50, vcc
	ds_read_b32 v50, v50 offset:1536
	v_add_u32_e32 v70, 0x2c0, v70
	v_cmp_lt_i32_e32 vcc, -1, v70
	v_min_u32_e32 v51, 0x7f, v70
	v_lshl_add_u32 v51, v51, 2, s87
	v_cndmask_b32_e32 v51, v190, v51, vcc
	ds_read_b32 v51, v51 offset:1536
	s_waitcnt lgkmcnt(0)
	v_add_f32_e32 v2, v44, v2
	v_mul_f32_e32 v2, 0x3fb8aa3b, v2
	v_add_f32_e32 v3, v45, v3
	v_mul_f32_e32 v3, 0x3fb8aa3b, v3
	v_add_f32_e32 v4, v46, v4
	v_mul_f32_e32 v4, 0x3fb8aa3b, v4
	v_add_f32_e32 v5, v47, v5
	v_mul_f32_e32 v5, 0x3fb8aa3b, v5
	v_add_f32_e32 v48, v6, v48
	v_mul_f32_e32 v48, 0x3fb8aa3b, v48
	v_add_f32_e32 v49, v7, v49
	v_mul_f32_e32 v49, 0x3fb8aa3b, v49
	v_add_f32_e32 v50, v8, v50
	v_mul_f32_e32 v50, 0x3fb8aa3b, v50
	v_add_f32_e32 v51, v9, v51
	v_mul_f32_e32 v51, 0x3fb8aa3b, v51
	s_mov_b64 s[6:7], 0

.LBB0_1340:
	s_nop 0
	v_sub_f32_e32 v6, v113, v97
	v_exp_f32_e32 v6, v6
	v_add_f32_e32 v103, v68, v69
	v_sub_f32_e32 v7, v112, v96
	v_exp_f32_e32 v7, v7
	v_fmac_f32_e32 v103, v100, v6
	v_sub_f32_e32 v6, v111, v95
	v_exp_f32_e32 v6, v6
	v_add_f32_e32 v105, v105, v107
	v_add_f32_e32 v106, v104, v106
	v_fmac_f32_e32 v105, v102, v7
	v_fmac_f32_e32 v106, v99, v6
	v_max_f32_e32 v6, v3, v3
	v_max_f32_e32 v7, v2, v2
	v_max_f32_e32 v6, v7, v6
	v_max_f32_e32 v7, v5, v5
	v_max_f32_e32 v8, v4, v4
	v_max_f32_e32 v7, v8, v7
	v_max_f32_e32 v8, v51, v51
	v_max_f32_e32 v9, v50, v50
	v_max_f32_e32 v8, v9, v8
	v_max3_f32 v8, v48, v49, v8
	v_max3_f32 v6, v6, v7, v8
	v_mov_b32_e32 v7, v6
	s_nop 1
	v_permlane16_swap_b32 v6, v7
	s_nop 1
	s_cmp_ge_u32 s16, s14
	v_max_f32_e32 v7, v7, v7
	v_max_f32_e32 v6, v6, v6
	v_max_f32_e32 v6, v6, v7
	v_mov_b32_e32 v7, v6
	s_nop 1
	v_permlane32_swap_b32 v6, v7
	s_nop 1
	s_mov_b64 s[6:7], -1
	v_max3_f32 v114, v98, v6, v7
	v_sub_f32_e32 v2, v2, v114
	v_exp_f32_e32 v2, v2
	v_sub_f32_e32 v3, v3, v114
	v_exp_f32_e32 v3, v3
	v_sub_f32_e32 v4, v4, v114
	v_exp_f32_e32 v4, v4
	v_sub_f32_e32 v5, v5, v114
	v_exp_f32_e32 v5, v5
	v_add_f32_e32 v2, 0, v2
	v_add_f32_e32 v2, v3, v2
	v_sub_f32_e32 v3, v48, v114
	v_add_f32_e32 v2, v4, v2
	v_exp_f32_e32 v3, v3
	v_sub_f32_e32 v4, v49, v114
	v_add_f32_e32 v2, v5, v2
	v_exp_f32_e32 v4, v4
	v_sub_f32_e32 v5, v50, v114
	v_exp_f32_e32 v5, v5
	v_sub_f32_e32 v6, v51, v114
	v_exp_f32_e32 v6, v6
	v_add_f32_e32 v2, v3, v2
	v_add_f32_e32 v2, v4, v2
	v_add_f32_e32 v2, v5, v2
	v_add_f32_e32 v2, v6, v2
	v_mov_b32_e32 v3, v2
	s_nop 1
	v_permlane16_swap_b32 v2, v3
	s_nop 1
	s_nop 0
	v_add_f32_e32 v2, v2, v3
	v_sub_f32_e32 v3, v98, v114
	v_exp_f32_e32 v3, v3
	v_mov_b32_e32 v4, v2
	s_nop 1
	v_permlane32_swap_b32 v2, v4
	s_nop 1
	s_nop 0
	v_add_f32_e32 v104, v2, v4
	v_fmac_f32_e32 v104, v101, v3
	s_cbranch_scc1 .LBB0_1421
	s_add_i32 s13, s13, 2
	s_waitcnt vmcnt(3)
	v_mfma_f32_16x16x32_bf16 v[2:5], v[64:67], v[12:15], 0
	s_min_i32 s48, s13, s12
	s_lshl_b64 s[4:5], s[48:49], 12
	v_lshl_add_u64 v[6:7], v[84:85], 0, s[4:5]
	global_load_dwordx4 v[48:51], v[6:7], off
	global_load_dwordx4 v[44:47], v[6:7], off offset:1024
	s_waitcnt vmcnt(4)
	v_mfma_f32_16x16x32_bf16 v[76:79], v[60:63], v[16:19], v[2:5]
	s_nop 2
	global_load_dwordx4 v[2:5], v[6:7], off offset:2048
	s_nop 0
	global_load_dwordx4 v[6:9], v[6:7], off offset:3072
	s_cmpk_lt_i32 s15, 0x7f
	v_add_u32_e32 v98, s15, v94
	s_waitcnt vmcnt(5)
	v_mfma_f32_16x16x32_bf16 v[68:71], v[56:59], v[12:15], 0
	s_cselect_b64 s[10:11], -1, 0
	s_cmpk_gt_i32 s15, 0x7e
	v_add_u32_e32 v99, 0x1f0, v98
	s_waitcnt vmcnt(4)
	v_mfma_f32_16x16x32_bf16 v[72:75], v[52:55], v[16:19], v[68:71]
	s_cbranch_scc1 .LBB0_1359
	v_mov_b32_e32 v190, 0x25ffc
	v_cmp_lt_i32_e32 vcc, -1, v99
	s_nop 0
	v_mov_b32_e32 v69, 0xff800000
	v_mov_b32_e32 v68, 0xff800000
	ds_write_b32 v190, v68
	v_min_u32_e32 v68, 0x7f, v99
	v_lshl_add_u32 v68, v68, 2, s87
	v_cndmask_b32_e32 v68, v190, v68, vcc
	ds_read_b32 v68, v68
	v_add_u32_e32 v70, 0x1e0, v98
	v_cmp_lt_i32_e32 vcc, -1, v70
	v_min_u32_e32 v69, 0x7f, v70
	v_lshl_add_u32 v69, v69, 2, s87
	v_cndmask_b32_e32 v69, v190, v69, vcc
	ds_read_b32 v69, v69
	v_add_u32_e32 v80, 0x1d0, v98
	v_cmp_lt_i32_e32 vcc, -1, v80
	v_mov_b32_e32 v71, 0xff800000
	v_mov_b32_e32 v70, 0xff800000
	v_min_u32_e32 v70, 0x7f, v80
	v_lshl_add_u32 v70, v70, 2, s87
	v_cndmask_b32_e32 v70, v190, v70, vcc
	ds_read_b32 v70, v70
	v_add_u32_e32 v80, 0x1c0, v98
	v_cmp_lt_i32_e32 vcc, -1, v80
	v_min_u32_e32 v71, 0x7f, v80
	v_lshl_add_u32 v71, v71, 2, s87
	v_cndmask_b32_e32 v71, v190, v71, vcc
	ds_read_b32 v71, v71
	v_add_u32_e32 v82, 0xf0, v98
	v_cmp_lt_i32_e32 vcc, -1, v82
	v_mov_b32_e32 v81, 0xff800000
	v_mov_b32_e32 v80, 0xff800000
	v_min_u32_e32 v80, 0x7f, v82
	v_lshl_add_u32 v80, v80, 2, s87
	v_cndmask_b32_e32 v80, v190, v80, vcc
	ds_read_b32 v80, v80
	v_add_u32_e32 v82, 0xe0, v98
	v_cmp_lt_i32_e32 vcc, -1, v82
	v_min_u32_e32 v81, 0x7f, v82
	v_lshl_add_u32 v81, v81, 2, s87
	v_cndmask_b32_e32 v81, v190, v81, vcc
	ds_read_b32 v81, v81
	v_add_u32_e32 v100, 0xd0, v98
	v_cmp_lt_i32_e32 vcc, -1, v100
	v_mov_b32_e32 v83, 0xff800000
	v_mov_b32_e32 v82, 0xff800000
	v_min_u32_e32 v82, 0x7f, v100
	v_lshl_add_u32 v82, v82, 2, s87
	v_cndmask_b32_e32 v82, v190, v82, vcc
	ds_read_b32 v82, v82
	v_add_u32_e32 v100, 0xc0, v98
	v_cmp_lt_i32_e32 vcc, -1, v100
	v_min_u32_e32 v83, 0x7f, v100
	v_lshl_add_u32 v83, v83, 2, s87
	v_cndmask_b32_e32 v83, v190, v83, vcc
	ds_read_b32 v83, v83
	s_waitcnt lgkmcnt(0)
	v_add_f32_e32 v68, v76, v68
	v_mul_f32_e32 v68, 0x3fb8aa3b, v68
	v_add_f32_e32 v69, v77, v69
	v_mul_f32_e32 v69, 0x3fb8aa3b, v69
	v_add_f32_e32 v70, v78, v70
	v_mul_f32_e32 v70, 0x3fb8aa3b, v70
	v_add_f32_e32 v71, v79, v71
	v_mul_f32_e32 v71, 0x3fb8aa3b, v71
	v_add_f32_e32 v80, v72, v80
	v_mul_f32_e32 v80, 0x3fb8aa3b, v80
	v_add_f32_e32 v81, v73, v81
	v_mul_f32_e32 v81, 0x3fb8aa3b, v81
	v_add_f32_e32 v82, v74, v82
	v_mul_f32_e32 v82, 0x3fb8aa3b, v82
	v_add_f32_e32 v83, v75, v83
	v_mul_f32_e32 v83, 0x3fb8aa3b, v83
	s_mov_b64 s[6:7], 0

.LBB0_1361:
	s_nop 4
	v_max_f32_e32 v72, v69, v69
	v_max_f32_e32 v73, v68, v68
	v_max_f32_e32 v72, v73, v72
	v_max_f32_e32 v73, v71, v71
	v_max_f32_e32 v74, v70, v70
	v_max_f32_e32 v73, v74, v73
	v_max_f32_e32 v74, v83, v83
	v_max_f32_e32 v75, v82, v82
	v_max_f32_e32 v74, v75, v74
	v_max3_f32 v74, v80, v81, v74
	v_max3_f32 v72, v72, v73, v74
	v_mov_b32_e32 v73, v72
	s_nop 1
	v_permlane16_swap_b32 v72, v73
	s_nop 1
	s_andn2_b64 vcc, exec, s[10:11]
	v_max_f32_e32 v73, v73, v73
	v_max_f32_e32 v72, v72, v72
	v_max_f32_e32 v72, v72, v73
	v_mov_b32_e32 v73, v72
	s_nop 1
	v_permlane32_swap_b32 v72, v73
	s_nop 1
	s_nop 0
	v_max3_f32 v111, v95, v72, v73
	v_sub_f32_e32 v68, v68, v111
	v_exp_f32_e32 v68, v68
	v_sub_f32_e32 v69, v69, v111
	v_exp_f32_e32 v69, v69
	v_sub_f32_e32 v70, v70, v111
	v_exp_f32_e32 v70, v70
	v_sub_f32_e32 v71, v71, v111
	v_exp_f32_e32 v71, v71
	v_sub_f32_e32 v72, v80, v111
	v_add_f32_e32 v68, 0, v68
	v_exp_f32_e32 v72, v72
	v_add_f32_e32 v68, v69, v68
	v_add_f32_e32 v68, v70, v68
	v_add_f32_e32 v68, v71, v68
	v_add_f32_e32 v72, v72, v68
	v_sub_f32_e32 v68, v81, v111
	v_exp_f32_e32 v73, v68
	v_sub_f32_e32 v68, v82, v111
	v_exp_f32_e32 v74, v68
	v_sub_f32_e32 v75, v83, v111
	v_mfma_f32_16x16x32_bf16 v[68:71], v[64:67], v[20:23], 0
	v_exp_f32_e32 v75, v75
	v_add_f32_e32 v72, v73, v72
	v_add_f32_e32 v72, v74, v72
	v_mfma_f32_16x16x32_bf16 v[76:79], v[60:63], v[24:27], v[68:71]
	v_add_f32_e32 v72, v75, v72
	v_mov_b32_e32 v73, v72
	s_nop 1
	v_permlane16_swap_b32 v72, v73
	s_nop 1
	v_mfma_f32_16x16x32_bf16 v[68:71], v[56:59], v[20:23], 0
	v_add_f32_e32 v101, v72, v73
	v_mov_b32_e32 v107, v101
	s_nop 1
	v_permlane32_swap_b32 v101, v107
	s_nop 1
	v_mfma_f32_16x16x32_bf16 v[72:75], v[52:55], v[24:27], v[68:71]
	s_nop 4
	v_cndmask_b32_e64 v68, 0, 1, s[10:11]
	v_cmp_ne_u32_e64 s[6:7], 1, v68
	s_mov_b64 s[10:11], -1
	s_cbranch_vccnz .LBB0_1379
	v_mov_b32_e32 v190, 0x25dfc
	v_cmp_lt_i32_e32 vcc, -1, v99
	v_mov_b32_e32 v69, 0xff800000
	v_mov_b32_e32 v68, 0xff800000
	ds_write_b32 v190, v68 offset:512
	v_min_u32_e32 v68, 0x7f, v99
	v_lshl_add_u32 v68, v68, 2, s87
	v_cndmask_b32_e32 v68, v190, v68, vcc
	ds_read_b32 v68, v68 offset:512
	v_add_u32_e32 v70, 0x1e0, v98
	v_cmp_lt_i32_e32 vcc, -1, v70
	v_min_u32_e32 v69, 0x7f, v70
	v_lshl_add_u32 v69, v69, 2, s87
	v_cndmask_b32_e32 v69, v190, v69, vcc
	ds_read_b32 v69, v69 offset:512
	v_add_u32_e32 v80, 0x1d0, v98
	v_cmp_lt_i32_e32 vcc, -1, v80
	v_mov_b32_e32 v71, 0xff800000
	v_mov_b32_e32 v70, 0xff800000
	v_min_u32_e32 v70, 0x7f, v80
	v_lshl_add_u32 v70, v70, 2, s87
	v_cndmask_b32_e32 v70, v190, v70, vcc
	ds_read_b32 v70, v70 offset:512
	v_add_u32_e32 v80, 0x1c0, v98
	v_cmp_lt_i32_e32 vcc, -1, v80
	v_min_u32_e32 v71, 0x7f, v80
	v_lshl_add_u32 v71, v71, 2, s87
	v_cndmask_b32_e32 v71, v190, v71, vcc
	ds_read_b32 v71, v71 offset:512
	v_add_u32_e32 v82, 0xf0, v98
	v_cmp_lt_i32_e32 vcc, -1, v82
	v_mov_b32_e32 v81, 0xff800000
	v_mov_b32_e32 v80, 0xff800000
	v_min_u32_e32 v80, 0x7f, v82
	v_lshl_add_u32 v80, v80, 2, s87
	v_cndmask_b32_e32 v80, v190, v80, vcc
	ds_read_b32 v80, v80 offset:512
	v_add_u32_e32 v82, 0xe0, v98
	v_cmp_lt_i32_e32 vcc, -1, v82
	v_min_u32_e32 v81, 0x7f, v82
	v_lshl_add_u32 v81, v81, 2, s87
	v_cndmask_b32_e32 v81, v190, v81, vcc
	ds_read_b32 v81, v81 offset:512
	v_add_u32_e32 v100, 0xd0, v98
	v_cmp_lt_i32_e32 vcc, -1, v100
	v_mov_b32_e32 v83, 0xff800000
	v_mov_b32_e32 v82, 0xff800000
	v_min_u32_e32 v82, 0x7f, v100
	v_lshl_add_u32 v82, v82, 2, s87
	v_cndmask_b32_e32 v82, v190, v82, vcc
	ds_read_b32 v82, v82 offset:512
	v_add_u32_e32 v100, 0xc0, v98
	v_cmp_lt_i32_e32 vcc, -1, v100
	v_min_u32_e32 v83, 0x7f, v100
	v_lshl_add_u32 v83, v83, 2, s87
	v_cndmask_b32_e32 v83, v190, v83, vcc
	ds_read_b32 v83, v83 offset:512
	s_waitcnt lgkmcnt(0)
	v_add_f32_e32 v68, v76, v68
	v_mul_f32_e32 v68, 0x3fb8aa3b, v68
	v_add_f32_e32 v69, v77, v69
	v_mul_f32_e32 v69, 0x3fb8aa3b, v69
	v_add_f32_e32 v70, v78, v70
	v_mul_f32_e32 v70, 0x3fb8aa3b, v70
	v_add_f32_e32 v71, v79, v71
	v_mul_f32_e32 v71, 0x3fb8aa3b, v71
	v_add_f32_e32 v80, v72, v80
	v_mul_f32_e32 v80, 0x3fb8aa3b, v80
	v_add_f32_e32 v81, v73, v81
	v_mul_f32_e32 v81, 0x3fb8aa3b, v81
	v_add_f32_e32 v82, v74, v82
	v_mul_f32_e32 v82, 0x3fb8aa3b, v82
	v_add_f32_e32 v83, v75, v83
	v_mul_f32_e32 v83, 0x3fb8aa3b, v83
	s_mov_b64 s[10:11], 0

.LBB0_1381:
	v_max_f32_e32 v72, v69, v69
	v_max_f32_e32 v73, v68, v68
	v_max_f32_e32 v72, v73, v72
	v_max_f32_e32 v73, v71, v71
	v_max_f32_e32 v74, v70, v70
	v_max_f32_e32 v73, v74, v73
	v_max_f32_e32 v74, v83, v83
	v_max_f32_e32 v75, v82, v82
	v_max_f32_e32 v74, v75, v74
	v_max3_f32 v74, v80, v81, v74
	v_max3_f32 v72, v72, v73, v74
	v_mov_b32_e32 v73, v72
	s_nop 1
	v_permlane16_swap_b32 v72, v73
	s_nop 1
	s_and_b64 vcc, exec, s[6:7]
	v_max_f32_e32 v73, v73, v73
	v_max_f32_e32 v72, v72, v72
	v_max_f32_e32 v72, v72, v73
	v_mov_b32_e32 v73, v72
	s_nop 1
	v_permlane32_swap_b32 v72, v73
	s_nop 1
	s_mov_b64 s[10:11], -1
	v_max3_f32 v112, v96, v72, v73
	v_sub_f32_e32 v68, v68, v112
	v_exp_f32_e32 v68, v68
	v_sub_f32_e32 v69, v69, v112
	v_exp_f32_e32 v69, v69
	v_sub_f32_e32 v70, v70, v112
	v_exp_f32_e32 v70, v70
	v_sub_f32_e32 v71, v71, v112
	v_exp_f32_e32 v71, v71
	v_sub_f32_e32 v72, v80, v112
	v_add_f32_e32 v68, 0, v68
	v_exp_f32_e32 v72, v72
	v_add_f32_e32 v68, v69, v68
	v_add_f32_e32 v68, v70, v68
	v_add_f32_e32 v68, v71, v68
	v_add_f32_e32 v72, v72, v68
	v_sub_f32_e32 v68, v81, v112
	v_exp_f32_e32 v73, v68
	v_sub_f32_e32 v68, v82, v112
	v_exp_f32_e32 v74, v68
	v_sub_f32_e32 v75, v83, v112
	v_mfma_f32_16x16x32_bf16 v[68:71], v[64:67], v[28:31], 0
	v_exp_f32_e32 v75, v75
	v_add_f32_e32 v72, v73, v72
	v_add_f32_e32 v72, v74, v72
	v_mfma_f32_16x16x32_bf16 v[76:79], v[60:63], v[32:35], v[68:71]
	v_add_f32_e32 v72, v75, v72
	v_mov_b32_e32 v73, v72
	s_nop 1
	v_permlane16_swap_b32 v72, v73
	s_nop 1
	v_mfma_f32_16x16x32_bf16 v[68:71], v[56:59], v[28:31], 0
	v_add_f32_e32 v102, v72, v73
	v_mov_b32_e32 v115, v102
	s_nop 1
	v_permlane32_swap_b32 v102, v115
	s_nop 1
	v_mfma_f32_16x16x32_bf16 v[72:75], v[52:55], v[32:35], v[68:71]
	s_cbranch_vccnz .LBB0_1399
	v_mov_b32_e32 v190, 0x25bfc
	v_cmp_lt_i32_e32 vcc, -1, v99
	s_nop 2
	v_mov_b32_e32 v69, 0xff800000
	v_mov_b32_e32 v68, 0xff800000
	ds_write_b32 v190, v68 offset:1024
	v_min_u32_e32 v68, 0x7f, v99
	v_lshl_add_u32 v68, v68, 2, s87
	v_cndmask_b32_e32 v68, v190, v68, vcc
	ds_read_b32 v68, v68 offset:1024
	v_add_u32_e32 v70, 0x1e0, v98
	v_cmp_lt_i32_e32 vcc, -1, v70
	v_min_u32_e32 v69, 0x7f, v70
	v_lshl_add_u32 v69, v69, 2, s87
	v_cndmask_b32_e32 v69, v190, v69, vcc
	ds_read_b32 v69, v69 offset:1024
	v_add_u32_e32 v80, 0x1d0, v98
	v_cmp_lt_i32_e32 vcc, -1, v80
	v_mov_b32_e32 v71, 0xff800000
	v_mov_b32_e32 v70, 0xff800000
	v_min_u32_e32 v70, 0x7f, v80
	v_lshl_add_u32 v70, v70, 2, s87
	v_cndmask_b32_e32 v70, v190, v70, vcc
	ds_read_b32 v70, v70 offset:1024
	v_add_u32_e32 v80, 0x1c0, v98
	v_cmp_lt_i32_e32 vcc, -1, v80
	v_min_u32_e32 v71, 0x7f, v80
	v_lshl_add_u32 v71, v71, 2, s87
	v_cndmask_b32_e32 v71, v190, v71, vcc
	ds_read_b32 v71, v71 offset:1024
	v_add_u32_e32 v82, 0xf0, v98
	v_cmp_lt_i32_e32 vcc, -1, v82
	v_mov_b32_e32 v81, 0xff800000
	v_mov_b32_e32 v80, 0xff800000
	v_min_u32_e32 v80, 0x7f, v82
	v_lshl_add_u32 v80, v80, 2, s87
	v_cndmask_b32_e32 v80, v190, v80, vcc
	ds_read_b32 v80, v80 offset:1024
	v_add_u32_e32 v82, 0xe0, v98
	v_cmp_lt_i32_e32 vcc, -1, v82
	v_min_u32_e32 v81, 0x7f, v82
	v_lshl_add_u32 v81, v81, 2, s87
	v_cndmask_b32_e32 v81, v190, v81, vcc
	ds_read_b32 v81, v81 offset:1024
	v_add_u32_e32 v100, 0xd0, v98
	v_cmp_lt_i32_e32 vcc, -1, v100
	v_mov_b32_e32 v83, 0xff800000
	v_mov_b32_e32 v82, 0xff800000
	v_min_u32_e32 v82, 0x7f, v100
	v_lshl_add_u32 v82, v82, 2, s87
	v_cndmask_b32_e32 v82, v190, v82, vcc
	ds_read_b32 v82, v82 offset:1024
	v_add_u32_e32 v100, 0xc0, v98
	v_cmp_lt_i32_e32 vcc, -1, v100
	v_min_u32_e32 v83, 0x7f, v100
	v_lshl_add_u32 v83, v83, 2, s87
	v_cndmask_b32_e32 v83, v190, v83, vcc
	ds_read_b32 v83, v83 offset:1024
	s_waitcnt lgkmcnt(0)
	v_add_f32_e32 v68, v76, v68
	v_mul_f32_e32 v68, 0x3fb8aa3b, v68
	v_add_f32_e32 v69, v77, v69
	v_mul_f32_e32 v69, 0x3fb8aa3b, v69
	v_add_f32_e32 v70, v78, v70
	v_mul_f32_e32 v70, 0x3fb8aa3b, v70
	v_add_f32_e32 v71, v79, v71
	v_mul_f32_e32 v71, 0x3fb8aa3b, v71
	v_add_f32_e32 v80, v72, v80
	v_mul_f32_e32 v80, 0x3fb8aa3b, v80
	v_add_f32_e32 v81, v73, v81
	v_mul_f32_e32 v81, 0x3fb8aa3b, v81
	v_add_f32_e32 v82, v74, v82
	v_mul_f32_e32 v82, 0x3fb8aa3b, v82
	v_add_f32_e32 v83, v75, v83
	v_mul_f32_e32 v83, 0x3fb8aa3b, v83
	s_mov_b64 s[10:11], 0

.LBB0_1401:
	s_nop 4
	v_max_f32_e32 v72, v69, v69
	v_max_f32_e32 v73, v68, v68
	v_max_f32_e32 v72, v73, v72
	v_max_f32_e32 v73, v71, v71
	v_max_f32_e32 v74, v70, v70
	v_max_f32_e32 v73, v74, v73
	v_max_f32_e32 v74, v83, v83
	v_max_f32_e32 v75, v82, v82
	v_max_f32_e32 v74, v75, v74
	v_max3_f32 v74, v80, v81, v74
	v_max3_f32 v72, v72, v73, v74
	v_mov_b32_e32 v73, v72
	s_nop 1
	v_permlane16_swap_b32 v72, v73
	s_nop 1
	v_mfma_f32_16x16x32_bf16 v[64:67], v[64:67], v[36:39], 0
	v_max_f32_e32 v73, v73, v73
	v_max_f32_e32 v72, v72, v72
	v_max_f32_e32 v72, v72, v73
	v_mov_b32_e32 v73, v72
	s_nop 1
	v_permlane32_swap_b32 v72, v73
	s_nop 1
	v_mfma_f32_16x16x32_bf16 v[56:59], v[56:59], v[36:39], 0
	v_max3_f32 v113, v97, v72, v73
	v_sub_f32_e32 v68, v68, v113
	v_exp_f32_e32 v68, v68
	v_sub_f32_e32 v69, v69, v113
	v_exp_f32_e32 v69, v69
	v_sub_f32_e32 v70, v70, v113
	v_exp_f32_e32 v70, v70
	v_sub_f32_e32 v71, v71, v113
	v_exp_f32_e32 v71, v71
	v_add_f32_e32 v68, 0, v68
	v_sub_f32_e32 v72, v80, v113
	v_exp_f32_e32 v72, v72
	v_add_f32_e32 v68, v69, v68
	v_sub_f32_e32 v69, v81, v113
	v_add_f32_e32 v68, v70, v68
	v_exp_f32_e32 v69, v69
	v_sub_f32_e32 v70, v82, v113
	v_add_f32_e32 v68, v71, v68
	v_exp_f32_e32 v70, v70
	v_sub_f32_e32 v71, v83, v113
	v_exp_f32_e32 v71, v71
	v_add_f32_e32 v68, v72, v68
	v_add_f32_e32 v68, v69, v68
	v_add_f32_e32 v68, v70, v68
	v_mfma_f32_16x16x32_bf16 v[60:63], v[60:63], v[40:43], v[64:67]
	s_and_b64 vcc, exec, s[6:7]
	s_mov_b64 s[6:7], -1
	s_nop 0
	v_add_f32_e32 v64, v71, v68
	v_mfma_f32_16x16x32_bf16 v[56:59], v[52:55], v[40:43], v[56:59]
	v_mov_b32_e32 v65, v64
	s_nop 1
	v_permlane16_swap_b32 v64, v65
	s_nop 1
	s_nop 0
	v_add_f32_e32 v68, v64, v65
	v_mov_b32_e32 v69, v68
	s_nop 1
	v_permlane32_swap_b32 v68, v69
	s_nop 1
	s_cbranch_vccnz .LBB0_1419
	v_mov_b32_e32 v190, 0x259fc
	v_cmp_lt_i32_e32 vcc, -1, v99
	v_mov_b32_e32 v53, 0xff800000
	v_mov_b32_e32 v52, 0xff800000
	ds_write_b32 v190, v52 offset:1536
	v_min_u32_e32 v52, 0x7f, v99
	v_lshl_add_u32 v52, v52, 2, s87
	v_cndmask_b32_e32 v52, v190, v52, vcc
	ds_read_b32 v52, v52 offset:1536
	v_add_u32_e32 v54, 0x1e0, v98
	v_cmp_lt_i32_e32 vcc, -1, v54
	v_min_u32_e32 v53, 0x7f, v54
	v_lshl_add_u32 v53, v53, 2, s87
	v_cndmask_b32_e32 v53, v190, v53, vcc
	ds_read_b32 v53, v53 offset:1536
	v_add_u32_e32 v64, 0x1d0, v98
	v_cmp_lt_i32_e32 vcc, -1, v64
	v_mov_b32_e32 v55, 0xff800000
	v_mov_b32_e32 v54, 0xff800000
	v_min_u32_e32 v54, 0x7f, v64
	v_lshl_add_u32 v54, v54, 2, s87
	v_cndmask_b32_e32 v54, v190, v54, vcc
	ds_read_b32 v54, v54 offset:1536
	v_add_u32_e32 v64, 0x1c0, v98
	v_cmp_lt_i32_e32 vcc, -1, v64
	v_min_u32_e32 v55, 0x7f, v64
	v_lshl_add_u32 v55, v55, 2, s87
	v_cndmask_b32_e32 v55, v190, v55, vcc
	ds_read_b32 v55, v55 offset:1536
	v_add_u32_e32 v66, 0xf0, v98
	v_cmp_lt_i32_e32 vcc, -1, v66
	v_mov_b32_e32 v65, 0xff800000
	v_mov_b32_e32 v64, 0xff800000
	v_min_u32_e32 v64, 0x7f, v66
	v_lshl_add_u32 v64, v64, 2, s87
	v_cndmask_b32_e32 v64, v190, v64, vcc
	ds_read_b32 v64, v64 offset:1536
	v_add_u32_e32 v66, 0xe0, v98
	v_cmp_lt_i32_e32 vcc, -1, v66
	v_min_u32_e32 v65, 0x7f, v66
	v_lshl_add_u32 v65, v65, 2, s87
	v_cndmask_b32_e32 v65, v190, v65, vcc
	ds_read_b32 v65, v65 offset:1536
	v_add_u32_e32 v70, 0xd0, v98
	v_cmp_lt_i32_e32 vcc, -1, v70
	v_mov_b32_e32 v67, 0xff800000
	v_mov_b32_e32 v66, 0xff800000
	v_min_u32_e32 v66, 0x7f, v70
	v_lshl_add_u32 v66, v66, 2, s87
	v_cndmask_b32_e32 v66, v190, v66, vcc
	ds_read_b32 v66, v66 offset:1536
	v_add_u32_e32 v70, 0xc0, v98
	v_cmp_lt_i32_e32 vcc, -1, v70
	v_min_u32_e32 v67, 0x7f, v70
	v_lshl_add_u32 v67, v67, 2, s87
	v_cndmask_b32_e32 v67, v190, v67, vcc
	ds_read_b32 v67, v67 offset:1536
	s_waitcnt lgkmcnt(0)
	v_add_f32_e32 v52, v60, v52
	v_mul_f32_e32 v52, 0x3fb8aa3b, v52
	v_add_f32_e32 v53, v61, v53
	v_mul_f32_e32 v53, 0x3fb8aa3b, v53
	v_add_f32_e32 v54, v62, v54
	v_mul_f32_e32 v54, 0x3fb8aa3b, v54
	v_add_f32_e32 v55, v63, v55
	v_mul_f32_e32 v55, 0x3fb8aa3b, v55
	v_add_f32_e32 v64, v56, v64
	v_mul_f32_e32 v64, 0x3fb8aa3b, v64
	v_add_f32_e32 v65, v57, v65
	v_mul_f32_e32 v65, 0x3fb8aa3b, v65
	v_add_f32_e32 v66, v58, v66
	v_mul_f32_e32 v66, 0x3fb8aa3b, v66
	v_add_f32_e32 v67, v59, v67
	v_mul_f32_e32 v67, 0x3fb8aa3b, v67
	s_mov_b64 s[6:7], 0

.LBB0_1427:
	s_waitcnt vmcnt(0)
	v_mov_b64_e32 v[124:125], v[196:197]
	v_mov_b64_e32 v[126:127], v[198:199]
	v_mov_b64_e32 v[128:129], v[214:215]
	v_mov_b64_e32 v[130:131], v[216:217]
	v_mov_b64_e32 v[132:133], v[224:225]
	v_mov_b64_e32 v[134:135], v[226:227]
	v_mov_b64_e32 v[136:137], v[228:229]
	v_mov_b64_e32 v[138:139], v[230:231]
	v_mov_b64_e32 v[120:121], v[244:245]
	v_mov_b64_e32 v[122:123], v[246:247]
	v_mov_b64_e32 v[116:117], v[248:249]
	v_mov_b64_e32 v[118:119], v[250:251]
	v_mov_b64_e32 v[112:113], v[252:253]
	v_mov_b64_e32 v[114:115], v[254:255]
	v_mov_b64_e32 v[108:109], v[218:219]
	v_mov_b32_e32 v110, v220
	v_mov_b32_e32 v111, v223
	v_add_co_u32_e32 v6, vcc, s80, v164
	s_cmpk_lt_i32 s10, 0x7f
	s_nop 0
	v_addc_co_u32_e32 v7, vcc, -1, v165, vcc
	global_load_dwordx4 v[196:199], v[6:7], off offset:-3072
	global_load_dwordx4 v[214:217], v[6:7], off offset:-1024
	global_load_dwordx4 v[224:227], v[6:7], off offset:-2048
	global_load_dwordx4 v[228:231], v[6:7], off offset:0
	global_load_dwordx4 v[244:247], v[164:165], off offset:-3072
	global_load_dwordx4 v[248:251], v[164:165], off offset:-2048
	global_load_dwordx4 v[252:255], v[164:165], off offset:-1024
	global_load_dwordx2 v[218:219], v[164:165], off offset:0
	global_load_dword v220, v[164:165], off offset:8
	global_load_dword v223, v[164:165], off offset:12
	s_cselect_b64 s[8:9], -1, 0
	s_cmpk_gt_i32 s10, 0x7e
	s_mov_b64 s[6:7], -1
	v_mfma_f32_16x16x32_bf16 v[2:5], v[124:127], v[12:15], 0
	v_mfma_f32_16x16x32_bf16 v[6:9], v[128:131], v[12:15], 0
	v_mfma_f32_16x16x32_bf16 v[140:143], v[132:135], v[16:19], v[2:5]
	v_mfma_f32_16x16x32_bf16 v[144:147], v[136:139], v[16:19], v[6:9]
	s_cbranch_scc1 .LBB0_1445
	v_add_u32_e32 v149, s10, v171
	v_add_u32_e32 v4, 0x1f0, v149
	v_mov_b32_e32 v195, 0x25ffc
	v_cmp_lt_i32_e32 vcc, -1, v4
	v_mov_b32_e32 v3, 0xff800000
	v_mov_b32_e32 v2, 0xff800000
	ds_write_b32 v195, v2
	v_min_u32_e32 v2, 0x7f, v4
	v_lshl_add_u32 v2, v2, 2, s87
	v_cndmask_b32_e32 v2, v195, v2, vcc
	ds_read_b32 v2, v2
	v_add_u32_e32 v4, 0x1e0, v149
	v_cmp_lt_i32_e32 vcc, -1, v4
	v_min_u32_e32 v3, 0x7f, v4
	v_lshl_add_u32 v3, v3, 2, s87
	v_cndmask_b32_e32 v3, v195, v3, vcc
	ds_read_b32 v3, v3
	v_add_u32_e32 v6, 0x1d0, v149
	v_cmp_lt_i32_e32 vcc, -1, v6
	v_mov_b32_e32 v5, 0xff800000
	v_mov_b32_e32 v4, 0xff800000
	v_min_u32_e32 v4, 0x7f, v6
	v_lshl_add_u32 v4, v4, 2, s87
	v_cndmask_b32_e32 v4, v195, v4, vcc
	ds_read_b32 v4, v4
	v_add_u32_e32 v6, 0x1c0, v149
	v_cmp_lt_i32_e32 vcc, -1, v6
	v_min_u32_e32 v5, 0x7f, v6
	v_lshl_add_u32 v5, v5, 2, s87
	v_cndmask_b32_e32 v5, v195, v5, vcc
	ds_read_b32 v5, v5
	v_add_u32_e32 v8, 0xf0, v149
	v_cmp_lt_i32_e32 vcc, -1, v8
	v_mov_b32_e32 v7, 0xff800000
	v_mov_b32_e32 v6, 0xff800000
	v_min_u32_e32 v6, 0x7f, v8
	v_lshl_add_u32 v6, v6, 2, s87
	v_cndmask_b32_e32 v6, v195, v6, vcc
	ds_read_b32 v6, v6
	v_add_u32_e32 v8, 0xe0, v149
	v_cmp_lt_i32_e32 vcc, -1, v8
	v_min_u32_e32 v7, 0x7f, v8
	v_lshl_add_u32 v7, v7, 2, s87
	v_cndmask_b32_e32 v7, v195, v7, vcc
	ds_read_b32 v7, v7
	v_add_u32_e32 v151, 0xd0, v149
	v_cmp_lt_i32_e32 vcc, -1, v151
	v_mov_b32_e32 v9, 0xff800000
	v_mov_b32_e32 v8, 0xff800000
	v_min_u32_e32 v8, 0x7f, v151
	v_lshl_add_u32 v8, v8, 2, s87
	v_cndmask_b32_e32 v8, v195, v8, vcc
	ds_read_b32 v8, v8
	v_add_u32_e32 v149, 0xc0, v149
	v_cmp_lt_i32_e32 vcc, -1, v149
	v_min_u32_e32 v9, 0x7f, v149
	v_lshl_add_u32 v9, v9, 2, s87
	v_cndmask_b32_e32 v9, v195, v9, vcc
	ds_read_b32 v9, v9
	s_waitcnt lgkmcnt(0)
	v_add_f32_e32 v2, v140, v2
	v_mul_f32_e32 v2, 0x3fb8aa3b, v2
	v_add_f32_e32 v3, v141, v3
	v_mul_f32_e32 v3, 0x3fb8aa3b, v3
	v_add_f32_e32 v4, v142, v4
	v_mul_f32_e32 v4, 0x3fb8aa3b, v4
	v_add_f32_e32 v5, v143, v5
	v_mul_f32_e32 v5, 0x3fb8aa3b, v5
	v_add_f32_e32 v6, v144, v6
	v_mul_f32_e32 v6, 0x3fb8aa3b, v6
	v_add_f32_e32 v7, v145, v7
	v_mul_f32_e32 v7, 0x3fb8aa3b, v7
	v_add_f32_e32 v8, v146, v8
	v_mul_f32_e32 v8, 0x3fb8aa3b, v8
	v_add_f32_e32 v9, v147, v9
	v_mul_f32_e32 v9, 0x3fb8aa3b, v9
	s_mov_b64 s[6:7], 0

.LBB0_1447:
	v_sub_f32_e32 v2, v2, v166
	v_exp_f32_e32 v173, v2
	v_sub_f32_e32 v2, v3, v166
	v_exp_f32_e32 v184, v2
	v_sub_f32_e32 v2, v4, v166
	v_exp_f32_e32 v183, v2
	v_sub_f32_e32 v2, v5, v166
	v_exp_f32_e32 v182, v2
	v_sub_f32_e32 v2, v6, v166
	v_exp_f32_e32 v185, v2
	v_sub_f32_e32 v2, v7, v166
	v_exp_f32_e32 v187, v2
	v_sub_f32_e32 v2, v8, v166
	v_exp_f32_e32 v186, v2
	v_sub_f32_e32 v2, v9, v166
	v_exp_f32_e32 v149, v2
	v_cvt_pk_bf16_f32 v2, v173, v184
	v_cvt_pk_bf16_f32 v3, v183, v182
	v_cvt_pk_bf16_f32 v4, v185, v187
	v_cvt_pk_bf16_f32 v5, v186, v149
	v_cndmask_b32_e64 v6, 0, 1, s[8:9]
	v_mfma_f32_16x16x32_bf16 v[96:99], v[120:123], v[2:5], v[96:99]
	v_cmp_ne_u32_e64 s[6:7], 1, v6
	s_andn2_b64 vcc, exec, s[8:9]
	s_mov_b64 s[8:9], -1
	v_mfma_f32_16x16x32_bf16 v[104:107], v[116:119], v[2:5], v[104:107]
	v_mfma_f32_16x16x32_bf16 v[100:103], v[112:115], v[2:5], v[100:103]
	v_mfma_f32_16x16x32_bf16 v[92:95], v[108:111], v[2:5], v[92:95]
	v_mfma_f32_16x16x32_bf16 v[2:5], v[124:127], v[20:23], 0
	v_mfma_f32_16x16x32_bf16 v[140:143], v[132:135], v[24:27], v[2:5]
	v_mfma_f32_16x16x32_bf16 v[2:5], v[128:131], v[20:23], 0
	v_mfma_f32_16x16x32_bf16 v[144:147], v[136:139], v[24:27], v[2:5]
	s_cbranch_vccnz .LBB0_1465
	v_add_u32_e32 v151, s10, v171
	s_nop 4
	v_add_u32_e32 v4, 0x1f0, v151
	v_mov_b32_e32 v195, 0x25dfc
	v_cmp_lt_i32_e32 vcc, -1, v4
	v_mov_b32_e32 v3, 0xff800000
	v_mov_b32_e32 v2, 0xff800000
	ds_write_b32 v195, v2 offset:512
	v_min_u32_e32 v2, 0x7f, v4
	v_lshl_add_u32 v2, v2, 2, s87
	v_cndmask_b32_e32 v2, v195, v2, vcc
	ds_read_b32 v2, v2 offset:512
	v_add_u32_e32 v4, 0x1e0, v151
	v_cmp_lt_i32_e32 vcc, -1, v4
	v_min_u32_e32 v3, 0x7f, v4
	v_lshl_add_u32 v3, v3, 2, s87
	v_cndmask_b32_e32 v3, v195, v3, vcc
	ds_read_b32 v3, v3 offset:512
	v_add_u32_e32 v6, 0x1d0, v151
	v_cmp_lt_i32_e32 vcc, -1, v6
	v_mov_b32_e32 v5, 0xff800000
	v_mov_b32_e32 v4, 0xff800000
	v_min_u32_e32 v4, 0x7f, v6
	v_lshl_add_u32 v4, v4, 2, s87
	v_cndmask_b32_e32 v4, v195, v4, vcc
	ds_read_b32 v4, v4 offset:512
	v_add_u32_e32 v6, 0x1c0, v151
	v_cmp_lt_i32_e32 vcc, -1, v6
	v_min_u32_e32 v5, 0x7f, v6
	v_lshl_add_u32 v5, v5, 2, s87
	v_cndmask_b32_e32 v5, v195, v5, vcc
	ds_read_b32 v5, v5 offset:512
	v_add_u32_e32 v8, 0xf0, v151
	v_cmp_lt_i32_e32 vcc, -1, v8
	v_mov_b32_e32 v7, 0xff800000
	v_mov_b32_e32 v6, 0xff800000
	v_min_u32_e32 v6, 0x7f, v8
	v_lshl_add_u32 v6, v6, 2, s87
	v_cndmask_b32_e32 v6, v195, v6, vcc
	ds_read_b32 v6, v6 offset:512
	v_add_u32_e32 v8, 0xe0, v151
	v_cmp_lt_i32_e32 vcc, -1, v8
	v_min_u32_e32 v7, 0x7f, v8
	v_lshl_add_u32 v7, v7, 2, s87
	v_cndmask_b32_e32 v7, v195, v7, vcc
	ds_read_b32 v7, v7 offset:512
	v_add_u32_e32 v153, 0xd0, v151
	v_cmp_lt_i32_e32 vcc, -1, v153
	v_mov_b32_e32 v9, 0xff800000
	v_mov_b32_e32 v8, 0xff800000
	v_min_u32_e32 v8, 0x7f, v153
	v_lshl_add_u32 v8, v8, 2, s87
	v_cndmask_b32_e32 v8, v195, v8, vcc
	ds_read_b32 v8, v8 offset:512
	v_add_u32_e32 v151, 0xc0, v151
	v_cmp_lt_i32_e32 vcc, -1, v151
	v_min_u32_e32 v9, 0x7f, v151
	v_lshl_add_u32 v9, v9, 2, s87
	v_cndmask_b32_e32 v9, v195, v9, vcc
	ds_read_b32 v9, v9 offset:512
	s_waitcnt lgkmcnt(0)
	v_add_f32_e32 v2, v140, v2
	v_mul_f32_e32 v2, 0x3fb8aa3b, v2
	v_add_f32_e32 v3, v141, v3
	v_mul_f32_e32 v3, 0x3fb8aa3b, v3
	v_add_f32_e32 v4, v142, v4
	v_mul_f32_e32 v4, 0x3fb8aa3b, v4
	v_add_f32_e32 v5, v143, v5
	v_mul_f32_e32 v5, 0x3fb8aa3b, v5
	v_add_f32_e32 v6, v144, v6
	v_mul_f32_e32 v6, 0x3fb8aa3b, v6
	v_add_f32_e32 v7, v145, v7
	v_mul_f32_e32 v7, 0x3fb8aa3b, v7
	v_add_f32_e32 v8, v146, v8
	v_mul_f32_e32 v8, 0x3fb8aa3b, v8
	v_add_f32_e32 v9, v147, v9
	v_mul_f32_e32 v9, 0x3fb8aa3b, v9
	s_mov_b64 s[8:9], 0

.LBB0_1467:
	s_nop 3
	v_sub_f32_e32 v2, v2, v167
	v_exp_f32_e32 v189, v2
	v_sub_f32_e32 v2, v3, v167
	v_exp_f32_e32 v192, v2
	v_sub_f32_e32 v2, v4, v167
	v_exp_f32_e32 v191, v2
	v_sub_f32_e32 v2, v5, v167
	v_exp_f32_e32 v188, v2
	v_sub_f32_e32 v2, v6, v167
	v_exp_f32_e32 v190, v2
	v_sub_f32_e32 v2, v7, v167
	v_exp_f32_e32 v194, v2
	v_sub_f32_e32 v2, v8, v167
	v_exp_f32_e32 v193, v2
	v_sub_f32_e32 v2, v9, v167
	v_exp_f32_e32 v153, v2
	v_cvt_pk_bf16_f32 v2, v189, v192
	v_cvt_pk_bf16_f32 v3, v191, v188
	v_cvt_pk_bf16_f32 v4, v190, v194
	v_cvt_pk_bf16_f32 v5, v193, v153
	s_mov_b64 s[8:9], -1
	v_mfma_f32_16x16x32_bf16 v[88:91], v[120:123], v[2:5], v[88:91]
	s_and_b64 vcc, exec, s[6:7]
	v_mfma_f32_16x16x32_bf16 v[84:87], v[116:119], v[2:5], v[84:87]
	v_mfma_f32_16x16x32_bf16 v[80:83], v[112:115], v[2:5], v[80:83]
	v_mfma_f32_16x16x32_bf16 v[76:79], v[108:111], v[2:5], v[76:79]
	v_mfma_f32_16x16x32_bf16 v[2:5], v[124:127], v[28:31], 0
	v_mfma_f32_16x16x32_bf16 v[140:143], v[132:135], v[32:35], v[2:5]
	v_mfma_f32_16x16x32_bf16 v[2:5], v[128:131], v[28:31], 0
	v_mfma_f32_16x16x32_bf16 v[144:147], v[136:139], v[32:35], v[2:5]
	s_cbranch_vccnz .LBB0_1485
	v_add_u32_e32 v151, s10, v171
	s_nop 4
	v_add_u32_e32 v4, 0x1f0, v151
	v_mov_b32_e32 v195, 0x25bfc
	v_cmp_lt_i32_e32 vcc, -1, v4
	v_mov_b32_e32 v3, 0xff800000
	v_mov_b32_e32 v2, 0xff800000
	ds_write_b32 v195, v2 offset:1024
	v_min_u32_e32 v2, 0x7f, v4
	v_lshl_add_u32 v2, v2, 2, s87
	v_cndmask_b32_e32 v2, v195, v2, vcc
	ds_read_b32 v2, v2 offset:1024
	v_add_u32_e32 v4, 0x1e0, v151
	v_cmp_lt_i32_e32 vcc, -1, v4
	v_min_u32_e32 v3, 0x7f, v4
	v_lshl_add_u32 v3, v3, 2, s87
	v_cndmask_b32_e32 v3, v195, v3, vcc
	ds_read_b32 v3, v3 offset:1024
	v_add_u32_e32 v6, 0x1d0, v151
	v_cmp_lt_i32_e32 vcc, -1, v6
	v_mov_b32_e32 v5, 0xff800000
	v_mov_b32_e32 v4, 0xff800000
	v_min_u32_e32 v4, 0x7f, v6
	v_lshl_add_u32 v4, v4, 2, s87
	v_cndmask_b32_e32 v4, v195, v4, vcc
	ds_read_b32 v4, v4 offset:1024
	v_add_u32_e32 v6, 0x1c0, v151
	v_cmp_lt_i32_e32 vcc, -1, v6
	v_min_u32_e32 v5, 0x7f, v6
	v_lshl_add_u32 v5, v5, 2, s87
	v_cndmask_b32_e32 v5, v195, v5, vcc
	ds_read_b32 v5, v5 offset:1024
	v_add_u32_e32 v8, 0xf0, v151
	v_cmp_lt_i32_e32 vcc, -1, v8
	v_mov_b32_e32 v7, 0xff800000
	v_mov_b32_e32 v6, 0xff800000
	v_min_u32_e32 v6, 0x7f, v8
	v_lshl_add_u32 v6, v6, 2, s87
	v_cndmask_b32_e32 v6, v195, v6, vcc
	ds_read_b32 v6, v6 offset:1024
	v_add_u32_e32 v8, 0xe0, v151
	v_cmp_lt_i32_e32 vcc, -1, v8
	v_min_u32_e32 v7, 0x7f, v8
	v_lshl_add_u32 v7, v7, 2, s87
	v_cndmask_b32_e32 v7, v195, v7, vcc
	ds_read_b32 v7, v7 offset:1024
	v_add_u32_e32 v155, 0xd0, v151
	v_cmp_lt_i32_e32 vcc, -1, v155
	v_mov_b32_e32 v9, 0xff800000
	v_mov_b32_e32 v8, 0xff800000
	v_min_u32_e32 v8, 0x7f, v155
	v_lshl_add_u32 v8, v8, 2, s87
	v_cndmask_b32_e32 v8, v195, v8, vcc
	ds_read_b32 v8, v8 offset:1024
	v_add_u32_e32 v151, 0xc0, v151
	v_cmp_lt_i32_e32 vcc, -1, v151
	v_min_u32_e32 v9, 0x7f, v151
	v_lshl_add_u32 v9, v9, 2, s87
	v_cndmask_b32_e32 v9, v195, v9, vcc
	ds_read_b32 v9, v9 offset:1024
	s_waitcnt lgkmcnt(0)
	v_add_f32_e32 v2, v140, v2
	v_mul_f32_e32 v2, 0x3fb8aa3b, v2
	v_add_f32_e32 v3, v141, v3
	v_mul_f32_e32 v3, 0x3fb8aa3b, v3
	v_add_f32_e32 v4, v142, v4
	v_mul_f32_e32 v4, 0x3fb8aa3b, v4
	v_add_f32_e32 v5, v143, v5
	v_mul_f32_e32 v5, 0x3fb8aa3b, v5
	v_add_f32_e32 v6, v144, v6
	v_mul_f32_e32 v6, 0x3fb8aa3b, v6
	v_add_f32_e32 v7, v145, v7
	v_mul_f32_e32 v7, 0x3fb8aa3b, v7
	v_add_f32_e32 v8, v146, v8
	v_mul_f32_e32 v8, 0x3fb8aa3b, v8
	v_add_f32_e32 v9, v147, v9
	v_mul_f32_e32 v9, 0x3fb8aa3b, v9
	s_mov_b64 s[8:9], 0

.LBB0_1487:
	s_nop 3
	v_sub_f32_e32 v2, v2, v168
	v_exp_f32_e32 v143, v2
	v_sub_f32_e32 v2, v3, v168
	v_exp_f32_e32 v146, v2
	v_sub_f32_e32 v2, v4, v168
	v_exp_f32_e32 v145, v2
	v_sub_f32_e32 v2, v5, v168
	v_exp_f32_e32 v141, v2
	v_sub_f32_e32 v2, v6, v168
	v_exp_f32_e32 v144, v2
	v_sub_f32_e32 v2, v7, v168
	v_exp_f32_e32 v147, v2
	v_sub_f32_e32 v2, v8, v168
	v_exp_f32_e32 v142, v2
	v_sub_f32_e32 v2, v9, v168
	v_exp_f32_e32 v140, v2
	v_cvt_pk_bf16_f32 v2, v143, v146
	v_cvt_pk_bf16_f32 v3, v145, v141
	v_cvt_pk_bf16_f32 v4, v144, v147
	v_cvt_pk_bf16_f32 v5, v142, v140
	s_mov_b64 s[8:9], -1
	v_mfma_f32_16x16x32_bf16 v[72:75], v[120:123], v[2:5], v[72:75]
	s_and_b64 vcc, exec, s[6:7]
	v_mfma_f32_16x16x32_bf16 v[68:71], v[116:119], v[2:5], v[68:71]
	v_mfma_f32_16x16x32_bf16 v[64:67], v[112:115], v[2:5], v[64:67]
	v_mfma_f32_16x16x32_bf16 v[60:63], v[108:111], v[2:5], v[60:63]
	v_mfma_f32_16x16x32_bf16 v[2:5], v[124:127], v[36:39], 0
	v_mfma_f32_16x16x32_bf16 v[124:127], v[132:135], v[40:43], v[2:5]
	v_mfma_f32_16x16x32_bf16 v[2:5], v[128:131], v[36:39], 0
	v_mfma_f32_16x16x32_bf16 v[128:131], v[136:139], v[40:43], v[2:5]
	s_cbranch_vccnz .LBB0_1505
	v_add_u32_e32 v132, s10, v171
	s_nop 4
	v_add_u32_e32 v4, 0x1f0, v132
	v_mov_b32_e32 v195, 0x259fc
	v_cmp_lt_i32_e32 vcc, -1, v4
	v_mov_b32_e32 v3, 0xff800000
	v_mov_b32_e32 v2, 0xff800000
	ds_write_b32 v195, v2 offset:1536
	v_min_u32_e32 v2, 0x7f, v4
	v_lshl_add_u32 v2, v2, 2, s87
	v_cndmask_b32_e32 v2, v195, v2, vcc
	ds_read_b32 v2, v2 offset:1536
	v_add_u32_e32 v4, 0x1e0, v132
	v_cmp_lt_i32_e32 vcc, -1, v4
	v_min_u32_e32 v3, 0x7f, v4
	v_lshl_add_u32 v3, v3, 2, s87
	v_cndmask_b32_e32 v3, v195, v3, vcc
	ds_read_b32 v3, v3 offset:1536
	v_add_u32_e32 v6, 0x1d0, v132
	v_cmp_lt_i32_e32 vcc, -1, v6
	v_mov_b32_e32 v5, 0xff800000
	v_mov_b32_e32 v4, 0xff800000
	v_min_u32_e32 v4, 0x7f, v6
	v_lshl_add_u32 v4, v4, 2, s87
	v_cndmask_b32_e32 v4, v195, v4, vcc
	ds_read_b32 v4, v4 offset:1536
	v_add_u32_e32 v6, 0x1c0, v132
	v_cmp_lt_i32_e32 vcc, -1, v6
	v_min_u32_e32 v5, 0x7f, v6
	v_lshl_add_u32 v5, v5, 2, s87
	v_cndmask_b32_e32 v5, v195, v5, vcc
	ds_read_b32 v5, v5 offset:1536
	v_add_u32_e32 v8, 0xf0, v132
	v_cmp_lt_i32_e32 vcc, -1, v8
	v_mov_b32_e32 v7, 0xff800000
	v_mov_b32_e32 v6, 0xff800000
	v_min_u32_e32 v6, 0x7f, v8
	v_lshl_add_u32 v6, v6, 2, s87
	v_cndmask_b32_e32 v6, v195, v6, vcc
	ds_read_b32 v6, v6 offset:1536
	v_add_u32_e32 v8, 0xe0, v132
	v_cmp_lt_i32_e32 vcc, -1, v8
	v_min_u32_e32 v7, 0x7f, v8
	v_lshl_add_u32 v7, v7, 2, s87
	v_cndmask_b32_e32 v7, v195, v7, vcc
	ds_read_b32 v7, v7 offset:1536
	v_add_u32_e32 v133, 0xd0, v132
	v_cmp_lt_i32_e32 vcc, -1, v133
	v_mov_b32_e32 v9, 0xff800000
	v_mov_b32_e32 v8, 0xff800000
	v_min_u32_e32 v8, 0x7f, v133
	v_lshl_add_u32 v8, v8, 2, s87
	v_cndmask_b32_e32 v8, v195, v8, vcc
	ds_read_b32 v8, v8 offset:1536
	v_add_u32_e32 v132, 0xc0, v132
	v_cmp_lt_i32_e32 vcc, -1, v132
	v_min_u32_e32 v9, 0x7f, v132
	v_lshl_add_u32 v9, v9, 2, s87
	v_cndmask_b32_e32 v9, v195, v9, vcc
	ds_read_b32 v9, v9 offset:1536
	s_waitcnt lgkmcnt(0)
	v_add_f32_e32 v2, v124, v2
	v_mul_f32_e32 v2, 0x3fb8aa3b, v2
	v_add_f32_e32 v3, v125, v3
	v_mul_f32_e32 v3, 0x3fb8aa3b, v3
	v_add_f32_e32 v4, v126, v4
	v_mul_f32_e32 v4, 0x3fb8aa3b, v4
	v_add_f32_e32 v5, v127, v5
	v_mul_f32_e32 v5, 0x3fb8aa3b, v5
	v_add_f32_e32 v6, v128, v6
	v_mul_f32_e32 v6, 0x3fb8aa3b, v6
	v_add_f32_e32 v7, v129, v7
	v_mul_f32_e32 v7, 0x3fb8aa3b, v7
	v_add_f32_e32 v8, v130, v8
	v_mul_f32_e32 v8, 0x3fb8aa3b, v8
	v_add_f32_e32 v9, v131, v9
	v_mul_f32_e32 v9, 0x3fb8aa3b, v9
	s_mov_b64 s[8:9], 0

.LBB0_1591:
	s_add_i32 s4, s19, -1
	s_min_i32 s4, s4, s18
	s_ashr_i32 s5, s4, 31
	s_lshl_b64 s[4:5], s[4:5], 12
	s_waitcnt vmcnt(0)
	v_lshl_add_u64 v[134:135], v[12:13], 0, s[4:5]
	global_load_dwordx4 v[162:165], v[134:135], off
	global_load_dwordx4 v[158:161], v[134:135], off offset:1024
	global_load_dwordx4 v[154:157], v[134:135], off offset:2048
	global_load_dwordx4 v[150:153], v[134:135], off offset:3072
	v_lshl_add_u64 v[134:135], v[182:183], 0, s[4:5]
	global_load_dwordx4 v[146:149], v[134:135], off
	global_load_dwordx4 v[138:141], v[134:135], off offset:1024
	global_load_dwordx4 v[142:145], v[134:135], off offset:2048
	s_nop 0
	global_load_dwordx4 v[134:137], v[134:135], off offset:3072
	s_waitcnt vmcnt(8)
	v_mfma_f32_16x16x32_bf16 v[166:169], v[130:133], v[70:73], 0
	s_sub_i32 s4, s2, 46
	s_cmpk_gt_i32 s4, 0x7e
	s_cselect_b64 s[4:5], -1, 0
	v_mfma_f32_16x16x32_bf16 v[170:173], v[126:129], v[74:77], v[166:169]
	s_cmpk_lt_i32 s2, 0x200
	s_cselect_b64 s[12:13], -1, 0
	s_and_b64 s[12:13], s[4:5], s[12:13]
	v_mfma_f32_16x16x32_bf16 v[166:169], v[122:125], v[70:73], 0
	s_mov_b64 s[14:15], -1
	s_and_b64 vcc, exec, s[12:13]
	v_mfma_f32_16x16x32_bf16 v[166:169], v[118:121], v[74:77], v[166:169]
	s_cbranch_vccnz .LBB0_1609
	v_add_u32_e32 v10, s2, v223
	v_add_u32_e32 v194, -15, v10
	v_mov_b32_e32 v244, 0x25ffc
	v_cmp_gt_u32_e32 vcc, s85, v194
	v_mov_b32_e32 v193, 0xff800000
	v_mov_b32_e32 v192, 0xff800000
	ds_write_b32 v244, v192
	v_min_u32_e32 v192, 0x7f, v194
	v_lshl_add_u32 v192, v192, 2, s87
	v_cndmask_b32_e32 v192, v244, v192, vcc
	ds_read_b32 v192, v192
	v_add_u32_e32 v194, -16, v10
	v_cmp_gt_u32_e32 vcc, s85, v194
	v_min_u32_e32 v193, 0x7f, v194
	v_lshl_add_u32 v193, v193, 2, s87
	v_cndmask_b32_e32 v193, v244, v193, vcc
	ds_read_b32 v193, v193
	v_subrev_u32_e32 v196, 17, v10
	v_cmp_gt_u32_e32 vcc, s85, v196
	v_mov_b32_e32 v195, 0xff800000
	v_mov_b32_e32 v194, 0xff800000
	v_min_u32_e32 v194, 0x7f, v196
	v_lshl_add_u32 v194, v194, 2, s87
	v_cndmask_b32_e32 v194, v244, v194, vcc
	ds_read_b32 v194, v194
	v_subrev_u32_e32 v196, 18, v10
	v_cmp_gt_u32_e32 vcc, s85, v196
	v_min_u32_e32 v195, 0x7f, v196
	v_lshl_add_u32 v195, v195, 2, s87
	v_cndmask_b32_e32 v195, v244, v195, vcc
	ds_read_b32 v195, v195
	v_subrev_u32_e32 v198, 31, v10
	v_cmp_gt_u32_e32 vcc, s85, v198
	v_mov_b32_e32 v197, 0xff800000
	v_mov_b32_e32 v196, 0xff800000
	v_min_u32_e32 v196, 0x7f, v198
	v_lshl_add_u32 v196, v196, 2, s87
	v_cndmask_b32_e32 v196, v244, v196, vcc
	ds_read_b32 v196, v196
	v_subrev_u32_e32 v198, 32, v10
	v_cmp_gt_u32_e32 vcc, s85, v198
	v_min_u32_e32 v197, 0x7f, v198
	v_lshl_add_u32 v197, v197, 2, s87
	v_cndmask_b32_e32 v197, v244, v197, vcc
	ds_read_b32 v197, v197
	v_subrev_u32_e32 v200, 33, v10
	v_cmp_gt_u32_e32 vcc, s85, v200
	v_mov_b32_e32 v199, 0xff800000
	v_mov_b32_e32 v198, 0xff800000
	v_min_u32_e32 v198, 0x7f, v200
	v_lshl_add_u32 v198, v198, 2, s87
	v_cndmask_b32_e32 v198, v244, v198, vcc
	ds_read_b32 v198, v198
	v_subrev_u32_e32 v10, 34, v10
	v_cmp_gt_u32_e32 vcc, s85, v10
	v_min_u32_e32 v199, 0x7f, v10
	v_lshl_add_u32 v199, v199, 2, s87
	v_cndmask_b32_e32 v199, v244, v199, vcc
	ds_read_b32 v199, v199
	s_waitcnt lgkmcnt(0)
	v_add_f32_e32 v192, v170, v192
	v_mul_f32_e32 v192, 0x3fb8aa3b, v192
	v_add_f32_e32 v193, v171, v193
	v_mul_f32_e32 v193, 0x3fb8aa3b, v193
	v_add_f32_e32 v194, v172, v194
	v_mul_f32_e32 v194, 0x3fb8aa3b, v194
	v_add_f32_e32 v195, v173, v195
	v_mul_f32_e32 v195, 0x3fb8aa3b, v195
	v_add_f32_e32 v196, v166, v196
	v_mul_f32_e32 v196, 0x3fb8aa3b, v196
	v_add_f32_e32 v197, v167, v197
	v_mul_f32_e32 v197, 0x3fb8aa3b, v197
	v_add_f32_e32 v198, v168, v198
	v_mul_f32_e32 v198, 0x3fb8aa3b, v198
	v_add_f32_e32 v199, v169, v199
	v_mul_f32_e32 v199, 0x3fb8aa3b, v199
	v_max3_f32 v10, v192, s89, v193
	v_max3_f32 v10, v10, v194, v195
	v_max3_f32 v10, v10, v196, v197
	v_max3_f32 v10, v10, v198, v199
	s_mov_b64 s[14:15], 0

.LBB0_1611:
	s_nop 4
	v_mov_b32_e32 v166, v10
	s_nop 1
	v_permlane16_swap_b32 v10, v166
	s_nop 1
	s_xor_b64 s[14:15], s[12:13], -1
	v_max_f32_e32 v166, v166, v166
	v_max_f32_e32 v10, v10, v10
	v_max_f32_e32 v10, v10, v166
	v_mov_b32_e32 v166, v10
	s_nop 1
	v_permlane32_swap_b32 v10, v166
	s_nop 1
	s_mov_b64 s[16:17], -1
	v_max3_f32 v236, v231, v10, v166
	v_sub_f32_e32 v166, v192, v236
	v_exp_f32_e32 v166, v166
	v_sub_f32_e32 v168, v193, v236
	v_exp_f32_e32 v168, v168
	v_sub_f32_e32 v169, v194, v236
	v_exp_f32_e32 v169, v169
	v_sub_f32_e32 v170, v195, v236
	v_exp_f32_e32 v170, v170
	v_sub_f32_e32 v171, v196, v236
	v_add_f32_e32 v167, 0, v166
	v_exp_f32_e32 v171, v171
	v_sub_f32_e32 v172, v197, v236
	v_add_f32_e32 v167, v168, v167
	v_exp_f32_e32 v172, v172
	v_sub_f32_e32 v173, v198, v236
	v_add_f32_e32 v167, v169, v167
	v_exp_f32_e32 v173, v173
	v_sub_f32_e32 v192, v199, v236
	v_add_f32_e32 v167, v170, v167
	v_exp_f32_e32 v192, v192
	v_add_f32_e32 v167, v171, v167
	v_sub_f32_e32 v10, v231, v236
	v_add_f32_e32 v167, v172, v167
	v_add_f32_e32 v167, v173, v167
	v_exp_f32_e32 v10, v10
	v_add_f32_e32 v167, v192, v167
	v_mov_b32_e32 v193, v167
	s_nop 1
	v_permlane16_swap_b32 v167, v193
	s_nop 1
	v_cvt_pk_bf16_f32 v166, v166, v168
	v_cvt_pk_bf16_f32 v168, v171, v172
	v_pk_mul_f32 v[68:69], v[68:69], v[10:11] op_sel_hi:[1,0]
	v_add_f32_e32 v231, v167, v193
	v_cvt_pk_bf16_f32 v167, v169, v170
	v_cvt_pk_bf16_f32 v169, v173, v192
	v_pk_mul_f32 v[66:67], v[66:67], v[10:11] op_sel_hi:[1,0]
	v_pk_mul_f32 v[64:65], v[64:65], v[10:11] op_sel_hi:[1,0]
	v_pk_mul_f32 v[62:63], v[62:63], v[10:11] op_sel_hi:[1,0]
	v_pk_mul_f32 v[60:61], v[60:61], v[10:11] op_sel_hi:[1,0]
	v_pk_mul_f32 v[58:59], v[58:59], v[10:11] op_sel_hi:[1,0]
	v_pk_mul_f32 v[56:57], v[56:57], v[10:11] op_sel_hi:[1,0]
	v_pk_mul_f32 v[54:55], v[54:55], v[10:11] op_sel_hi:[1,0]
	v_mfma_f32_16x16x32_bf16 v[66:69], v[114:117], v[166:169], v[66:69]
	v_cndmask_b32_e64 v192, 0, 1, s[14:15]
	v_mov_b32_e32 v232, v231
	v_cmp_ne_u32_e64 s[12:13], 1, v192
	v_mfma_f32_16x16x32_bf16 v[62:65], v[106:109], v[166:169], v[62:65]
	s_andn2_b64 vcc, exec, s[14:15]
	s_nop 1
	v_permlane32_swap_b32 v231, v232
	s_nop 1
	v_mfma_f32_16x16x32_bf16 v[58:61], v[110:113], v[166:169], v[58:61]
	v_mfma_f32_16x16x32_bf16 v[54:57], v[102:105], v[166:169], v[54:57]
	v_mfma_f32_16x16x32_bf16 v[166:169], v[130:133], v[78:81], 0
	v_mfma_f32_16x16x32_bf16 v[170:173], v[122:125], v[78:81], 0
	v_mfma_f32_16x16x32_bf16 v[166:169], v[126:129], v[82:85], v[166:169]
	v_mfma_f32_16x16x32_bf16 v[170:173], v[118:121], v[82:85], v[170:173]
	s_cbranch_vccnz .LBB0_1629
	v_add_u32_e32 v200, s2, v223
	v_add_u32_e32 v194, -15, v200
	v_mov_b32_e32 v244, 0x25dfc
	v_cmp_gt_u32_e32 vcc, s85, v194
	v_mov_b32_e32 v193, 0xff800000
	v_mov_b32_e32 v192, 0xff800000
	ds_write_b32 v244, v192 offset:512
	v_min_u32_e32 v192, 0x7f, v194
	v_lshl_add_u32 v192, v192, 2, s87
	v_cndmask_b32_e32 v192, v244, v192, vcc
	ds_read_b32 v192, v192 offset:512
	v_add_u32_e32 v194, -16, v200
	v_cmp_gt_u32_e32 vcc, s85, v194
	v_min_u32_e32 v193, 0x7f, v194
	v_lshl_add_u32 v193, v193, 2, s87
	v_cndmask_b32_e32 v193, v244, v193, vcc
	ds_read_b32 v193, v193 offset:512
	v_subrev_u32_e32 v196, 17, v200
	v_cmp_gt_u32_e32 vcc, s85, v196
	v_mov_b32_e32 v195, 0xff800000
	v_mov_b32_e32 v194, 0xff800000
	v_min_u32_e32 v194, 0x7f, v196
	v_lshl_add_u32 v194, v194, 2, s87
	v_cndmask_b32_e32 v194, v244, v194, vcc
	ds_read_b32 v194, v194 offset:512
	v_subrev_u32_e32 v196, 18, v200
	v_cmp_gt_u32_e32 vcc, s85, v196
	v_min_u32_e32 v195, 0x7f, v196
	v_lshl_add_u32 v195, v195, 2, s87
	v_cndmask_b32_e32 v195, v244, v195, vcc
	ds_read_b32 v195, v195 offset:512
	v_subrev_u32_e32 v198, 31, v200
	v_cmp_gt_u32_e32 vcc, s85, v198
	v_mov_b32_e32 v197, 0xff800000
	v_mov_b32_e32 v196, 0xff800000
	v_min_u32_e32 v196, 0x7f, v198
	v_lshl_add_u32 v196, v196, 2, s87
	v_cndmask_b32_e32 v196, v244, v196, vcc
	ds_read_b32 v196, v196 offset:512
	v_subrev_u32_e32 v198, 32, v200
	v_cmp_gt_u32_e32 vcc, s85, v198
	v_min_u32_e32 v197, 0x7f, v198
	v_lshl_add_u32 v197, v197, 2, s87
	v_cndmask_b32_e32 v197, v244, v197, vcc
	ds_read_b32 v197, v197 offset:512
	v_subrev_u32_e32 v201, 33, v200
	v_cmp_gt_u32_e32 vcc, s85, v201
	v_mov_b32_e32 v199, 0xff800000
	v_mov_b32_e32 v198, 0xff800000
	v_min_u32_e32 v198, 0x7f, v201
	v_lshl_add_u32 v198, v198, 2, s87
	v_cndmask_b32_e32 v198, v244, v198, vcc
	ds_read_b32 v198, v198 offset:512
	v_subrev_u32_e32 v200, 34, v200
	v_cmp_gt_u32_e32 vcc, s85, v200
	v_min_u32_e32 v199, 0x7f, v200
	v_lshl_add_u32 v199, v199, 2, s87
	v_cndmask_b32_e32 v199, v244, v199, vcc
	ds_read_b32 v199, v199 offset:512
	s_waitcnt lgkmcnt(0)
	v_add_f32_e32 v192, v166, v192
	v_mul_f32_e32 v192, 0x3fb8aa3b, v192
	v_add_f32_e32 v193, v167, v193
	v_mul_f32_e32 v193, 0x3fb8aa3b, v193
	v_add_f32_e32 v194, v168, v194
	v_mul_f32_e32 v194, 0x3fb8aa3b, v194
	v_add_f32_e32 v195, v169, v195
	v_mul_f32_e32 v195, 0x3fb8aa3b, v195
	v_add_f32_e32 v196, v170, v196
	v_mul_f32_e32 v196, 0x3fb8aa3b, v196
	v_add_f32_e32 v197, v171, v197
	v_mul_f32_e32 v197, 0x3fb8aa3b, v197
	v_add_f32_e32 v198, v172, v198
	v_mul_f32_e32 v198, 0x3fb8aa3b, v198
	v_add_f32_e32 v199, v173, v199
	v_mul_f32_e32 v199, 0x3fb8aa3b, v199
	v_max3_f32 v200, v192, s89, v193
	v_max3_f32 v200, v200, v194, v195
	v_max3_f32 v200, v200, v196, v197
	v_max3_f32 v200, v200, v198, v199
	s_mov_b64 s[16:17], 0

.LBB0_1631:
	s_nop 3
	v_mov_b32_e32 v166, v200
	s_nop 1
	v_permlane16_swap_b32 v200, v166
	s_nop 1
	s_mov_b64 s[14:15], -1
	v_max_f32_e32 v166, v166, v166
	v_max_f32_e32 v167, v200, v200
	v_max_f32_e32 v166, v167, v166
	v_mov_b32_e32 v167, v166
	s_nop 1
	v_permlane32_swap_b32 v167, v166
	s_nop 1
	s_and_b64 vcc, exec, s[12:13]
	v_max3_f32 v237, v230, v167, v166
	v_sub_f32_e32 v167, v192, v237
	v_exp_f32_e32 v167, v167
	v_sub_f32_e32 v169, v193, v237
	v_exp_f32_e32 v169, v169
	v_sub_f32_e32 v170, v194, v237
	v_exp_f32_e32 v170, v170
	v_sub_f32_e32 v171, v195, v237
	v_exp_f32_e32 v171, v171
	v_sub_f32_e32 v172, v196, v237
	v_add_f32_e32 v168, 0, v167
	v_exp_f32_e32 v172, v172
	v_sub_f32_e32 v173, v197, v237
	v_add_f32_e32 v168, v169, v168
	v_exp_f32_e32 v173, v173
	v_sub_f32_e32 v192, v198, v237
	v_add_f32_e32 v168, v170, v168
	v_exp_f32_e32 v194, v192
	v_sub_f32_e32 v192, v199, v237
	v_add_f32_e32 v168, v171, v168
	v_exp_f32_e32 v195, v192
	v_add_f32_e32 v168, v172, v168
	v_add_f32_e32 v168, v173, v168
	v_sub_f32_e32 v166, v230, v237
	v_add_f32_e32 v168, v194, v168
	v_add_f32_e32 v168, v195, v168
	v_exp_f32_e32 v192, v166
	v_mov_b32_e32 v166, v168
	s_nop 1
	v_permlane16_swap_b32 v166, v168
	s_nop 1
	s_nop 0
	v_add_f32_e32 v193, v166, v168
	v_mov_b32_e32 v230, v193
	s_nop 1
	v_permlane32_swap_b32 v230, v193
	s_nop 1
	v_cvt_pk_bf16_f32 v166, v167, v169
	v_cvt_pk_bf16_f32 v167, v170, v171
	v_cvt_pk_bf16_f32 v168, v172, v173
	v_cvt_pk_bf16_f32 v169, v194, v195
	v_mfma_f32_16x16x32_bf16 v[170:173], v[122:125], v[86:89], 0
	v_mul_f32_e64 v52, v52, v192
	v_mul_f32_e64 v53, v53, v192
	v_pk_mul_f32 v[50:51], v[50:51], v[192:193] op_sel_hi:[1,0]
	v_pk_mul_f32 v[48:49], v[48:49], v[192:193] op_sel_hi:[1,0]
	v_pk_mul_f32 v[46:47], v[46:47], v[192:193] op_sel_hi:[1,0]
	v_pk_mul_f32 v[44:45], v[44:45], v[192:193] op_sel_hi:[1,0]
	v_pk_mul_f32 v[42:43], v[42:43], v[192:193] op_sel_hi:[1,0]
	v_pk_mul_f32 v[40:41], v[40:41], v[192:193] op_sel_hi:[1,0]
	v_pk_mul_f32 v[38:39], v[38:39], v[192:193] op_sel_hi:[1,0]
	v_mfma_f32_16x16x32_bf16 v[50:53], v[114:117], v[166:169], v[50:53]
	v_mfma_f32_16x16x32_bf16 v[46:49], v[106:109], v[166:169], v[46:49]
	v_mfma_f32_16x16x32_bf16 v[42:45], v[110:113], v[166:169], v[42:45]
	v_mfma_f32_16x16x32_bf16 v[38:41], v[102:105], v[166:169], v[38:41]
	v_mfma_f32_16x16x32_bf16 v[166:169], v[130:133], v[86:89], 0
	v_mfma_f32_16x16x32_bf16 v[166:169], v[126:129], v[90:93], v[166:169]
	v_mfma_f32_16x16x32_bf16 v[170:173], v[118:121], v[90:93], v[170:173]
	s_cbranch_vccnz .LBB0_1649
	v_add_u32_e32 v233, s2, v223
	v_add_u32_e32 v196, -15, v233
	v_mov_b32_e32 v244, 0x25bfc
	v_cmp_gt_u32_e32 vcc, s85, v196
	v_mov_b32_e32 v195, 0xff800000
	v_mov_b32_e32 v194, 0xff800000
	ds_write_b32 v244, v194 offset:1024
	v_min_u32_e32 v194, 0x7f, v196
	v_lshl_add_u32 v194, v194, 2, s87
	v_cndmask_b32_e32 v194, v244, v194, vcc
	ds_read_b32 v194, v194 offset:1024
	v_add_u32_e32 v196, -16, v233
	v_cmp_gt_u32_e32 vcc, s85, v196
	v_min_u32_e32 v195, 0x7f, v196
	v_lshl_add_u32 v195, v195, 2, s87
	v_cndmask_b32_e32 v195, v244, v195, vcc
	ds_read_b32 v195, v195 offset:1024
	v_subrev_u32_e32 v198, 17, v233
	v_cmp_gt_u32_e32 vcc, s85, v198
	v_mov_b32_e32 v197, 0xff800000
	v_mov_b32_e32 v196, 0xff800000
	v_min_u32_e32 v196, 0x7f, v198
	v_lshl_add_u32 v196, v196, 2, s87
	v_cndmask_b32_e32 v196, v244, v196, vcc
	ds_read_b32 v196, v196 offset:1024
	v_subrev_u32_e32 v198, 18, v233
	v_cmp_gt_u32_e32 vcc, s85, v198
	v_min_u32_e32 v197, 0x7f, v198
	v_lshl_add_u32 v197, v197, 2, s87
	v_cndmask_b32_e32 v197, v244, v197, vcc
	ds_read_b32 v197, v197 offset:1024
	v_subrev_u32_e32 v200, 31, v233
	v_cmp_gt_u32_e32 vcc, s85, v200
	v_mov_b32_e32 v199, 0xff800000
	v_mov_b32_e32 v198, 0xff800000
	v_min_u32_e32 v198, 0x7f, v200
	v_lshl_add_u32 v198, v198, 2, s87
	v_cndmask_b32_e32 v198, v244, v198, vcc
	ds_read_b32 v198, v198 offset:1024
	v_subrev_u32_e32 v200, 32, v233
	v_cmp_gt_u32_e32 vcc, s85, v200
	v_min_u32_e32 v199, 0x7f, v200
	v_lshl_add_u32 v199, v199, 2, s87
	v_cndmask_b32_e32 v199, v244, v199, vcc
	ds_read_b32 v199, v199 offset:1024
	v_subrev_u32_e32 v234, 33, v233
	v_cmp_gt_u32_e32 vcc, s85, v234
	v_mov_b32_e32 v201, 0xff800000
	v_mov_b32_e32 v200, 0xff800000
	v_min_u32_e32 v200, 0x7f, v234
	v_lshl_add_u32 v200, v200, 2, s87
	v_cndmask_b32_e32 v200, v244, v200, vcc
	ds_read_b32 v200, v200 offset:1024
	v_subrev_u32_e32 v233, 34, v233
	v_cmp_gt_u32_e32 vcc, s85, v233
	v_min_u32_e32 v201, 0x7f, v233
	v_lshl_add_u32 v201, v201, 2, s87
	v_cndmask_b32_e32 v201, v244, v201, vcc
	ds_read_b32 v201, v201 offset:1024
	s_waitcnt lgkmcnt(0)
	v_add_f32_e32 v194, v166, v194
	v_mul_f32_e32 v194, 0x3fb8aa3b, v194
	v_add_f32_e32 v195, v167, v195
	v_mul_f32_e32 v195, 0x3fb8aa3b, v195
	v_add_f32_e32 v196, v168, v196
	v_mul_f32_e32 v196, 0x3fb8aa3b, v196
	v_add_f32_e32 v197, v169, v197
	v_mul_f32_e32 v197, 0x3fb8aa3b, v197
	v_add_f32_e32 v198, v170, v198
	v_mul_f32_e32 v198, 0x3fb8aa3b, v198
	v_add_f32_e32 v199, v171, v199
	v_mul_f32_e32 v199, 0x3fb8aa3b, v199
	v_add_f32_e32 v200, v172, v200
	v_mul_f32_e32 v200, 0x3fb8aa3b, v200
	v_add_f32_e32 v201, v173, v201
	v_mul_f32_e32 v201, 0x3fb8aa3b, v201
	v_max3_f32 v233, v194, s89, v195
	v_max3_f32 v233, v233, v196, v197
	v_max3_f32 v233, v233, v198, v199
	v_max3_f32 v233, v233, v200, v201
	s_mov_b64 s[14:15], 0

.LBB0_1651:
	s_nop 3
	v_mov_b32_e32 v166, v233
	s_nop 1
	v_permlane16_swap_b32 v233, v166
	s_nop 1
	v_mfma_f32_16x16x32_bf16 v[130:133], v[130:133], v[94:97], 0
	v_max_f32_e32 v166, v166, v166
	v_max_f32_e32 v167, v233, v233
	v_max_f32_e32 v166, v167, v166
	v_mov_b32_e32 v167, v166
	s_nop 1
	v_permlane32_swap_b32 v166, v167
	s_nop 1
	v_mfma_f32_16x16x32_bf16 v[122:125], v[122:125], v[94:97], 0
	v_max3_f32 v238, v229, v166, v167
	v_sub_f32_e32 v168, v195, v238
	v_exp_f32_e32 v172, v168
	v_sub_f32_e32 v168, v196, v238
	v_sub_f32_e32 v166, v229, v238
	v_sub_f32_e32 v167, v194, v238
	v_exp_f32_e32 v173, v168
	v_sub_f32_e32 v168, v197, v238
	v_exp_f32_e32 v167, v167
	v_exp_f32_e32 v194, v168
	v_sub_f32_e32 v168, v198, v238
	v_exp_f32_e32 v166, v166
	v_exp_f32_e32 v195, v168
	v_sub_f32_e32 v168, v199, v238
	v_exp_f32_e32 v196, v168
	v_sub_f32_e32 v168, v200, v238
	v_exp_f32_e32 v197, v168
	v_sub_f32_e32 v168, v201, v238
	v_exp_f32_e32 v198, v168
	v_cvt_pk_bf16_f32 v168, v167, v172
	v_pk_mul_f32 v[36:37], v[36:37], v[166:167] op_sel_hi:[1,0]
	v_pk_mul_f32 v[34:35], v[34:35], v[166:167] op_sel_hi:[1,0]
	v_pk_mul_f32 v[32:33], v[32:33], v[166:167] op_sel_hi:[1,0]
	v_pk_mul_f32 v[30:31], v[30:31], v[166:167] op_sel_hi:[1,0]
	v_pk_mul_f32 v[28:29], v[28:29], v[166:167] op_sel_hi:[1,0]
	v_pk_mul_f32 v[26:27], v[26:27], v[166:167] op_sel_hi:[1,0]
	v_add_f32_e32 v167, 0, v167
	v_pk_mul_f32 v[24:25], v[24:25], v[166:167] op_sel_hi:[1,0]
	v_pk_mul_f32 v[22:23], v[22:23], v[166:167] op_sel_hi:[1,0]
	v_add_f32_e32 v167, v172, v167
	v_add_f32_e32 v167, v173, v167
	v_add_f32_e32 v167, v194, v167
	v_add_f32_e32 v167, v195, v167
	v_add_f32_e32 v167, v196, v167
	v_add_f32_e32 v167, v197, v167
	v_cvt_pk_bf16_f32 v169, v173, v194
	v_cvt_pk_bf16_f32 v170, v195, v196
	v_cvt_pk_bf16_f32 v171, v197, v198
	v_mfma_f32_16x16x32_bf16 v[126:129], v[126:129], v[98:101], v[130:133]
	s_and_b64 vcc, exec, s[12:13]
	s_mov_b64 s[12:13], -1
	v_mfma_f32_16x16x32_bf16 v[34:37], v[114:117], v[168:171], v[34:37]
	v_add_f32_e32 v130, v198, v167
	v_mov_b32_e32 v131, v130
	s_nop 1
	v_permlane16_swap_b32 v130, v131
	s_nop 1
	v_mfma_f32_16x16x32_bf16 v[30:33], v[106:109], v[168:171], v[30:33]
	v_add_f32_e32 v167, v130, v131
	v_mfma_f32_16x16x32_bf16 v[26:29], v[110:113], v[168:171], v[26:29]
	v_mfma_f32_16x16x32_bf16 v[22:25], v[102:105], v[168:171], v[22:25]
	v_mov_b32_e32 v168, v167
	s_nop 1
	v_permlane32_swap_b32 v167, v168
	s_nop 1
	v_mfma_f32_16x16x32_bf16 v[118:121], v[118:121], v[98:101], v[122:125]
	s_cbranch_vccnz .LBB0_1669
	v_add_u32_e32 v169, s2, v223
	s_nop 0
	v_add_u32_e32 v124, -15, v169
	v_mov_b32_e32 v244, 0x259fc
	v_cmp_gt_u32_e32 vcc, s85, v124
	v_mov_b32_e32 v123, 0xff800000
	v_mov_b32_e32 v122, 0xff800000
	ds_write_b32 v244, v122 offset:1536
	v_min_u32_e32 v122, 0x7f, v124
	v_lshl_add_u32 v122, v122, 2, s87
	v_cndmask_b32_e32 v122, v244, v122, vcc
	ds_read_b32 v122, v122 offset:1536
	v_add_u32_e32 v124, -16, v169
	v_cmp_gt_u32_e32 vcc, s85, v124
	v_min_u32_e32 v123, 0x7f, v124
	v_lshl_add_u32 v123, v123, 2, s87
	v_cndmask_b32_e32 v123, v244, v123, vcc
	ds_read_b32 v123, v123 offset:1536
	v_subrev_u32_e32 v130, 17, v169
	v_cmp_gt_u32_e32 vcc, s85, v130
	v_mov_b32_e32 v125, 0xff800000
	v_mov_b32_e32 v124, 0xff800000
	v_min_u32_e32 v124, 0x7f, v130
	v_lshl_add_u32 v124, v124, 2, s87
	v_cndmask_b32_e32 v124, v244, v124, vcc
	ds_read_b32 v124, v124 offset:1536
	v_subrev_u32_e32 v130, 18, v169
	v_cmp_gt_u32_e32 vcc, s85, v130
	v_min_u32_e32 v125, 0x7f, v130
	v_lshl_add_u32 v125, v125, 2, s87
	v_cndmask_b32_e32 v125, v244, v125, vcc
	ds_read_b32 v125, v125 offset:1536
	v_subrev_u32_e32 v132, 31, v169
	v_cmp_gt_u32_e32 vcc, s85, v132
	v_mov_b32_e32 v131, 0xff800000
	v_mov_b32_e32 v130, 0xff800000
	v_min_u32_e32 v130, 0x7f, v132
	v_lshl_add_u32 v130, v130, 2, s87
	v_cndmask_b32_e32 v130, v244, v130, vcc
	ds_read_b32 v130, v130 offset:1536
	v_subrev_u32_e32 v132, 32, v169
	v_cmp_gt_u32_e32 vcc, s85, v132
	v_min_u32_e32 v131, 0x7f, v132
	v_lshl_add_u32 v131, v131, 2, s87
	v_cndmask_b32_e32 v131, v244, v131, vcc
	ds_read_b32 v131, v131 offset:1536
	v_subrev_u32_e32 v170, 33, v169
	v_cmp_gt_u32_e32 vcc, s85, v170
	v_mov_b32_e32 v133, 0xff800000
	v_mov_b32_e32 v132, 0xff800000
	v_min_u32_e32 v132, 0x7f, v170
	v_lshl_add_u32 v132, v132, 2, s87
	v_cndmask_b32_e32 v132, v244, v132, vcc
	ds_read_b32 v132, v132 offset:1536
	v_subrev_u32_e32 v169, 34, v169
	v_cmp_gt_u32_e32 vcc, s85, v169
	v_min_u32_e32 v133, 0x7f, v169
	v_lshl_add_u32 v133, v133, 2, s87
	v_cndmask_b32_e32 v133, v244, v133, vcc
	ds_read_b32 v133, v133 offset:1536
	s_waitcnt lgkmcnt(0)
	v_add_f32_e32 v122, v126, v122
	v_mul_f32_e32 v122, 0x3fb8aa3b, v122
	v_add_f32_e32 v123, v127, v123
	v_mul_f32_e32 v123, 0x3fb8aa3b, v123
	v_add_f32_e32 v124, v128, v124
	v_mul_f32_e32 v124, 0x3fb8aa3b, v124
	v_add_f32_e32 v125, v129, v125
	v_mul_f32_e32 v125, 0x3fb8aa3b, v125
	v_add_f32_e32 v130, v118, v130
	v_mul_f32_e32 v130, 0x3fb8aa3b, v130
	v_add_f32_e32 v131, v119, v131
	v_mul_f32_e32 v131, 0x3fb8aa3b, v131
	v_add_f32_e32 v132, v120, v132
	v_mul_f32_e32 v132, 0x3fb8aa3b, v132
	v_add_f32_e32 v133, v121, v133
	v_mul_f32_e32 v133, 0x3fb8aa3b, v133
	v_max3_f32 v169, v122, s89, v123
	v_max3_f32 v169, v169, v124, v125
	v_max3_f32 v169, v169, v130, v131
	v_max3_f32 v169, v169, v132, v133
	s_mov_b64 s[12:13], 0

.LBB0_1671:
	v_add_f32_e32 v235, v231, v232
	v_fmac_f32_e32 v235, v228, v10
	v_mov_b32_e32 v10, v169
	s_nop 1
	v_permlane16_swap_b32 v169, v10
	s_nop 1
	v_add_f32_e32 v233, v167, v168
	v_max_f32_e32 v10, v10, v10
	v_max_f32_e32 v118, v169, v169
	v_max_f32_e32 v10, v118, v10
	v_mov_b32_e32 v118, v10
	s_nop 1
	v_permlane32_swap_b32 v10, v118
	s_nop 1
	v_add_f32_e32 v234, v230, v193
	v_max3_f32 v239, v225, v10, v118
	v_sub_f32_e32 v118, v122, v239
	v_exp_f32_e32 v118, v118
	v_sub_f32_e32 v119, v123, v239
	v_exp_f32_e32 v119, v119
	v_sub_f32_e32 v120, v124, v239
	v_exp_f32_e32 v120, v120
	v_sub_f32_e32 v121, v125, v239
	v_exp_f32_e32 v121, v121
	v_sub_f32_e32 v123, v130, v239
	v_add_f32_e32 v122, 0, v118
	v_exp_f32_e32 v123, v123
	v_sub_f32_e32 v124, v131, v239
	v_add_f32_e32 v122, v119, v122
	v_exp_f32_e32 v124, v124
	v_sub_f32_e32 v125, v132, v239
	v_add_f32_e32 v122, v120, v122
	v_exp_f32_e32 v125, v125
	v_sub_f32_e32 v126, v133, v239
	v_add_f32_e32 v122, v121, v122
	v_exp_f32_e32 v126, v126
	v_sub_f32_e32 v10, v225, v239
	v_add_f32_e32 v122, v123, v122
	v_add_f32_e32 v122, v124, v122
	v_exp_f32_e32 v10, v10
	v_add_f32_e32 v122, v125, v122
	v_add_f32_e32 v122, v126, v122
	v_mov_b32_e32 v127, v122
	s_nop 1
	v_permlane16_swap_b32 v122, v127
	s_nop 1
	v_pk_mul_f32 v[20:21], v[20:21], v[10:11] op_sel_hi:[1,0]
	v_pk_mul_f32 v[18:19], v[18:19], v[10:11] op_sel_hi:[1,0]
	v_pk_mul_f32 v[16:17], v[16:17], v[10:11] op_sel_hi:[1,0]
	v_pk_mul_f32 v[14:15], v[14:15], v[10:11] op_sel_hi:[1,0]
	v_pk_mul_f32 v[8:9], v[8:9], v[10:11] op_sel_hi:[1,0]
	v_pk_mul_f32 v[6:7], v[6:7], v[10:11] op_sel_hi:[1,0]
	v_pk_mul_f32 v[4:5], v[4:5], v[10:11] op_sel_hi:[1,0]
	v_pk_mul_f32 v[2:3], v[2:3], v[10:11] op_sel_hi:[1,0]
	v_add_f32_e32 v122, v122, v127
	v_cvt_pk_bf16_f32 v118, v118, v119
	v_cvt_pk_bf16_f32 v119, v120, v121
	v_cvt_pk_bf16_f32 v120, v123, v124
	v_cvt_pk_bf16_f32 v121, v125, v126
	v_mov_b32_e32 v127, v122
	v_mfma_f32_16x16x32_bf16 v[18:21], v[114:117], v[118:121], v[18:21]
	s_add_i32 s4, s19, -2
	s_nop 1
	v_permlane32_swap_b32 v122, v127
	s_nop 1
	v_fmac_f32_e32 v233, v226, v166
	v_mfma_f32_16x16x32_bf16 v[14:17], v[106:109], v[118:121], v[14:17]
	v_add_f32_e32 v232, v122, v127
	v_fmac_f32_e32 v234, v227, v192
	v_fmac_f32_e32 v232, v224, v10
	v_mfma_f32_16x16x32_bf16 v[6:9], v[110:113], v[118:121], v[6:9]
	s_cmp_ge_i32 s4, s18
	s_mov_b64 s[12:13], -1
	v_mfma_f32_16x16x32_bf16 v[2:5], v[102:105], v[118:121], v[2:5]
	s_cbranch_scc1 .LBB0_1752
	s_min_i32 s4, s19, s18
	s_ashr_i32 s5, s4, 31
	s_lshl_b64 s[4:5], s[4:5], 12
	v_lshl_add_u64 v[102:103], v[12:13], 0, s[4:5]
	global_load_dwordx4 v[130:133], v[102:103], off
	global_load_dwordx4 v[126:129], v[102:103], off offset:1024
	global_load_dwordx4 v[122:125], v[102:103], off offset:2048
	global_load_dwordx4 v[118:121], v[102:103], off offset:3072
	v_lshl_add_u64 v[102:103], v[182:183], 0, s[4:5]
	global_load_dwordx4 v[114:117], v[102:103], off
	global_load_dwordx4 v[106:109], v[102:103], off offset:1024
	global_load_dwordx4 v[110:113], v[102:103], off offset:2048
	s_nop 0
	global_load_dwordx4 v[102:105], v[102:103], off offset:3072
	s_waitcnt vmcnt(15)
	v_mfma_f32_16x16x32_bf16 v[166:169], v[162:165], v[70:73], 0
	s_add_i32 s4, s2, 0xffffffb2
	s_cmpk_gt_i32 s4, 0x7e
	s_cselect_b64 s[4:5], -1, 0
	s_waitcnt vmcnt(14)
	v_mfma_f32_16x16x32_bf16 v[170:173], v[158:161], v[74:77], v[166:169]
	s_sub_i32 s12, s2, 32
	s_cmpk_lt_i32 s12, 0x200
	s_cselect_b64 s[12:13], -1, 0
	s_waitcnt vmcnt(13)
	v_mfma_f32_16x16x32_bf16 v[166:169], v[154:157], v[70:73], 0
	s_and_b64 s[12:13], s[4:5], s[12:13]
	v_add_u32_e32 v224, s2, v223
	s_mov_b64 s[14:15], -1
	s_waitcnt vmcnt(12)
	v_mfma_f32_16x16x32_bf16 v[166:169], v[150:153], v[74:77], v[166:169]
	s_and_b64 vcc, exec, s[12:13]
	v_subrev_u32_e32 v225, 47, v224
	s_cbranch_vccnz .LBB0_1690
	v_mov_b32_e32 v244, 0x25ffc
	v_cmp_gt_u32_e32 vcc, s85, v225
	v_mov_b32_e32 v193, 0xff800000
	v_mov_b32_e32 v192, 0xff800000
	ds_write_b32 v244, v192
	v_min_u32_e32 v192, 0x7f, v225
	v_lshl_add_u32 v192, v192, 2, s87
	v_cndmask_b32_e32 v192, v244, v192, vcc
	ds_read_b32 v192, v192
	v_subrev_u32_e32 v10, 48, v224
	v_cmp_gt_u32_e32 vcc, s85, v10
	v_min_u32_e32 v193, 0x7f, v10
	v_lshl_add_u32 v193, v193, 2, s87
	v_cndmask_b32_e32 v193, v244, v193, vcc
	ds_read_b32 v193, v193
	v_subrev_u32_e32 v10, 49, v224
	v_cmp_gt_u32_e32 vcc, s85, v10
	v_mov_b32_e32 v195, 0xff800000
	v_mov_b32_e32 v194, 0xff800000
	v_min_u32_e32 v194, 0x7f, v10
	v_lshl_add_u32 v194, v194, 2, s87
	v_cndmask_b32_e32 v194, v244, v194, vcc
	ds_read_b32 v194, v194
	v_subrev_u32_e32 v10, 50, v224
	v_cmp_gt_u32_e32 vcc, s85, v10
	v_min_u32_e32 v195, 0x7f, v10
	v_lshl_add_u32 v195, v195, 2, s87
	v_cndmask_b32_e32 v195, v244, v195, vcc
	ds_read_b32 v195, v195
	v_subrev_u32_e32 v10, 63, v224
	v_cmp_gt_u32_e32 vcc, s85, v10
	v_mov_b32_e32 v197, 0xff800000
	v_mov_b32_e32 v196, 0xff800000
	v_min_u32_e32 v196, 0x7f, v10
	v_lshl_add_u32 v196, v196, 2, s87
	v_cndmask_b32_e32 v196, v244, v196, vcc
	ds_read_b32 v196, v196
	v_subrev_u32_e32 v10, 64, v224
	v_cmp_gt_u32_e32 vcc, s85, v10
	v_min_u32_e32 v197, 0x7f, v10
	v_lshl_add_u32 v197, v197, 2, s87
	v_cndmask_b32_e32 v197, v244, v197, vcc
	ds_read_b32 v197, v197
	v_add_u32_e32 v10, 0xffffffbf, v224
	v_cmp_gt_u32_e32 vcc, s85, v10
	v_mov_b32_e32 v199, 0xff800000
	v_mov_b32_e32 v198, 0xff800000
	v_min_u32_e32 v198, 0x7f, v10
	v_lshl_add_u32 v198, v198, 2, s87
	v_cndmask_b32_e32 v198, v244, v198, vcc
	ds_read_b32 v198, v198
	v_add_u32_e32 v10, 0xffffffbe, v224
	v_cmp_gt_u32_e32 vcc, s85, v10
	v_min_u32_e32 v199, 0x7f, v10
	v_lshl_add_u32 v199, v199, 2, s87
	v_cndmask_b32_e32 v199, v244, v199, vcc
	ds_read_b32 v199, v199
	s_waitcnt lgkmcnt(0)
	v_add_f32_e32 v192, v170, v192
	v_mul_f32_e32 v192, 0x3fb8aa3b, v192
	v_add_f32_e32 v193, v171, v193
	v_mul_f32_e32 v193, 0x3fb8aa3b, v193
	v_add_f32_e32 v194, v172, v194
	v_mul_f32_e32 v194, 0x3fb8aa3b, v194
	v_add_f32_e32 v195, v173, v195
	v_mul_f32_e32 v195, 0x3fb8aa3b, v195
	v_add_f32_e32 v196, v166, v196
	v_mul_f32_e32 v196, 0x3fb8aa3b, v196
	v_add_f32_e32 v197, v167, v197
	v_mul_f32_e32 v197, 0x3fb8aa3b, v197
	v_add_f32_e32 v198, v168, v198
	v_mul_f32_e32 v198, 0x3fb8aa3b, v198
	v_add_f32_e32 v199, v169, v199
	v_mul_f32_e32 v199, 0x3fb8aa3b, v199
	v_max3_f32 v10, v192, s89, v193
	v_max3_f32 v10, v10, v194, v195
	v_max3_f32 v10, v10, v196, v197
	v_max3_f32 v10, v10, v198, v199
	s_mov_b64 s[14:15], 0

.LBB0_1692:
	s_nop 2
	v_mov_b32_e32 v166, v10
	s_nop 1
	v_permlane16_swap_b32 v10, v166
	s_nop 1
	s_xor_b64 s[14:15], s[12:13], -1
	v_max_f32_e32 v166, v166, v166
	v_max_f32_e32 v10, v10, v10
	v_max_f32_e32 v10, v10, v166
	v_mov_b32_e32 v166, v10
	s_nop 1
	v_permlane32_swap_b32 v10, v166
	s_nop 1
	s_mov_b64 s[16:17], -1
	v_max3_f32 v231, v236, v10, v166
	v_sub_f32_e32 v166, v192, v231
	v_exp_f32_e32 v166, v166
	v_sub_f32_e32 v168, v193, v231
	v_exp_f32_e32 v168, v168
	v_sub_f32_e32 v169, v194, v231
	v_exp_f32_e32 v169, v169
	v_sub_f32_e32 v170, v195, v231
	v_exp_f32_e32 v170, v170
	v_sub_f32_e32 v171, v196, v231
	v_add_f32_e32 v167, 0, v166
	v_exp_f32_e32 v171, v171
	v_sub_f32_e32 v172, v197, v231
	v_add_f32_e32 v167, v168, v167
	v_exp_f32_e32 v172, v172
	v_sub_f32_e32 v173, v198, v231
	v_add_f32_e32 v167, v169, v167
	v_exp_f32_e32 v173, v173
	v_sub_f32_e32 v192, v199, v231
	v_add_f32_e32 v167, v170, v167
	v_exp_f32_e32 v192, v192
	v_add_f32_e32 v167, v171, v167
	v_sub_f32_e32 v10, v236, v231
	v_add_f32_e32 v167, v172, v167
	v_add_f32_e32 v167, v173, v167
	v_exp_f32_e32 v10, v10
	v_add_f32_e32 v167, v192, v167
	v_mov_b32_e32 v193, v167
	s_nop 1
	v_permlane16_swap_b32 v167, v193
	s_nop 1
	v_cvt_pk_bf16_f32 v166, v166, v168
	v_cvt_pk_bf16_f32 v168, v171, v172
	v_pk_mul_f32 v[68:69], v[68:69], v[10:11] op_sel_hi:[1,0]
	v_add_f32_e32 v228, v167, v193
	v_cvt_pk_bf16_f32 v167, v169, v170
	v_cvt_pk_bf16_f32 v169, v173, v192
	v_pk_mul_f32 v[66:67], v[66:67], v[10:11] op_sel_hi:[1,0]
	v_pk_mul_f32 v[64:65], v[64:65], v[10:11] op_sel_hi:[1,0]
	v_pk_mul_f32 v[62:63], v[62:63], v[10:11] op_sel_hi:[1,0]
	v_pk_mul_f32 v[60:61], v[60:61], v[10:11] op_sel_hi:[1,0]
	v_pk_mul_f32 v[58:59], v[58:59], v[10:11] op_sel_hi:[1,0]
	v_pk_mul_f32 v[56:57], v[56:57], v[10:11] op_sel_hi:[1,0]
	v_pk_mul_f32 v[54:55], v[54:55], v[10:11] op_sel_hi:[1,0]
	s_waitcnt vmcnt(11)
	v_mfma_f32_16x16x32_bf16 v[66:69], v[146:149], v[166:169], v[66:69]
	v_cndmask_b32_e64 v192, 0, 1, s[14:15]
	v_mov_b32_e32 v236, v228
	v_cmp_ne_u32_e64 s[12:13], 1, v192
	s_waitcnt vmcnt(10)
	v_mfma_f32_16x16x32_bf16 v[62:65], v[138:141], v[166:169], v[62:65]
	s_andn2_b64 vcc, exec, s[14:15]
	s_nop 1
	v_permlane32_swap_b32 v228, v236
	s_nop 1
	s_waitcnt vmcnt(9)
	v_mfma_f32_16x16x32_bf16 v[58:61], v[142:145], v[166:169], v[58:61]
	s_waitcnt vmcnt(8)
	v_mfma_f32_16x16x32_bf16 v[54:57], v[134:137], v[166:169], v[54:57]
	v_mfma_f32_16x16x32_bf16 v[166:169], v[162:165], v[78:81], 0
	v_mfma_f32_16x16x32_bf16 v[170:173], v[154:157], v[78:81], 0
	v_mfma_f32_16x16x32_bf16 v[166:169], v[158:161], v[82:85], v[166:169]
	v_mfma_f32_16x16x32_bf16 v[170:173], v[150:153], v[82:85], v[170:173]
	s_cbranch_vccnz .LBB0_1710
	v_mov_b32_e32 v244, 0x25dfc
	v_cmp_gt_u32_e32 vcc, s85, v225
	v_mov_b32_e32 v193, 0xff800000
	v_mov_b32_e32 v192, 0xff800000
	ds_write_b32 v244, v192 offset:512
	v_min_u32_e32 v192, 0x7f, v225
	v_lshl_add_u32 v192, v192, 2, s87
	v_cndmask_b32_e32 v192, v244, v192, vcc
	ds_read_b32 v192, v192 offset:512
	v_subrev_u32_e32 v194, 48, v224
	v_cmp_gt_u32_e32 vcc, s85, v194
	v_min_u32_e32 v193, 0x7f, v194
	v_lshl_add_u32 v193, v193, 2, s87
	v_cndmask_b32_e32 v193, v244, v193, vcc
	ds_read_b32 v193, v193 offset:512
	v_subrev_u32_e32 v196, 49, v224
	v_cmp_gt_u32_e32 vcc, s85, v196
	v_mov_b32_e32 v195, 0xff800000
	v_mov_b32_e32 v194, 0xff800000
	v_min_u32_e32 v194, 0x7f, v196
	v_lshl_add_u32 v194, v194, 2, s87
	v_cndmask_b32_e32 v194, v244, v194, vcc
	ds_read_b32 v194, v194 offset:512
	v_subrev_u32_e32 v196, 50, v224
	v_cmp_gt_u32_e32 vcc, s85, v196
	v_min_u32_e32 v195, 0x7f, v196
	v_lshl_add_u32 v195, v195, 2, s87
	v_cndmask_b32_e32 v195, v244, v195, vcc
	ds_read_b32 v195, v195 offset:512
	v_subrev_u32_e32 v198, 63, v224
	v_cmp_gt_u32_e32 vcc, s85, v198
	v_mov_b32_e32 v197, 0xff800000
	v_mov_b32_e32 v196, 0xff800000
	v_min_u32_e32 v196, 0x7f, v198
	v_lshl_add_u32 v196, v196, 2, s87
	v_cndmask_b32_e32 v196, v244, v196, vcc
	ds_read_b32 v196, v196 offset:512
	v_subrev_u32_e32 v198, 64, v224
	v_cmp_gt_u32_e32 vcc, s85, v198
	v_min_u32_e32 v197, 0x7f, v198
	v_lshl_add_u32 v197, v197, 2, s87
	v_cndmask_b32_e32 v197, v244, v197, vcc
	ds_read_b32 v197, v197 offset:512
	v_add_u32_e32 v200, 0xffffffbf, v224
	v_cmp_gt_u32_e32 vcc, s85, v200
	v_mov_b32_e32 v199, 0xff800000
	v_mov_b32_e32 v198, 0xff800000
	v_min_u32_e32 v198, 0x7f, v200
	v_lshl_add_u32 v198, v198, 2, s87
	v_cndmask_b32_e32 v198, v244, v198, vcc
	ds_read_b32 v198, v198 offset:512
	v_add_u32_e32 v200, 0xffffffbe, v224
	v_cmp_gt_u32_e32 vcc, s85, v200
	v_min_u32_e32 v199, 0x7f, v200
	v_lshl_add_u32 v199, v199, 2, s87
	v_cndmask_b32_e32 v199, v244, v199, vcc
	ds_read_b32 v199, v199 offset:512
	s_waitcnt lgkmcnt(0)
	v_add_f32_e32 v192, v166, v192
	v_mul_f32_e32 v192, 0x3fb8aa3b, v192
	v_add_f32_e32 v193, v167, v193
	v_mul_f32_e32 v193, 0x3fb8aa3b, v193
	v_add_f32_e32 v194, v168, v194
	v_mul_f32_e32 v194, 0x3fb8aa3b, v194
	v_add_f32_e32 v195, v169, v195
	v_mul_f32_e32 v195, 0x3fb8aa3b, v195
	v_add_f32_e32 v196, v170, v196
	v_mul_f32_e32 v196, 0x3fb8aa3b, v196
	v_add_f32_e32 v197, v171, v197
	v_mul_f32_e32 v197, 0x3fb8aa3b, v197
	v_add_f32_e32 v198, v172, v198
	v_mul_f32_e32 v198, 0x3fb8aa3b, v198
	v_add_f32_e32 v199, v173, v199
	v_mul_f32_e32 v199, 0x3fb8aa3b, v199
	v_max3_f32 v200, v192, s89, v193
	v_max3_f32 v200, v200, v194, v195
	v_max3_f32 v200, v200, v196, v197
	v_max3_f32 v200, v200, v198, v199
	s_mov_b64 s[16:17], 0

.LBB0_1712:
	s_nop 3
	v_mov_b32_e32 v166, v200
	s_nop 1
	v_permlane16_swap_b32 v200, v166
	s_nop 1
	s_mov_b64 s[14:15], -1
	v_max_f32_e32 v166, v166, v166
	v_max_f32_e32 v167, v200, v200
	v_max_f32_e32 v166, v167, v166
	v_mov_b32_e32 v167, v166
	s_nop 1
	v_permlane32_swap_b32 v166, v167
	s_nop 1
	s_and_b64 vcc, exec, s[12:13]
	v_max3_f32 v230, v237, v166, v167
	v_sub_f32_e32 v167, v192, v230
	v_exp_f32_e32 v167, v167
	v_sub_f32_e32 v169, v193, v230
	v_exp_f32_e32 v169, v169
	v_sub_f32_e32 v170, v194, v230
	v_exp_f32_e32 v170, v170
	v_sub_f32_e32 v171, v195, v230
	v_exp_f32_e32 v171, v171
	v_sub_f32_e32 v172, v196, v230
	v_add_f32_e32 v168, 0, v167
	v_exp_f32_e32 v172, v172
	v_sub_f32_e32 v173, v197, v230
	v_add_f32_e32 v168, v169, v168
	v_exp_f32_e32 v173, v173
	v_sub_f32_e32 v192, v198, v230
	v_add_f32_e32 v168, v170, v168
	v_exp_f32_e32 v194, v192
	v_sub_f32_e32 v192, v199, v230
	v_add_f32_e32 v168, v171, v168
	v_exp_f32_e32 v195, v192
	v_add_f32_e32 v168, v172, v168
	v_add_f32_e32 v168, v173, v168
	v_sub_f32_e32 v166, v237, v230
	v_add_f32_e32 v168, v194, v168
	v_add_f32_e32 v168, v195, v168
	v_exp_f32_e32 v192, v166
	v_mov_b32_e32 v166, v168
	s_nop 1
	v_permlane16_swap_b32 v168, v166
	s_nop 1
	s_nop 0
	v_add_f32_e32 v193, v168, v166
	v_mov_b32_e32 v227, v193
	s_nop 1
	v_permlane32_swap_b32 v193, v227
	s_nop 1
	v_cvt_pk_bf16_f32 v166, v167, v169
	v_cvt_pk_bf16_f32 v167, v170, v171
	v_cvt_pk_bf16_f32 v168, v172, v173
	v_cvt_pk_bf16_f32 v169, v194, v195
	v_mfma_f32_16x16x32_bf16 v[170:173], v[154:157], v[86:89], 0
	v_mul_f32_e64 v52, v52, v192
	v_mul_f32_e64 v53, v53, v192
	v_pk_mul_f32 v[50:51], v[50:51], v[192:193] op_sel_hi:[1,0]
	v_pk_mul_f32 v[48:49], v[48:49], v[192:193] op_sel_hi:[1,0]
	v_pk_mul_f32 v[46:47], v[46:47], v[192:193] op_sel_hi:[1,0]
	v_pk_mul_f32 v[44:45], v[44:45], v[192:193] op_sel_hi:[1,0]
	v_pk_mul_f32 v[42:43], v[42:43], v[192:193] op_sel_hi:[1,0]
	v_pk_mul_f32 v[40:41], v[40:41], v[192:193] op_sel_hi:[1,0]
	v_pk_mul_f32 v[38:39], v[38:39], v[192:193] op_sel_hi:[1,0]
	v_mfma_f32_16x16x32_bf16 v[50:53], v[146:149], v[166:169], v[50:53]
	v_mfma_f32_16x16x32_bf16 v[46:49], v[138:141], v[166:169], v[46:49]
	v_mfma_f32_16x16x32_bf16 v[42:45], v[142:145], v[166:169], v[42:45]
	v_mfma_f32_16x16x32_bf16 v[38:41], v[134:137], v[166:169], v[38:41]
	v_mfma_f32_16x16x32_bf16 v[166:169], v[162:165], v[86:89], 0
	v_mfma_f32_16x16x32_bf16 v[166:169], v[158:161], v[90:93], v[166:169]
	v_mfma_f32_16x16x32_bf16 v[170:173], v[150:153], v[90:93], v[170:173]
	s_cbranch_vccnz .LBB0_1730
	v_mov_b32_e32 v244, 0x25bfc
	v_cmp_gt_u32_e32 vcc, s85, v225
	v_mov_b32_e32 v195, 0xff800000
	v_mov_b32_e32 v194, 0xff800000
	ds_write_b32 v244, v194 offset:1024
	v_min_u32_e32 v194, 0x7f, v225
	v_lshl_add_u32 v194, v194, 2, s87
	v_cndmask_b32_e32 v194, v244, v194, vcc
	ds_read_b32 v194, v194 offset:1024
	v_subrev_u32_e32 v196, 48, v224
	v_cmp_gt_u32_e32 vcc, s85, v196
	v_min_u32_e32 v195, 0x7f, v196
	v_lshl_add_u32 v195, v195, 2, s87
	v_cndmask_b32_e32 v195, v244, v195, vcc
	ds_read_b32 v195, v195 offset:1024
	v_subrev_u32_e32 v198, 49, v224
	v_cmp_gt_u32_e32 vcc, s85, v198
	v_mov_b32_e32 v197, 0xff800000
	v_mov_b32_e32 v196, 0xff800000
	v_min_u32_e32 v196, 0x7f, v198
	v_lshl_add_u32 v196, v196, 2, s87
	v_cndmask_b32_e32 v196, v244, v196, vcc
	ds_read_b32 v196, v196 offset:1024
	v_subrev_u32_e32 v198, 50, v224
	v_cmp_gt_u32_e32 vcc, s85, v198
	v_min_u32_e32 v197, 0x7f, v198
	v_lshl_add_u32 v197, v197, 2, s87
	v_cndmask_b32_e32 v197, v244, v197, vcc
	ds_read_b32 v197, v197 offset:1024
	v_subrev_u32_e32 v200, 63, v224
	v_cmp_gt_u32_e32 vcc, s85, v200
	v_mov_b32_e32 v199, 0xff800000
	v_mov_b32_e32 v198, 0xff800000
	v_min_u32_e32 v198, 0x7f, v200
	v_lshl_add_u32 v198, v198, 2, s87
	v_cndmask_b32_e32 v198, v244, v198, vcc
	ds_read_b32 v198, v198 offset:1024
	v_subrev_u32_e32 v200, 64, v224
	v_cmp_gt_u32_e32 vcc, s85, v200
	v_min_u32_e32 v199, 0x7f, v200
	v_lshl_add_u32 v199, v199, 2, s87
	v_cndmask_b32_e32 v199, v244, v199, vcc
	ds_read_b32 v199, v199 offset:1024
	v_add_u32_e32 v226, 0xffffffbf, v224
	v_cmp_gt_u32_e32 vcc, s85, v226
	v_mov_b32_e32 v201, 0xff800000
	v_mov_b32_e32 v200, 0xff800000
	v_min_u32_e32 v200, 0x7f, v226
	v_lshl_add_u32 v200, v200, 2, s87
	v_cndmask_b32_e32 v200, v244, v200, vcc
	ds_read_b32 v200, v200 offset:1024
	v_add_u32_e32 v226, 0xffffffbe, v224
	v_cmp_gt_u32_e32 vcc, s85, v226
	v_min_u32_e32 v201, 0x7f, v226
	v_lshl_add_u32 v201, v201, 2, s87
	v_cndmask_b32_e32 v201, v244, v201, vcc
	ds_read_b32 v201, v201 offset:1024
	s_waitcnt lgkmcnt(0)
	v_add_f32_e32 v194, v166, v194
	v_mul_f32_e32 v194, 0x3fb8aa3b, v194
	v_add_f32_e32 v195, v167, v195
	v_mul_f32_e32 v195, 0x3fb8aa3b, v195
	v_add_f32_e32 v196, v168, v196
	v_mul_f32_e32 v196, 0x3fb8aa3b, v196
	v_add_f32_e32 v197, v169, v197
	v_mul_f32_e32 v197, 0x3fb8aa3b, v197
	v_add_f32_e32 v198, v170, v198
	v_mul_f32_e32 v198, 0x3fb8aa3b, v198
	v_add_f32_e32 v199, v171, v199
	v_mul_f32_e32 v199, 0x3fb8aa3b, v199
	v_add_f32_e32 v200, v172, v200
	v_mul_f32_e32 v200, 0x3fb8aa3b, v200
	v_add_f32_e32 v201, v173, v201
	v_mul_f32_e32 v201, 0x3fb8aa3b, v201
	v_max3_f32 v226, v194, s89, v195
	v_max3_f32 v226, v226, v196, v197
	v_max3_f32 v226, v226, v198, v199
	v_max3_f32 v226, v226, v200, v201
	s_mov_b64 s[14:15], 0

.LBB0_1732:
	s_nop 3
	v_mov_b32_e32 v166, v226
	s_nop 1
	v_permlane16_swap_b32 v226, v166
	s_nop 1
	v_mfma_f32_16x16x32_bf16 v[162:165], v[162:165], v[94:97], 0
	v_max_f32_e32 v166, v166, v166
	v_max_f32_e32 v167, v226, v226
	v_max_f32_e32 v166, v167, v166
	v_mov_b32_e32 v167, v166
	s_nop 1
	v_permlane32_swap_b32 v166, v167
	s_nop 1
	v_mfma_f32_16x16x32_bf16 v[154:157], v[154:157], v[94:97], 0
	v_max3_f32 v229, v238, v166, v167
	v_sub_f32_e32 v168, v195, v229
	v_exp_f32_e32 v172, v168
	v_sub_f32_e32 v168, v196, v229
	v_sub_f32_e32 v166, v238, v229
	v_sub_f32_e32 v167, v194, v229
	v_exp_f32_e32 v173, v168
	v_sub_f32_e32 v168, v197, v229
	v_exp_f32_e32 v167, v167
	v_exp_f32_e32 v194, v168
	v_sub_f32_e32 v168, v198, v229
	v_exp_f32_e32 v166, v166
	v_exp_f32_e32 v195, v168
	v_sub_f32_e32 v168, v199, v229
	v_exp_f32_e32 v196, v168
	v_sub_f32_e32 v168, v200, v229
	v_exp_f32_e32 v197, v168
	v_sub_f32_e32 v168, v201, v229
	v_exp_f32_e32 v198, v168
	v_cvt_pk_bf16_f32 v168, v167, v172
	v_pk_mul_f32 v[36:37], v[36:37], v[166:167] op_sel_hi:[1,0]
	v_pk_mul_f32 v[34:35], v[34:35], v[166:167] op_sel_hi:[1,0]
	v_pk_mul_f32 v[32:33], v[32:33], v[166:167] op_sel_hi:[1,0]
	v_pk_mul_f32 v[30:31], v[30:31], v[166:167] op_sel_hi:[1,0]
	v_pk_mul_f32 v[28:29], v[28:29], v[166:167] op_sel_hi:[1,0]
	v_pk_mul_f32 v[26:27], v[26:27], v[166:167] op_sel_hi:[1,0]
	v_add_f32_e32 v167, 0, v167
	v_pk_mul_f32 v[24:25], v[24:25], v[166:167] op_sel_hi:[1,0]
	v_pk_mul_f32 v[22:23], v[22:23], v[166:167] op_sel_hi:[1,0]
	v_add_f32_e32 v167, v172, v167
	v_add_f32_e32 v167, v173, v167
	v_add_f32_e32 v167, v194, v167
	v_add_f32_e32 v167, v195, v167
	v_add_f32_e32 v167, v196, v167
	v_add_f32_e32 v167, v197, v167
	v_cvt_pk_bf16_f32 v169, v173, v194
	v_cvt_pk_bf16_f32 v170, v195, v196
	v_cvt_pk_bf16_f32 v171, v197, v198
	v_mfma_f32_16x16x32_bf16 v[158:161], v[158:161], v[98:101], v[162:165]
	s_and_b64 vcc, exec, s[12:13]
	s_mov_b64 s[12:13], -1
	v_mfma_f32_16x16x32_bf16 v[34:37], v[146:149], v[168:171], v[34:37]
	v_add_f32_e32 v162, v198, v167
	v_mov_b32_e32 v163, v162
	s_nop 1
	v_permlane16_swap_b32 v162, v163
	s_nop 1
	v_mfma_f32_16x16x32_bf16 v[30:33], v[138:141], v[168:171], v[30:33]
	v_add_f32_e32 v167, v162, v163
	v_mfma_f32_16x16x32_bf16 v[26:29], v[142:145], v[168:171], v[26:29]
	v_mfma_f32_16x16x32_bf16 v[22:25], v[134:137], v[168:171], v[22:25]
	v_mov_b32_e32 v168, v167
	s_nop 1
	v_permlane32_swap_b32 v167, v168
	s_nop 1
	v_mfma_f32_16x16x32_bf16 v[150:153], v[150:153], v[98:101], v[154:157]
	s_cbranch_vccnz .LBB0_1750
	v_mov_b32_e32 v244, 0x259fc
	v_cmp_gt_u32_e32 vcc, s85, v225
	s_nop 0
	v_mov_b32_e32 v155, 0xff800000
	v_mov_b32_e32 v154, 0xff800000
	ds_write_b32 v244, v154 offset:1536
	v_min_u32_e32 v154, 0x7f, v225
	v_lshl_add_u32 v154, v154, 2, s87
	v_cndmask_b32_e32 v154, v244, v154, vcc
	ds_read_b32 v154, v154 offset:1536
	v_subrev_u32_e32 v156, 48, v224
	v_cmp_gt_u32_e32 vcc, s85, v156
	v_min_u32_e32 v155, 0x7f, v156
	v_lshl_add_u32 v155, v155, 2, s87
	v_cndmask_b32_e32 v155, v244, v155, vcc
	ds_read_b32 v155, v155 offset:1536
	v_subrev_u32_e32 v162, 49, v224
	v_cmp_gt_u32_e32 vcc, s85, v162
	v_mov_b32_e32 v157, 0xff800000
	v_mov_b32_e32 v156, 0xff800000
	v_min_u32_e32 v156, 0x7f, v162
	v_lshl_add_u32 v156, v156, 2, s87
	v_cndmask_b32_e32 v156, v244, v156, vcc
	ds_read_b32 v156, v156 offset:1536
	v_subrev_u32_e32 v162, 50, v224
	v_cmp_gt_u32_e32 vcc, s85, v162
	v_min_u32_e32 v157, 0x7f, v162
	v_lshl_add_u32 v157, v157, 2, s87
	v_cndmask_b32_e32 v157, v244, v157, vcc
	ds_read_b32 v157, v157 offset:1536
	v_subrev_u32_e32 v164, 63, v224
	v_cmp_gt_u32_e32 vcc, s85, v164
	v_mov_b32_e32 v163, 0xff800000
	v_mov_b32_e32 v162, 0xff800000
	v_min_u32_e32 v162, 0x7f, v164
	v_lshl_add_u32 v162, v162, 2, s87
	v_cndmask_b32_e32 v162, v244, v162, vcc
	ds_read_b32 v162, v162 offset:1536
	v_subrev_u32_e32 v164, 64, v224
	v_cmp_gt_u32_e32 vcc, s85, v164
	v_min_u32_e32 v163, 0x7f, v164
	v_lshl_add_u32 v163, v163, 2, s87
	v_cndmask_b32_e32 v163, v244, v163, vcc
	ds_read_b32 v163, v163 offset:1536
	v_add_u32_e32 v169, 0xffffffbf, v224
	v_cmp_gt_u32_e32 vcc, s85, v169
	v_mov_b32_e32 v165, 0xff800000
	v_mov_b32_e32 v164, 0xff800000
	v_min_u32_e32 v164, 0x7f, v169
	v_lshl_add_u32 v164, v164, 2, s87
	v_cndmask_b32_e32 v164, v244, v164, vcc
	ds_read_b32 v164, v164 offset:1536
	v_add_u32_e32 v169, 0xffffffbe, v224
	v_cmp_gt_u32_e32 vcc, s85, v169
	v_min_u32_e32 v165, 0x7f, v169
	v_lshl_add_u32 v165, v165, 2, s87
	v_cndmask_b32_e32 v165, v244, v165, vcc
	ds_read_b32 v165, v165 offset:1536
	s_waitcnt lgkmcnt(0)
	v_add_f32_e32 v154, v158, v154
	v_mul_f32_e32 v154, 0x3fb8aa3b, v154
	v_add_f32_e32 v155, v159, v155
	v_mul_f32_e32 v155, 0x3fb8aa3b, v155
	v_add_f32_e32 v156, v160, v156
	v_mul_f32_e32 v156, 0x3fb8aa3b, v156
	v_add_f32_e32 v157, v161, v157
	v_mul_f32_e32 v157, 0x3fb8aa3b, v157
	v_add_f32_e32 v162, v150, v162
	v_mul_f32_e32 v162, 0x3fb8aa3b, v162
	v_add_f32_e32 v163, v151, v163
	v_mul_f32_e32 v163, 0x3fb8aa3b, v163
	v_add_f32_e32 v164, v152, v164
	v_mul_f32_e32 v164, 0x3fb8aa3b, v164
	v_add_f32_e32 v165, v153, v165
	v_mul_f32_e32 v165, 0x3fb8aa3b, v165
	v_max3_f32 v169, v154, s89, v155
	v_max3_f32 v169, v169, v156, v157
	v_max3_f32 v169, v169, v162, v163
	v_max3_f32 v169, v169, v164, v165
	s_mov_b64 s[12:13], 0

.LBB0_1760:
	s_add_i32 s40, s23, 1
	s_waitcnt vmcnt(0)
	v_mfma_f32_16x16x32_bf16 v[52:55], v[48:51], v[12:15], 0
	s_min_i32 s48, s40, s21
	s_lshl_b64 s[4:5], s[48:49], 12
	v_lshl_add_u64 v[68:69], v[84:85], 0, s[4:5]
	global_load_dwordx4 v[64:67], v[68:69], off
	global_load_dwordx4 v[60:63], v[68:69], off offset:1024
	v_mfma_f32_16x16x32_bf16 v[76:79], v[44:47], v[16:19], v[52:55]
	global_load_dwordx4 v[56:59], v[68:69], off offset:2048
	s_nop 1
	global_load_dwordx4 v[52:55], v[68:69], off offset:3072
	s_add_i32 s4, s27, 0x200
	s_cmpk_lt_i32 s4, 0x7f
	v_mfma_f32_16x16x32_bf16 v[68:71], v[2:5], v[12:15], 0
	s_cselect_b64 s[30:31], -1, 0
	s_cmpk_gt_i32 s4, 0x7e
	s_mov_b64 s[12:13], -1
	v_mfma_f32_16x16x32_bf16 v[72:75], v[6:9], v[16:19], v[68:71]
	s_cbranch_scc1 .LBB0_1778
	v_add_u32_e32 v95, s27, v94
	s_nop 1
	v_add_u32_e32 v70, 0x3f0, v95
	v_mov_b32_e32 v190, 0x25ffc
	v_cmp_lt_i32_e32 vcc, -1, v70
	v_mov_b32_e32 v69, 0xff800000
	v_mov_b32_e32 v68, 0xff800000
	ds_write_b32 v190, v68
	v_min_u32_e32 v68, 0x7f, v70
	v_lshl_add_u32 v68, v68, 2, s87
	v_cndmask_b32_e32 v68, v190, v68, vcc
	ds_read_b32 v68, v68
	v_add_u32_e32 v70, 0x3e0, v95
	v_cmp_lt_i32_e32 vcc, -1, v70
	v_min_u32_e32 v69, 0x7f, v70
	v_lshl_add_u32 v69, v69, 2, s87
	v_cndmask_b32_e32 v69, v190, v69, vcc
	ds_read_b32 v69, v69
	v_add_u32_e32 v80, 0x3d0, v95
	v_cmp_lt_i32_e32 vcc, -1, v80
	v_mov_b32_e32 v71, 0xff800000
	v_mov_b32_e32 v70, 0xff800000
	v_min_u32_e32 v70, 0x7f, v80
	v_lshl_add_u32 v70, v70, 2, s87
	v_cndmask_b32_e32 v70, v190, v70, vcc
	ds_read_b32 v70, v70
	v_add_u32_e32 v80, 0x3c0, v95
	v_cmp_lt_i32_e32 vcc, -1, v80
	v_min_u32_e32 v71, 0x7f, v80
	v_lshl_add_u32 v71, v71, 2, s87
	v_cndmask_b32_e32 v71, v190, v71, vcc
	ds_read_b32 v71, v71
	v_add_u32_e32 v82, 0x2f0, v95
	v_cmp_lt_i32_e32 vcc, -1, v82
	v_mov_b32_e32 v81, 0xff800000
	v_mov_b32_e32 v80, 0xff800000
	v_min_u32_e32 v80, 0x7f, v82
	v_lshl_add_u32 v80, v80, 2, s87
	v_cndmask_b32_e32 v80, v190, v80, vcc
	ds_read_b32 v80, v80
	v_add_u32_e32 v82, 0x2e0, v95
	v_cmp_lt_i32_e32 vcc, -1, v82
	v_min_u32_e32 v81, 0x7f, v82
	v_lshl_add_u32 v81, v81, 2, s87
	v_cndmask_b32_e32 v81, v190, v81, vcc
	ds_read_b32 v81, v81
	v_add_u32_e32 v96, 0x2d0, v95
	v_cmp_lt_i32_e32 vcc, -1, v96
	v_mov_b32_e32 v83, 0xff800000
	v_mov_b32_e32 v82, 0xff800000
	v_min_u32_e32 v82, 0x7f, v96
	v_lshl_add_u32 v82, v82, 2, s87
	v_cndmask_b32_e32 v82, v190, v82, vcc
	ds_read_b32 v82, v82
	v_add_u32_e32 v95, 0x2c0, v95
	v_cmp_lt_i32_e32 vcc, -1, v95
	v_min_u32_e32 v83, 0x7f, v95
	v_lshl_add_u32 v83, v83, 2, s87
	v_cndmask_b32_e32 v83, v190, v83, vcc
	ds_read_b32 v83, v83
	s_waitcnt lgkmcnt(0)
	v_add_f32_e32 v68, v76, v68
	v_mul_f32_e32 v68, 0x3fb8aa3b, v68
	v_add_f32_e32 v69, v77, v69
	v_mul_f32_e32 v69, 0x3fb8aa3b, v69
	v_add_f32_e32 v70, v78, v70
	v_mul_f32_e32 v70, 0x3fb8aa3b, v70
	v_add_f32_e32 v71, v79, v71
	v_mul_f32_e32 v71, 0x3fb8aa3b, v71
	v_add_f32_e32 v80, v72, v80
	v_mul_f32_e32 v80, 0x3fb8aa3b, v80
	v_add_f32_e32 v81, v73, v81
	v_mul_f32_e32 v81, 0x3fb8aa3b, v81
	v_add_f32_e32 v82, v74, v82
	v_mul_f32_e32 v82, 0x3fb8aa3b, v82
	v_add_f32_e32 v83, v75, v83
	v_mul_f32_e32 v83, 0x3fb8aa3b, v83
	s_mov_b64 s[12:13], 0

.LBB0_1780:
	s_nop 4
	v_max_f32_e32 v72, v69, v69
	v_max_f32_e32 v73, v68, v68
	v_max_f32_e32 v72, v73, v72
	v_max_f32_e32 v73, v71, v71
	v_max_f32_e32 v74, v70, v70
	v_max_f32_e32 v73, v74, v73
	v_max_f32_e32 v74, v83, v83
	v_max_f32_e32 v75, v82, v82
	v_max_f32_e32 v74, v75, v74
	v_max3_f32 v74, v80, v81, v74
	v_max3_f32 v72, v72, v73, v74
	v_mov_b32_e32 v73, v72
	s_nop 1
	v_permlane16_swap_b32 v72, v73
	s_nop 1
	s_andn2_b64 vcc, exec, s[30:31]
	v_max_f32_e32 v73, v73, v73
	v_max_f32_e32 v72, v72, v72
	v_max_f32_e32 v72, v72, v73
	v_mov_b32_e32 v73, v72
	s_nop 1
	v_permlane32_swap_b32 v72, v73
	s_nop 1
	s_nop 0
	v_max3_f32 v95, v111, v72, v73
	v_sub_f32_e32 v68, v68, v95
	v_exp_f32_e32 v68, v68
	v_sub_f32_e32 v69, v69, v95
	v_exp_f32_e32 v69, v69
	v_sub_f32_e32 v70, v70, v95
	v_exp_f32_e32 v70, v70
	v_sub_f32_e32 v71, v71, v95
	v_exp_f32_e32 v71, v71
	v_sub_f32_e32 v72, v80, v95
	v_add_f32_e32 v68, 0, v68
	v_exp_f32_e32 v72, v72
	v_add_f32_e32 v68, v69, v68
	v_add_f32_e32 v68, v70, v68
	v_add_f32_e32 v68, v71, v68
	v_add_f32_e32 v72, v72, v68
	v_sub_f32_e32 v68, v81, v95
	v_exp_f32_e32 v73, v68
	v_sub_f32_e32 v68, v82, v95
	v_exp_f32_e32 v74, v68
	v_sub_f32_e32 v75, v83, v95
	v_mfma_f32_16x16x32_bf16 v[68:71], v[48:51], v[20:23], 0
	v_exp_f32_e32 v75, v75
	v_add_f32_e32 v72, v73, v72
	v_add_f32_e32 v72, v74, v72
	v_mfma_f32_16x16x32_bf16 v[76:79], v[44:47], v[24:27], v[68:71]
	v_add_f32_e32 v72, v75, v72
	v_mov_b32_e32 v73, v72
	s_nop 1
	v_permlane16_swap_b32 v72, v73
	s_nop 1
	v_mfma_f32_16x16x32_bf16 v[68:71], v[2:5], v[20:23], 0
	v_add_f32_e32 v104, v72, v73
	v_mov_b32_e32 v106, v104
	s_nop 1
	v_permlane32_swap_b32 v104, v106
	s_nop 1
	v_mfma_f32_16x16x32_bf16 v[72:75], v[6:9], v[24:27], v[68:71]
	s_nop 4
	v_cndmask_b32_e64 v68, 0, 1, s[30:31]
	v_cmp_ne_u32_e64 s[12:13], 1, v68
	s_mov_b64 s[30:31], -1
	s_cbranch_vccnz .LBB0_1798
	v_add_u32_e32 v96, s27, v94
	v_add_u32_e32 v70, 0x3f0, v96
	v_mov_b32_e32 v190, 0x25dfc
	v_cmp_lt_i32_e32 vcc, -1, v70
	v_mov_b32_e32 v69, 0xff800000
	v_mov_b32_e32 v68, 0xff800000
	ds_write_b32 v190, v68 offset:512
	v_min_u32_e32 v68, 0x7f, v70
	v_lshl_add_u32 v68, v68, 2, s87
	v_cndmask_b32_e32 v68, v190, v68, vcc
	ds_read_b32 v68, v68 offset:512
	v_add_u32_e32 v70, 0x3e0, v96
	v_cmp_lt_i32_e32 vcc, -1, v70
	v_min_u32_e32 v69, 0x7f, v70
	v_lshl_add_u32 v69, v69, 2, s87
	v_cndmask_b32_e32 v69, v190, v69, vcc
	ds_read_b32 v69, v69 offset:512
	v_add_u32_e32 v80, 0x3d0, v96
	v_cmp_lt_i32_e32 vcc, -1, v80
	v_mov_b32_e32 v71, 0xff800000
	v_mov_b32_e32 v70, 0xff800000
	v_min_u32_e32 v70, 0x7f, v80
	v_lshl_add_u32 v70, v70, 2, s87
	v_cndmask_b32_e32 v70, v190, v70, vcc
	ds_read_b32 v70, v70 offset:512
	v_add_u32_e32 v80, 0x3c0, v96
	v_cmp_lt_i32_e32 vcc, -1, v80
	v_min_u32_e32 v71, 0x7f, v80
	v_lshl_add_u32 v71, v71, 2, s87
	v_cndmask_b32_e32 v71, v190, v71, vcc
	ds_read_b32 v71, v71 offset:512
	v_add_u32_e32 v82, 0x2f0, v96
	v_cmp_lt_i32_e32 vcc, -1, v82
	v_mov_b32_e32 v81, 0xff800000
	v_mov_b32_e32 v80, 0xff800000
	v_min_u32_e32 v80, 0x7f, v82
	v_lshl_add_u32 v80, v80, 2, s87
	v_cndmask_b32_e32 v80, v190, v80, vcc
	ds_read_b32 v80, v80 offset:512
	v_add_u32_e32 v82, 0x2e0, v96
	v_cmp_lt_i32_e32 vcc, -1, v82
	v_min_u32_e32 v81, 0x7f, v82
	v_lshl_add_u32 v81, v81, 2, s87
	v_cndmask_b32_e32 v81, v190, v81, vcc
	ds_read_b32 v81, v81 offset:512
	v_add_u32_e32 v97, 0x2d0, v96
	v_cmp_lt_i32_e32 vcc, -1, v97
	v_mov_b32_e32 v83, 0xff800000
	v_mov_b32_e32 v82, 0xff800000
	v_min_u32_e32 v82, 0x7f, v97
	v_lshl_add_u32 v82, v82, 2, s87
	v_cndmask_b32_e32 v82, v190, v82, vcc
	ds_read_b32 v82, v82 offset:512
	v_add_u32_e32 v96, 0x2c0, v96
	v_cmp_lt_i32_e32 vcc, -1, v96
	v_min_u32_e32 v83, 0x7f, v96
	v_lshl_add_u32 v83, v83, 2, s87
	v_cndmask_b32_e32 v83, v190, v83, vcc
	ds_read_b32 v83, v83 offset:512
	s_waitcnt lgkmcnt(0)
	v_add_f32_e32 v68, v76, v68
	v_mul_f32_e32 v68, 0x3fb8aa3b, v68
	v_add_f32_e32 v69, v77, v69
	v_mul_f32_e32 v69, 0x3fb8aa3b, v69
	v_add_f32_e32 v70, v78, v70
	v_mul_f32_e32 v70, 0x3fb8aa3b, v70
	v_add_f32_e32 v71, v79, v71
	v_mul_f32_e32 v71, 0x3fb8aa3b, v71
	v_add_f32_e32 v80, v72, v80
	v_mul_f32_e32 v80, 0x3fb8aa3b, v80
	v_add_f32_e32 v81, v73, v81
	v_mul_f32_e32 v81, 0x3fb8aa3b, v81
	v_add_f32_e32 v82, v74, v82
	v_mul_f32_e32 v82, 0x3fb8aa3b, v82
	v_add_f32_e32 v83, v75, v83
	v_mul_f32_e32 v83, 0x3fb8aa3b, v83
	s_mov_b64 s[30:31], 0

.LBB0_1800:
	v_max_f32_e32 v72, v69, v69
	v_max_f32_e32 v73, v68, v68
	v_max_f32_e32 v72, v73, v72
	v_max_f32_e32 v73, v71, v71
	v_max_f32_e32 v74, v70, v70
	v_max_f32_e32 v73, v74, v73
	v_max_f32_e32 v74, v83, v83
	v_max_f32_e32 v75, v82, v82
	v_max_f32_e32 v74, v75, v74
	v_max3_f32 v74, v80, v81, v74
	v_max3_f32 v72, v72, v73, v74
	v_mov_b32_e32 v73, v72
	s_nop 1
	v_permlane16_swap_b32 v72, v73
	s_nop 1
	s_and_b64 vcc, exec, s[12:13]
	v_max_f32_e32 v73, v73, v73
	v_max_f32_e32 v72, v72, v72
	v_max_f32_e32 v72, v72, v73
	v_mov_b32_e32 v73, v72
	s_nop 1
	v_permlane32_swap_b32 v72, v73
	s_nop 1
	s_mov_b64 s[30:31], -1
	v_max3_f32 v96, v112, v72, v73
	v_sub_f32_e32 v68, v68, v96
	v_exp_f32_e32 v68, v68
	v_sub_f32_e32 v69, v69, v96
	v_exp_f32_e32 v69, v69
	v_sub_f32_e32 v70, v70, v96
	v_exp_f32_e32 v70, v70
	v_sub_f32_e32 v71, v71, v96
	v_exp_f32_e32 v71, v71
	v_sub_f32_e32 v72, v80, v96
	v_add_f32_e32 v68, 0, v68
	v_exp_f32_e32 v72, v72
	v_add_f32_e32 v68, v69, v68
	v_add_f32_e32 v68, v70, v68
	v_add_f32_e32 v68, v71, v68
	v_add_f32_e32 v72, v72, v68
	v_sub_f32_e32 v68, v81, v96
	v_exp_f32_e32 v73, v68
	v_sub_f32_e32 v68, v82, v96
	v_exp_f32_e32 v74, v68
	v_sub_f32_e32 v75, v83, v96
	v_mfma_f32_16x16x32_bf16 v[68:71], v[48:51], v[28:31], 0
	v_exp_f32_e32 v75, v75
	v_add_f32_e32 v72, v73, v72
	v_add_f32_e32 v72, v74, v72
	v_mfma_f32_16x16x32_bf16 v[76:79], v[44:47], v[32:35], v[68:71]
	v_add_f32_e32 v72, v75, v72
	v_mov_b32_e32 v73, v72
	s_nop 1
	v_permlane16_swap_b32 v72, v73
	s_nop 1
	v_mfma_f32_16x16x32_bf16 v[68:71], v[2:5], v[28:31], 0
	v_add_f32_e32 v105, v72, v73
	v_mov_b32_e32 v107, v105
	s_nop 1
	v_permlane32_swap_b32 v105, v107
	s_nop 1
	v_mfma_f32_16x16x32_bf16 v[72:75], v[6:9], v[32:35], v[68:71]
	s_cbranch_vccnz .LBB0_1818
	v_add_u32_e32 v97, s27, v94
	s_nop 2
	v_add_u32_e32 v70, 0x3f0, v97
	v_mov_b32_e32 v190, 0x25bfc
	v_cmp_lt_i32_e32 vcc, -1, v70
	v_mov_b32_e32 v69, 0xff800000
	v_mov_b32_e32 v68, 0xff800000
	ds_write_b32 v190, v68 offset:1024
	v_min_u32_e32 v68, 0x7f, v70
	v_lshl_add_u32 v68, v68, 2, s87
	v_cndmask_b32_e32 v68, v190, v68, vcc
	ds_read_b32 v68, v68 offset:1024
	v_add_u32_e32 v70, 0x3e0, v97
	v_cmp_lt_i32_e32 vcc, -1, v70
	v_min_u32_e32 v69, 0x7f, v70
	v_lshl_add_u32 v69, v69, 2, s87
	v_cndmask_b32_e32 v69, v190, v69, vcc
	ds_read_b32 v69, v69 offset:1024
	v_add_u32_e32 v80, 0x3d0, v97
	v_cmp_lt_i32_e32 vcc, -1, v80
	v_mov_b32_e32 v71, 0xff800000
	v_mov_b32_e32 v70, 0xff800000
	v_min_u32_e32 v70, 0x7f, v80
	v_lshl_add_u32 v70, v70, 2, s87
	v_cndmask_b32_e32 v70, v190, v70, vcc
	ds_read_b32 v70, v70 offset:1024
	v_add_u32_e32 v80, 0x3c0, v97
	v_cmp_lt_i32_e32 vcc, -1, v80
	v_min_u32_e32 v71, 0x7f, v80
	v_lshl_add_u32 v71, v71, 2, s87
	v_cndmask_b32_e32 v71, v190, v71, vcc
	ds_read_b32 v71, v71 offset:1024
	v_add_u32_e32 v82, 0x2f0, v97
	v_cmp_lt_i32_e32 vcc, -1, v82
	v_mov_b32_e32 v81, 0xff800000
	v_mov_b32_e32 v80, 0xff800000
	v_min_u32_e32 v80, 0x7f, v82
	v_lshl_add_u32 v80, v80, 2, s87
	v_cndmask_b32_e32 v80, v190, v80, vcc
	ds_read_b32 v80, v80 offset:1024
	v_add_u32_e32 v82, 0x2e0, v97
	v_cmp_lt_i32_e32 vcc, -1, v82
	v_min_u32_e32 v81, 0x7f, v82
	v_lshl_add_u32 v81, v81, 2, s87
	v_cndmask_b32_e32 v81, v190, v81, vcc
	ds_read_b32 v81, v81 offset:1024
	v_add_u32_e32 v103, 0x2d0, v97
	v_cmp_lt_i32_e32 vcc, -1, v103
	v_mov_b32_e32 v83, 0xff800000
	v_mov_b32_e32 v82, 0xff800000
	v_min_u32_e32 v82, 0x7f, v103
	v_lshl_add_u32 v82, v82, 2, s87
	v_cndmask_b32_e32 v82, v190, v82, vcc
	ds_read_b32 v82, v82 offset:1024
	v_add_u32_e32 v97, 0x2c0, v97
	v_cmp_lt_i32_e32 vcc, -1, v97
	v_min_u32_e32 v83, 0x7f, v97
	v_lshl_add_u32 v83, v83, 2, s87
	v_cndmask_b32_e32 v83, v190, v83, vcc
	ds_read_b32 v83, v83 offset:1024
	s_waitcnt lgkmcnt(0)
	v_add_f32_e32 v68, v76, v68
	v_mul_f32_e32 v68, 0x3fb8aa3b, v68
	v_add_f32_e32 v69, v77, v69
	v_mul_f32_e32 v69, 0x3fb8aa3b, v69
	v_add_f32_e32 v70, v78, v70
	v_mul_f32_e32 v70, 0x3fb8aa3b, v70
	v_add_f32_e32 v71, v79, v71
	v_mul_f32_e32 v71, 0x3fb8aa3b, v71
	v_add_f32_e32 v80, v72, v80
	v_mul_f32_e32 v80, 0x3fb8aa3b, v80
	v_add_f32_e32 v81, v73, v81
	v_mul_f32_e32 v81, 0x3fb8aa3b, v81
	v_add_f32_e32 v82, v74, v82
	v_mul_f32_e32 v82, 0x3fb8aa3b, v82
	v_add_f32_e32 v83, v75, v83
	v_mul_f32_e32 v83, 0x3fb8aa3b, v83
	s_mov_b64 s[30:31], 0

.LBB0_1820:
	s_nop 4
	v_max_f32_e32 v72, v69, v69
	v_max_f32_e32 v73, v68, v68
	v_max_f32_e32 v72, v73, v72
	v_max_f32_e32 v73, v71, v71
	v_max_f32_e32 v74, v70, v70
	v_max_f32_e32 v73, v74, v73
	v_max_f32_e32 v74, v83, v83
	v_max_f32_e32 v75, v82, v82
	v_max_f32_e32 v74, v75, v74
	v_max3_f32 v74, v80, v81, v74
	v_max3_f32 v72, v72, v73, v74
	v_mov_b32_e32 v73, v72
	s_nop 1
	v_permlane16_swap_b32 v72, v73
	s_nop 1
	v_mfma_f32_16x16x32_bf16 v[48:51], v[48:51], v[36:39], 0
	v_max_f32_e32 v73, v73, v73
	v_max_f32_e32 v72, v72, v72
	v_max_f32_e32 v72, v72, v73
	v_mov_b32_e32 v73, v72
	s_nop 1
	v_permlane32_swap_b32 v72, v73
	s_nop 1
	v_mfma_f32_16x16x32_bf16 v[2:5], v[2:5], v[36:39], 0
	v_max3_f32 v97, v113, v72, v73
	v_sub_f32_e32 v68, v68, v97
	v_exp_f32_e32 v68, v68
	v_sub_f32_e32 v69, v69, v97
	v_exp_f32_e32 v69, v69
	v_sub_f32_e32 v70, v70, v97
	v_exp_f32_e32 v70, v70
	v_sub_f32_e32 v71, v71, v97
	v_exp_f32_e32 v71, v71
	v_add_f32_e32 v68, 0, v68
	v_sub_f32_e32 v72, v80, v97
	v_exp_f32_e32 v72, v72
	v_add_f32_e32 v68, v69, v68
	v_sub_f32_e32 v69, v81, v97
	v_add_f32_e32 v68, v70, v68
	v_exp_f32_e32 v69, v69
	v_sub_f32_e32 v70, v82, v97
	v_add_f32_e32 v68, v71, v68
	v_exp_f32_e32 v70, v70
	v_sub_f32_e32 v71, v83, v97
	v_exp_f32_e32 v71, v71
	v_add_f32_e32 v68, v72, v68
	v_add_f32_e32 v68, v69, v68
	v_add_f32_e32 v68, v70, v68
	v_mfma_f32_16x16x32_bf16 v[44:47], v[44:47], v[40:43], v[48:51]
	s_and_b64 vcc, exec, s[12:13]
	s_mov_b64 s[12:13], -1
	s_nop 0
	v_add_f32_e32 v48, v71, v68
	v_mfma_f32_16x16x32_bf16 v[6:9], v[6:9], v[40:43], v[2:5]
	v_mov_b32_e32 v49, v48
	s_nop 1
	v_permlane16_swap_b32 v48, v49
	s_nop 1
	s_nop 0
	v_add_f32_e32 v68, v48, v49
	v_mov_b32_e32 v69, v68
	s_nop 1
	v_permlane32_swap_b32 v68, v69
	s_nop 1
	s_cbranch_vccnz .LBB0_1838
	v_add_u32_e32 v70, s27, v94
	v_add_u32_e32 v4, 0x3f0, v70
	v_mov_b32_e32 v190, 0x259fc
	v_cmp_lt_i32_e32 vcc, -1, v4
	v_mov_b32_e32 v3, 0xff800000
	v_mov_b32_e32 v2, 0xff800000
	ds_write_b32 v190, v2 offset:1536
	v_min_u32_e32 v2, 0x7f, v4
	v_lshl_add_u32 v2, v2, 2, s87
	v_cndmask_b32_e32 v2, v190, v2, vcc
	ds_read_b32 v2, v2 offset:1536
	v_add_u32_e32 v4, 0x3e0, v70
	v_cmp_lt_i32_e32 vcc, -1, v4
	v_min_u32_e32 v3, 0x7f, v4
	v_lshl_add_u32 v3, v3, 2, s87
	v_cndmask_b32_e32 v3, v190, v3, vcc
	ds_read_b32 v3, v3 offset:1536
	v_add_u32_e32 v48, 0x3d0, v70
	v_cmp_lt_i32_e32 vcc, -1, v48
	v_mov_b32_e32 v5, 0xff800000
	v_mov_b32_e32 v4, 0xff800000
	v_min_u32_e32 v4, 0x7f, v48
	v_lshl_add_u32 v4, v4, 2, s87
	v_cndmask_b32_e32 v4, v190, v4, vcc
	ds_read_b32 v4, v4 offset:1536
	v_add_u32_e32 v48, 0x3c0, v70
	v_cmp_lt_i32_e32 vcc, -1, v48
	v_min_u32_e32 v5, 0x7f, v48
	v_lshl_add_u32 v5, v5, 2, s87
	v_cndmask_b32_e32 v5, v190, v5, vcc
	ds_read_b32 v5, v5 offset:1536
	v_add_u32_e32 v50, 0x2f0, v70
	v_cmp_lt_i32_e32 vcc, -1, v50
	v_mov_b32_e32 v49, 0xff800000
	v_mov_b32_e32 v48, 0xff800000
	v_min_u32_e32 v48, 0x7f, v50
	v_lshl_add_u32 v48, v48, 2, s87
	v_cndmask_b32_e32 v48, v190, v48, vcc
	ds_read_b32 v48, v48 offset:1536
	v_add_u32_e32 v50, 0x2e0, v70
	v_cmp_lt_i32_e32 vcc, -1, v50
	v_min_u32_e32 v49, 0x7f, v50
	v_lshl_add_u32 v49, v49, 2, s87
	v_cndmask_b32_e32 v49, v190, v49, vcc
	ds_read_b32 v49, v49 offset:1536
	v_add_u32_e32 v71, 0x2d0, v70
	v_cmp_lt_i32_e32 vcc, -1, v71
	v_mov_b32_e32 v51, 0xff800000
	v_mov_b32_e32 v50, 0xff800000
	v_min_u32_e32 v50, 0x7f, v71
	v_lshl_add_u32 v50, v50, 2, s87
	v_cndmask_b32_e32 v50, v190, v50, vcc
	ds_read_b32 v50, v50 offset:1536
	v_add_u32_e32 v70, 0x2c0, v70
	v_cmp_lt_i32_e32 vcc, -1, v70
	v_min_u32_e32 v51, 0x7f, v70
	v_lshl_add_u32 v51, v51, 2, s87
	v_cndmask_b32_e32 v51, v190, v51, vcc
	ds_read_b32 v51, v51 offset:1536
	s_waitcnt lgkmcnt(0)
	v_add_f32_e32 v2, v44, v2
	v_mul_f32_e32 v2, 0x3fb8aa3b, v2
	v_add_f32_e32 v3, v45, v3
	v_mul_f32_e32 v3, 0x3fb8aa3b, v3
	v_add_f32_e32 v4, v46, v4
	v_mul_f32_e32 v4, 0x3fb8aa3b, v4
	v_add_f32_e32 v5, v47, v5
	v_mul_f32_e32 v5, 0x3fb8aa3b, v5
	v_add_f32_e32 v48, v6, v48
	v_mul_f32_e32 v48, 0x3fb8aa3b, v48
	v_add_f32_e32 v49, v7, v49
	v_mul_f32_e32 v49, 0x3fb8aa3b, v49
	v_add_f32_e32 v50, v8, v50
	v_mul_f32_e32 v50, 0x3fb8aa3b, v50
	v_add_f32_e32 v51, v9, v51
	v_mul_f32_e32 v51, 0x3fb8aa3b, v51
	s_mov_b64 s[12:13], 0

.LBB0_1840:
	s_nop 0
	v_sub_f32_e32 v6, v113, v97
	v_exp_f32_e32 v6, v6
	v_add_f32_e32 v103, v68, v69
	v_sub_f32_e32 v7, v112, v96
	v_exp_f32_e32 v7, v7
	v_fmac_f32_e32 v103, v100, v6
	v_sub_f32_e32 v6, v111, v95
	v_exp_f32_e32 v6, v6
	v_add_f32_e32 v105, v105, v107
	v_add_f32_e32 v106, v104, v106
	v_fmac_f32_e32 v105, v102, v7
	v_fmac_f32_e32 v106, v99, v6
	v_max_f32_e32 v6, v3, v3
	v_max_f32_e32 v7, v2, v2
	v_max_f32_e32 v6, v7, v6
	v_max_f32_e32 v7, v5, v5
	v_max_f32_e32 v8, v4, v4
	v_max_f32_e32 v7, v8, v7
	v_max_f32_e32 v8, v51, v51
	v_max_f32_e32 v9, v50, v50
	v_max_f32_e32 v8, v9, v8
	v_max3_f32 v8, v48, v49, v8
	v_max3_f32 v6, v6, v7, v8
	v_mov_b32_e32 v7, v6
	s_nop 1
	v_permlane16_swap_b32 v6, v7
	s_nop 1
	s_cmp_ge_u32 s40, s25
	v_max_f32_e32 v7, v7, v7
	v_max_f32_e32 v6, v6, v6
	v_max_f32_e32 v6, v6, v7
	v_mov_b32_e32 v7, v6
	s_nop 1
	v_permlane32_swap_b32 v6, v7
	s_nop 1
	s_mov_b64 s[12:13], -1
	v_max3_f32 v114, v98, v6, v7
	v_sub_f32_e32 v2, v2, v114
	v_exp_f32_e32 v2, v2
	v_sub_f32_e32 v3, v3, v114
	v_exp_f32_e32 v3, v3
	v_sub_f32_e32 v4, v4, v114
	v_exp_f32_e32 v4, v4
	v_sub_f32_e32 v5, v5, v114
	v_exp_f32_e32 v5, v5
	v_add_f32_e32 v2, 0, v2
	v_add_f32_e32 v2, v3, v2
	v_sub_f32_e32 v3, v48, v114
	v_add_f32_e32 v2, v4, v2
	v_exp_f32_e32 v3, v3
	v_sub_f32_e32 v4, v49, v114
	v_add_f32_e32 v2, v5, v2
	v_exp_f32_e32 v4, v4
	v_sub_f32_e32 v5, v50, v114
	v_exp_f32_e32 v5, v5
	v_sub_f32_e32 v6, v51, v114
	v_exp_f32_e32 v6, v6
	v_add_f32_e32 v2, v3, v2
	v_add_f32_e32 v2, v4, v2
	v_add_f32_e32 v2, v5, v2
	v_add_f32_e32 v2, v6, v2
	v_mov_b32_e32 v3, v2
	s_nop 1
	v_permlane16_swap_b32 v2, v3
	s_nop 1
	s_nop 0
	v_add_f32_e32 v2, v2, v3
	v_sub_f32_e32 v3, v98, v114
	v_exp_f32_e32 v3, v3
	v_mov_b32_e32 v4, v2
	s_nop 1
	v_permlane32_swap_b32 v2, v4
	s_nop 1
	s_nop 0
	v_add_f32_e32 v104, v2, v4
	v_fmac_f32_e32 v104, v101, v3
	s_cbranch_scc1 .LBB0_1921
	s_add_i32 s23, s23, 2
	s_waitcnt vmcnt(3)
	v_mfma_f32_16x16x32_bf16 v[2:5], v[64:67], v[12:15], 0
	s_min_i32 s48, s23, s21
	s_lshl_b64 s[4:5], s[48:49], 12
	v_lshl_add_u64 v[6:7], v[84:85], 0, s[4:5]
	global_load_dwordx4 v[48:51], v[6:7], off
	global_load_dwordx4 v[44:47], v[6:7], off offset:1024
	s_waitcnt vmcnt(4)
	v_mfma_f32_16x16x32_bf16 v[76:79], v[60:63], v[16:19], v[2:5]
	s_nop 2
	global_load_dwordx4 v[2:5], v[6:7], off offset:2048
	s_nop 0
	global_load_dwordx4 v[6:9], v[6:7], off offset:3072
	s_cmpk_lt_i32 s27, 0x7f
	v_add_u32_e32 v98, s27, v94
	s_waitcnt vmcnt(5)
	v_mfma_f32_16x16x32_bf16 v[68:71], v[56:59], v[12:15], 0
	s_cselect_b64 s[30:31], -1, 0
	s_cmpk_gt_i32 s27, 0x7e
	v_add_u32_e32 v99, 0x1f0, v98
	s_waitcnt vmcnt(4)
	v_mfma_f32_16x16x32_bf16 v[72:75], v[52:55], v[16:19], v[68:71]
	s_cbranch_scc1 .LBB0_1859
	v_mov_b32_e32 v190, 0x25ffc
	v_cmp_lt_i32_e32 vcc, -1, v99
	s_nop 0
	v_mov_b32_e32 v69, 0xff800000
	v_mov_b32_e32 v68, 0xff800000
	ds_write_b32 v190, v68
	v_min_u32_e32 v68, 0x7f, v99
	v_lshl_add_u32 v68, v68, 2, s87
	v_cndmask_b32_e32 v68, v190, v68, vcc
	ds_read_b32 v68, v68
	v_add_u32_e32 v70, 0x1e0, v98
	v_cmp_lt_i32_e32 vcc, -1, v70
	v_min_u32_e32 v69, 0x7f, v70
	v_lshl_add_u32 v69, v69, 2, s87
	v_cndmask_b32_e32 v69, v190, v69, vcc
	ds_read_b32 v69, v69
	v_add_u32_e32 v80, 0x1d0, v98
	v_cmp_lt_i32_e32 vcc, -1, v80
	v_mov_b32_e32 v71, 0xff800000
	v_mov_b32_e32 v70, 0xff800000
	v_min_u32_e32 v70, 0x7f, v80
	v_lshl_add_u32 v70, v70, 2, s87
	v_cndmask_b32_e32 v70, v190, v70, vcc
	ds_read_b32 v70, v70
	v_add_u32_e32 v80, 0x1c0, v98
	v_cmp_lt_i32_e32 vcc, -1, v80
	v_min_u32_e32 v71, 0x7f, v80
	v_lshl_add_u32 v71, v71, 2, s87
	v_cndmask_b32_e32 v71, v190, v71, vcc
	ds_read_b32 v71, v71
	v_add_u32_e32 v82, 0xf0, v98
	v_cmp_lt_i32_e32 vcc, -1, v82
	v_mov_b32_e32 v81, 0xff800000
	v_mov_b32_e32 v80, 0xff800000
	v_min_u32_e32 v80, 0x7f, v82
	v_lshl_add_u32 v80, v80, 2, s87
	v_cndmask_b32_e32 v80, v190, v80, vcc
	ds_read_b32 v80, v80
	v_add_u32_e32 v82, 0xe0, v98
	v_cmp_lt_i32_e32 vcc, -1, v82
	v_min_u32_e32 v81, 0x7f, v82
	v_lshl_add_u32 v81, v81, 2, s87
	v_cndmask_b32_e32 v81, v190, v81, vcc
	ds_read_b32 v81, v81
	v_add_u32_e32 v100, 0xd0, v98
	v_cmp_lt_i32_e32 vcc, -1, v100
	v_mov_b32_e32 v83, 0xff800000
	v_mov_b32_e32 v82, 0xff800000
	v_min_u32_e32 v82, 0x7f, v100
	v_lshl_add_u32 v82, v82, 2, s87
	v_cndmask_b32_e32 v82, v190, v82, vcc
	ds_read_b32 v82, v82
	v_add_u32_e32 v100, 0xc0, v98
	v_cmp_lt_i32_e32 vcc, -1, v100
	v_min_u32_e32 v83, 0x7f, v100
	v_lshl_add_u32 v83, v83, 2, s87
	v_cndmask_b32_e32 v83, v190, v83, vcc
	ds_read_b32 v83, v83
	s_waitcnt lgkmcnt(0)
	v_add_f32_e32 v68, v76, v68
	v_mul_f32_e32 v68, 0x3fb8aa3b, v68
	v_add_f32_e32 v69, v77, v69
	v_mul_f32_e32 v69, 0x3fb8aa3b, v69
	v_add_f32_e32 v70, v78, v70
	v_mul_f32_e32 v70, 0x3fb8aa3b, v70
	v_add_f32_e32 v71, v79, v71
	v_mul_f32_e32 v71, 0x3fb8aa3b, v71
	v_add_f32_e32 v80, v72, v80
	v_mul_f32_e32 v80, 0x3fb8aa3b, v80
	v_add_f32_e32 v81, v73, v81
	v_mul_f32_e32 v81, 0x3fb8aa3b, v81
	v_add_f32_e32 v82, v74, v82
	v_mul_f32_e32 v82, 0x3fb8aa3b, v82
	v_add_f32_e32 v83, v75, v83
	v_mul_f32_e32 v83, 0x3fb8aa3b, v83
	s_mov_b64 s[12:13], 0

.LBB0_1861:
	s_nop 4
	v_max_f32_e32 v72, v69, v69
	v_max_f32_e32 v73, v68, v68
	v_max_f32_e32 v72, v73, v72
	v_max_f32_e32 v73, v71, v71
	v_max_f32_e32 v74, v70, v70
	v_max_f32_e32 v73, v74, v73
	v_max_f32_e32 v74, v83, v83
	v_max_f32_e32 v75, v82, v82
	v_max_f32_e32 v74, v75, v74
	v_max3_f32 v74, v80, v81, v74
	v_max3_f32 v72, v72, v73, v74
	v_mov_b32_e32 v73, v72
	s_nop 1
	v_permlane16_swap_b32 v72, v73
	s_nop 1
	s_andn2_b64 vcc, exec, s[30:31]
	v_max_f32_e32 v73, v73, v73
	v_max_f32_e32 v72, v72, v72
	v_max_f32_e32 v72, v72, v73
	v_mov_b32_e32 v73, v72
	s_nop 1
	v_permlane32_swap_b32 v72, v73
	s_nop 1
	s_nop 0
	v_max3_f32 v111, v95, v72, v73
	v_sub_f32_e32 v68, v68, v111
	v_exp_f32_e32 v68, v68
	v_sub_f32_e32 v69, v69, v111
	v_exp_f32_e32 v69, v69
	v_sub_f32_e32 v70, v70, v111
	v_exp_f32_e32 v70, v70
	v_sub_f32_e32 v71, v71, v111
	v_exp_f32_e32 v71, v71
	v_sub_f32_e32 v72, v80, v111
	v_add_f32_e32 v68, 0, v68
	v_exp_f32_e32 v72, v72
	v_add_f32_e32 v68, v69, v68
	v_add_f32_e32 v68, v70, v68
	v_add_f32_e32 v68, v71, v68
	v_add_f32_e32 v72, v72, v68
	v_sub_f32_e32 v68, v81, v111
	v_exp_f32_e32 v73, v68
	v_sub_f32_e32 v68, v82, v111
	v_exp_f32_e32 v74, v68
	v_sub_f32_e32 v75, v83, v111
	v_mfma_f32_16x16x32_bf16 v[68:71], v[64:67], v[20:23], 0
	v_exp_f32_e32 v75, v75
	v_add_f32_e32 v72, v73, v72
	v_add_f32_e32 v72, v74, v72
	v_mfma_f32_16x16x32_bf16 v[76:79], v[60:63], v[24:27], v[68:71]
	v_add_f32_e32 v72, v75, v72
	v_mov_b32_e32 v73, v72
	s_nop 1
	v_permlane16_swap_b32 v72, v73
	s_nop 1
	v_mfma_f32_16x16x32_bf16 v[68:71], v[56:59], v[20:23], 0
	v_add_f32_e32 v101, v72, v73
	v_mov_b32_e32 v107, v101
	s_nop 1
	v_permlane32_swap_b32 v101, v107
	s_nop 1
	v_mfma_f32_16x16x32_bf16 v[72:75], v[52:55], v[24:27], v[68:71]
	s_nop 4
	v_cndmask_b32_e64 v68, 0, 1, s[30:31]
	v_cmp_ne_u32_e64 s[12:13], 1, v68
	s_mov_b64 s[30:31], -1
	s_cbranch_vccnz .LBB0_1879
	v_mov_b32_e32 v190, 0x25dfc
	v_cmp_lt_i32_e32 vcc, -1, v99
	v_mov_b32_e32 v69, 0xff800000
	v_mov_b32_e32 v68, 0xff800000
	ds_write_b32 v190, v68 offset:512
	v_min_u32_e32 v68, 0x7f, v99
	v_lshl_add_u32 v68, v68, 2, s87
	v_cndmask_b32_e32 v68, v190, v68, vcc
	ds_read_b32 v68, v68 offset:512
	v_add_u32_e32 v70, 0x1e0, v98
	v_cmp_lt_i32_e32 vcc, -1, v70
	v_min_u32_e32 v69, 0x7f, v70
	v_lshl_add_u32 v69, v69, 2, s87
	v_cndmask_b32_e32 v69, v190, v69, vcc
	ds_read_b32 v69, v69 offset:512
	v_add_u32_e32 v80, 0x1d0, v98
	v_cmp_lt_i32_e32 vcc, -1, v80
	v_mov_b32_e32 v71, 0xff800000
	v_mov_b32_e32 v70, 0xff800000
	v_min_u32_e32 v70, 0x7f, v80
	v_lshl_add_u32 v70, v70, 2, s87
	v_cndmask_b32_e32 v70, v190, v70, vcc
	ds_read_b32 v70, v70 offset:512
	v_add_u32_e32 v80, 0x1c0, v98
	v_cmp_lt_i32_e32 vcc, -1, v80
	v_min_u32_e32 v71, 0x7f, v80
	v_lshl_add_u32 v71, v71, 2, s87
	v_cndmask_b32_e32 v71, v190, v71, vcc
	ds_read_b32 v71, v71 offset:512
	v_add_u32_e32 v82, 0xf0, v98
	v_cmp_lt_i32_e32 vcc, -1, v82
	v_mov_b32_e32 v81, 0xff800000
	v_mov_b32_e32 v80, 0xff800000
	v_min_u32_e32 v80, 0x7f, v82
	v_lshl_add_u32 v80, v80, 2, s87
	v_cndmask_b32_e32 v80, v190, v80, vcc
	ds_read_b32 v80, v80 offset:512
	v_add_u32_e32 v82, 0xe0, v98
	v_cmp_lt_i32_e32 vcc, -1, v82
	v_min_u32_e32 v81, 0x7f, v82
	v_lshl_add_u32 v81, v81, 2, s87
	v_cndmask_b32_e32 v81, v190, v81, vcc
	ds_read_b32 v81, v81 offset:512
	v_add_u32_e32 v100, 0xd0, v98
	v_cmp_lt_i32_e32 vcc, -1, v100
	v_mov_b32_e32 v83, 0xff800000
	v_mov_b32_e32 v82, 0xff800000
	v_min_u32_e32 v82, 0x7f, v100
	v_lshl_add_u32 v82, v82, 2, s87
	v_cndmask_b32_e32 v82, v190, v82, vcc
	ds_read_b32 v82, v82 offset:512
	v_add_u32_e32 v100, 0xc0, v98
	v_cmp_lt_i32_e32 vcc, -1, v100
	v_min_u32_e32 v83, 0x7f, v100
	v_lshl_add_u32 v83, v83, 2, s87
	v_cndmask_b32_e32 v83, v190, v83, vcc
	ds_read_b32 v83, v83 offset:512
	s_waitcnt lgkmcnt(0)
	v_add_f32_e32 v68, v76, v68
	v_mul_f32_e32 v68, 0x3fb8aa3b, v68
	v_add_f32_e32 v69, v77, v69
	v_mul_f32_e32 v69, 0x3fb8aa3b, v69
	v_add_f32_e32 v70, v78, v70
	v_mul_f32_e32 v70, 0x3fb8aa3b, v70
	v_add_f32_e32 v71, v79, v71
	v_mul_f32_e32 v71, 0x3fb8aa3b, v71
	v_add_f32_e32 v80, v72, v80
	v_mul_f32_e32 v80, 0x3fb8aa3b, v80
	v_add_f32_e32 v81, v73, v81
	v_mul_f32_e32 v81, 0x3fb8aa3b, v81
	v_add_f32_e32 v82, v74, v82
	v_mul_f32_e32 v82, 0x3fb8aa3b, v82
	v_add_f32_e32 v83, v75, v83
	v_mul_f32_e32 v83, 0x3fb8aa3b, v83
	s_mov_b64 s[30:31], 0

.LBB0_1881:
	v_max_f32_e32 v72, v69, v69
	v_max_f32_e32 v73, v68, v68
	v_max_f32_e32 v72, v73, v72
	v_max_f32_e32 v73, v71, v71
	v_max_f32_e32 v74, v70, v70
	v_max_f32_e32 v73, v74, v73
	v_max_f32_e32 v74, v83, v83
	v_max_f32_e32 v75, v82, v82
	v_max_f32_e32 v74, v75, v74
	v_max3_f32 v74, v80, v81, v74
	v_max3_f32 v72, v72, v73, v74
	v_mov_b32_e32 v73, v72
	s_nop 1
	v_permlane16_swap_b32 v72, v73
	s_nop 1
	s_and_b64 vcc, exec, s[12:13]
	v_max_f32_e32 v73, v73, v73
	v_max_f32_e32 v72, v72, v72
	v_max_f32_e32 v72, v72, v73
	v_mov_b32_e32 v73, v72
	s_nop 1
	v_permlane32_swap_b32 v72, v73
	s_nop 1
	s_mov_b64 s[30:31], -1
	v_max3_f32 v112, v96, v72, v73
	v_sub_f32_e32 v68, v68, v112
	v_exp_f32_e32 v68, v68
	v_sub_f32_e32 v69, v69, v112
	v_exp_f32_e32 v69, v69
	v_sub_f32_e32 v70, v70, v112
	v_exp_f32_e32 v70, v70
	v_sub_f32_e32 v71, v71, v112
	v_exp_f32_e32 v71, v71
	v_sub_f32_e32 v72, v80, v112
	v_add_f32_e32 v68, 0, v68
	v_exp_f32_e32 v72, v72
	v_add_f32_e32 v68, v69, v68
	v_add_f32_e32 v68, v70, v68
	v_add_f32_e32 v68, v71, v68
	v_add_f32_e32 v72, v72, v68
	v_sub_f32_e32 v68, v81, v112
	v_exp_f32_e32 v73, v68
	v_sub_f32_e32 v68, v82, v112
	v_exp_f32_e32 v74, v68
	v_sub_f32_e32 v75, v83, v112
	v_mfma_f32_16x16x32_bf16 v[68:71], v[64:67], v[28:31], 0
	v_exp_f32_e32 v75, v75
	v_add_f32_e32 v72, v73, v72
	v_add_f32_e32 v72, v74, v72
	v_mfma_f32_16x16x32_bf16 v[76:79], v[60:63], v[32:35], v[68:71]
	v_add_f32_e32 v72, v75, v72
	v_mov_b32_e32 v73, v72
	s_nop 1
	v_permlane16_swap_b32 v72, v73
	s_nop 1
	v_mfma_f32_16x16x32_bf16 v[68:71], v[56:59], v[28:31], 0
	v_add_f32_e32 v102, v72, v73
	v_mov_b32_e32 v115, v102
	s_nop 1
	v_permlane32_swap_b32 v102, v115
	s_nop 1
	v_mfma_f32_16x16x32_bf16 v[72:75], v[52:55], v[32:35], v[68:71]
	s_cbranch_vccnz .LBB0_1899
	v_mov_b32_e32 v190, 0x25bfc
	v_cmp_lt_i32_e32 vcc, -1, v99
	s_nop 2
	v_mov_b32_e32 v69, 0xff800000
	v_mov_b32_e32 v68, 0xff800000
	ds_write_b32 v190, v68 offset:1024
	v_min_u32_e32 v68, 0x7f, v99
	v_lshl_add_u32 v68, v68, 2, s87
	v_cndmask_b32_e32 v68, v190, v68, vcc
	ds_read_b32 v68, v68 offset:1024
	v_add_u32_e32 v70, 0x1e0, v98
	v_cmp_lt_i32_e32 vcc, -1, v70
	v_min_u32_e32 v69, 0x7f, v70
	v_lshl_add_u32 v69, v69, 2, s87
	v_cndmask_b32_e32 v69, v190, v69, vcc
	ds_read_b32 v69, v69 offset:1024
	v_add_u32_e32 v80, 0x1d0, v98
	v_cmp_lt_i32_e32 vcc, -1, v80
	v_mov_b32_e32 v71, 0xff800000
	v_mov_b32_e32 v70, 0xff800000
	v_min_u32_e32 v70, 0x7f, v80
	v_lshl_add_u32 v70, v70, 2, s87
	v_cndmask_b32_e32 v70, v190, v70, vcc
	ds_read_b32 v70, v70 offset:1024
	v_add_u32_e32 v80, 0x1c0, v98
	v_cmp_lt_i32_e32 vcc, -1, v80
	v_min_u32_e32 v71, 0x7f, v80
	v_lshl_add_u32 v71, v71, 2, s87
	v_cndmask_b32_e32 v71, v190, v71, vcc
	ds_read_b32 v71, v71 offset:1024
	v_add_u32_e32 v82, 0xf0, v98
	v_cmp_lt_i32_e32 vcc, -1, v82
	v_mov_b32_e32 v81, 0xff800000
	v_mov_b32_e32 v80, 0xff800000
	v_min_u32_e32 v80, 0x7f, v82
	v_lshl_add_u32 v80, v80, 2, s87
	v_cndmask_b32_e32 v80, v190, v80, vcc
	ds_read_b32 v80, v80 offset:1024
	v_add_u32_e32 v82, 0xe0, v98
	v_cmp_lt_i32_e32 vcc, -1, v82
	v_min_u32_e32 v81, 0x7f, v82
	v_lshl_add_u32 v81, v81, 2, s87
	v_cndmask_b32_e32 v81, v190, v81, vcc
	ds_read_b32 v81, v81 offset:1024
	v_add_u32_e32 v100, 0xd0, v98
	v_cmp_lt_i32_e32 vcc, -1, v100
	v_mov_b32_e32 v83, 0xff800000
	v_mov_b32_e32 v82, 0xff800000
	v_min_u32_e32 v82, 0x7f, v100
	v_lshl_add_u32 v82, v82, 2, s87
	v_cndmask_b32_e32 v82, v190, v82, vcc
	ds_read_b32 v82, v82 offset:1024
	v_add_u32_e32 v100, 0xc0, v98
	v_cmp_lt_i32_e32 vcc, -1, v100
	v_min_u32_e32 v83, 0x7f, v100
	v_lshl_add_u32 v83, v83, 2, s87
	v_cndmask_b32_e32 v83, v190, v83, vcc
	ds_read_b32 v83, v83 offset:1024
	s_waitcnt lgkmcnt(0)
	v_add_f32_e32 v68, v76, v68
	v_mul_f32_e32 v68, 0x3fb8aa3b, v68
	v_add_f32_e32 v69, v77, v69
	v_mul_f32_e32 v69, 0x3fb8aa3b, v69
	v_add_f32_e32 v70, v78, v70
	v_mul_f32_e32 v70, 0x3fb8aa3b, v70
	v_add_f32_e32 v71, v79, v71
	v_mul_f32_e32 v71, 0x3fb8aa3b, v71
	v_add_f32_e32 v80, v72, v80
	v_mul_f32_e32 v80, 0x3fb8aa3b, v80
	v_add_f32_e32 v81, v73, v81
	v_mul_f32_e32 v81, 0x3fb8aa3b, v81
	v_add_f32_e32 v82, v74, v82
	v_mul_f32_e32 v82, 0x3fb8aa3b, v82
	v_add_f32_e32 v83, v75, v83
	v_mul_f32_e32 v83, 0x3fb8aa3b, v83
	s_mov_b64 s[30:31], 0

.LBB0_1901:
	s_nop 4
	v_max_f32_e32 v72, v69, v69
	v_max_f32_e32 v73, v68, v68
	v_max_f32_e32 v72, v73, v72
	v_max_f32_e32 v73, v71, v71
	v_max_f32_e32 v74, v70, v70
	v_max_f32_e32 v73, v74, v73
	v_max_f32_e32 v74, v83, v83
	v_max_f32_e32 v75, v82, v82
	v_max_f32_e32 v74, v75, v74
	v_max3_f32 v74, v80, v81, v74
	v_max3_f32 v72, v72, v73, v74
	v_mov_b32_e32 v73, v72
	s_nop 1
	v_permlane16_swap_b32 v72, v73
	s_nop 1
	v_mfma_f32_16x16x32_bf16 v[64:67], v[64:67], v[36:39], 0
	v_max_f32_e32 v73, v73, v73
	v_max_f32_e32 v72, v72, v72
	v_max_f32_e32 v72, v72, v73
	v_mov_b32_e32 v73, v72
	s_nop 1
	v_permlane32_swap_b32 v72, v73
	s_nop 1
	v_mfma_f32_16x16x32_bf16 v[56:59], v[56:59], v[36:39], 0
	v_max3_f32 v113, v97, v72, v73
	v_sub_f32_e32 v68, v68, v113
	v_exp_f32_e32 v68, v68
	v_sub_f32_e32 v69, v69, v113
	v_exp_f32_e32 v69, v69
	v_sub_f32_e32 v70, v70, v113
	v_exp_f32_e32 v70, v70
	v_sub_f32_e32 v71, v71, v113
	v_exp_f32_e32 v71, v71
	v_add_f32_e32 v68, 0, v68
	v_sub_f32_e32 v72, v80, v113
	v_exp_f32_e32 v72, v72
	v_add_f32_e32 v68, v69, v68
	v_sub_f32_e32 v69, v81, v113
	v_add_f32_e32 v68, v70, v68
	v_exp_f32_e32 v69, v69
	v_sub_f32_e32 v70, v82, v113
	v_add_f32_e32 v68, v71, v68
	v_exp_f32_e32 v70, v70
	v_sub_f32_e32 v71, v83, v113
	v_exp_f32_e32 v71, v71
	v_add_f32_e32 v68, v72, v68
	v_add_f32_e32 v68, v69, v68
	v_add_f32_e32 v68, v70, v68
	v_mfma_f32_16x16x32_bf16 v[60:63], v[60:63], v[40:43], v[64:67]
	s_and_b64 vcc, exec, s[12:13]
	s_mov_b64 s[12:13], -1
	s_nop 0
	v_add_f32_e32 v64, v71, v68
	v_mfma_f32_16x16x32_bf16 v[56:59], v[52:55], v[40:43], v[56:59]
	v_mov_b32_e32 v65, v64
	s_nop 1
	v_permlane16_swap_b32 v64, v65
	s_nop 1
	s_nop 0
	v_add_f32_e32 v68, v64, v65
	v_mov_b32_e32 v69, v68
	s_nop 1
	v_permlane32_swap_b32 v68, v69
	s_nop 1
	s_cbranch_vccnz .LBB0_1919
	v_mov_b32_e32 v190, 0x259fc
	v_cmp_lt_i32_e32 vcc, -1, v99
	v_mov_b32_e32 v53, 0xff800000
	v_mov_b32_e32 v52, 0xff800000
	ds_write_b32 v190, v52 offset:1536
	v_min_u32_e32 v52, 0x7f, v99
	v_lshl_add_u32 v52, v52, 2, s87
	v_cndmask_b32_e32 v52, v190, v52, vcc
	ds_read_b32 v52, v52 offset:1536
	v_add_u32_e32 v54, 0x1e0, v98
	v_cmp_lt_i32_e32 vcc, -1, v54
	v_min_u32_e32 v53, 0x7f, v54
	v_lshl_add_u32 v53, v53, 2, s87
	v_cndmask_b32_e32 v53, v190, v53, vcc
	ds_read_b32 v53, v53 offset:1536
	v_add_u32_e32 v64, 0x1d0, v98
	v_cmp_lt_i32_e32 vcc, -1, v64
	v_mov_b32_e32 v55, 0xff800000
	v_mov_b32_e32 v54, 0xff800000
	v_min_u32_e32 v54, 0x7f, v64
	v_lshl_add_u32 v54, v54, 2, s87
	v_cndmask_b32_e32 v54, v190, v54, vcc
	ds_read_b32 v54, v54 offset:1536
	v_add_u32_e32 v64, 0x1c0, v98
	v_cmp_lt_i32_e32 vcc, -1, v64
	v_min_u32_e32 v55, 0x7f, v64
	v_lshl_add_u32 v55, v55, 2, s87
	v_cndmask_b32_e32 v55, v190, v55, vcc
	ds_read_b32 v55, v55 offset:1536
	v_add_u32_e32 v66, 0xf0, v98
	v_cmp_lt_i32_e32 vcc, -1, v66
	v_mov_b32_e32 v65, 0xff800000
	v_mov_b32_e32 v64, 0xff800000
	v_min_u32_e32 v64, 0x7f, v66
	v_lshl_add_u32 v64, v64, 2, s87
	v_cndmask_b32_e32 v64, v190, v64, vcc
	ds_read_b32 v64, v64 offset:1536
	v_add_u32_e32 v66, 0xe0, v98
	v_cmp_lt_i32_e32 vcc, -1, v66
	v_min_u32_e32 v65, 0x7f, v66
	v_lshl_add_u32 v65, v65, 2, s87
	v_cndmask_b32_e32 v65, v190, v65, vcc
	ds_read_b32 v65, v65 offset:1536
	v_add_u32_e32 v70, 0xd0, v98
	v_cmp_lt_i32_e32 vcc, -1, v70
	v_mov_b32_e32 v67, 0xff800000
	v_mov_b32_e32 v66, 0xff800000
	v_min_u32_e32 v66, 0x7f, v70
	v_lshl_add_u32 v66, v66, 2, s87
	v_cndmask_b32_e32 v66, v190, v66, vcc
	ds_read_b32 v66, v66 offset:1536
	v_add_u32_e32 v70, 0xc0, v98
	v_cmp_lt_i32_e32 vcc, -1, v70
	v_min_u32_e32 v67, 0x7f, v70
	v_lshl_add_u32 v67, v67, 2, s87
	v_cndmask_b32_e32 v67, v190, v67, vcc
	ds_read_b32 v67, v67 offset:1536
	s_waitcnt lgkmcnt(0)
	v_add_f32_e32 v52, v60, v52
	v_mul_f32_e32 v52, 0x3fb8aa3b, v52
	v_add_f32_e32 v53, v61, v53
	v_mul_f32_e32 v53, 0x3fb8aa3b, v53
	v_add_f32_e32 v54, v62, v54
	v_mul_f32_e32 v54, 0x3fb8aa3b, v54
	v_add_f32_e32 v55, v63, v55
	v_mul_f32_e32 v55, 0x3fb8aa3b, v55
	v_add_f32_e32 v64, v56, v64
	v_mul_f32_e32 v64, 0x3fb8aa3b, v64
	v_add_f32_e32 v65, v57, v65
	v_mul_f32_e32 v65, 0x3fb8aa3b, v65
	v_add_f32_e32 v66, v58, v66
	v_mul_f32_e32 v66, 0x3fb8aa3b, v66
	v_add_f32_e32 v67, v59, v67
	v_mul_f32_e32 v67, 0x3fb8aa3b, v67
	s_mov_b64 s[12:13], 0

.LBB0_2091:
	s_add_i32 s4, s13, -1
	s_min_i32 s4, s4, s12
	s_ashr_i32 s5, s4, 31
	s_lshl_b64 s[4:5], s[4:5], 12
	s_waitcnt vmcnt(0)
	v_lshl_add_u64 v[134:135], v[12:13], 0, s[4:5]
	global_load_dwordx4 v[162:165], v[134:135], off
	global_load_dwordx4 v[158:161], v[134:135], off offset:1024
	global_load_dwordx4 v[154:157], v[134:135], off offset:2048
	global_load_dwordx4 v[150:153], v[134:135], off offset:3072
	v_lshl_add_u64 v[134:135], v[182:183], 0, s[4:5]
	global_load_dwordx4 v[146:149], v[134:135], off
	global_load_dwordx4 v[138:141], v[134:135], off offset:1024
	global_load_dwordx4 v[142:145], v[134:135], off offset:2048
	s_nop 0
	global_load_dwordx4 v[134:137], v[134:135], off offset:3072
	s_waitcnt vmcnt(8)
	v_mfma_f32_16x16x32_bf16 v[166:169], v[130:133], v[70:73], 0
	s_sub_i32 s4, s2, 46
	s_cmpk_gt_i32 s4, 0x7e
	s_cselect_b64 s[4:5], -1, 0
	v_mfma_f32_16x16x32_bf16 v[170:173], v[126:129], v[74:77], v[166:169]
	s_cmpk_lt_i32 s2, 0x200
	s_cselect_b64 s[6:7], -1, 0
	s_and_b64 s[6:7], s[4:5], s[6:7]
	v_mfma_f32_16x16x32_bf16 v[166:169], v[122:125], v[70:73], 0
	s_mov_b64 s[8:9], -1
	s_and_b64 vcc, exec, s[6:7]
	v_mfma_f32_16x16x32_bf16 v[166:169], v[118:121], v[74:77], v[166:169]
	s_cbranch_vccnz .LBB0_2109
	v_add_u32_e32 v10, s2, v214
	v_add_u32_e32 v194, -15, v10
	v_mov_b32_e32 v244, 0x25ffc
	v_cmp_gt_u32_e32 vcc, s85, v194
	v_mov_b32_e32 v193, 0xff800000
	v_mov_b32_e32 v192, 0xff800000
	ds_write_b32 v244, v192
	v_min_u32_e32 v192, 0x7f, v194
	v_lshl_add_u32 v192, v192, 2, s87
	v_cndmask_b32_e32 v192, v244, v192, vcc
	ds_read_b32 v192, v192
	v_add_u32_e32 v194, -16, v10
	v_cmp_gt_u32_e32 vcc, s85, v194
	v_min_u32_e32 v193, 0x7f, v194
	v_lshl_add_u32 v193, v193, 2, s87
	v_cndmask_b32_e32 v193, v244, v193, vcc
	ds_read_b32 v193, v193
	v_subrev_u32_e32 v196, 17, v10
	v_cmp_gt_u32_e32 vcc, s85, v196
	v_mov_b32_e32 v195, 0xff800000
	v_mov_b32_e32 v194, 0xff800000
	v_min_u32_e32 v194, 0x7f, v196
	v_lshl_add_u32 v194, v194, 2, s87
	v_cndmask_b32_e32 v194, v244, v194, vcc
	ds_read_b32 v194, v194
	v_subrev_u32_e32 v196, 18, v10
	v_cmp_gt_u32_e32 vcc, s85, v196
	v_min_u32_e32 v195, 0x7f, v196
	v_lshl_add_u32 v195, v195, 2, s87
	v_cndmask_b32_e32 v195, v244, v195, vcc
	ds_read_b32 v195, v195
	v_subrev_u32_e32 v198, 31, v10
	v_cmp_gt_u32_e32 vcc, s85, v198
	v_mov_b32_e32 v197, 0xff800000
	v_mov_b32_e32 v196, 0xff800000
	v_min_u32_e32 v196, 0x7f, v198
	v_lshl_add_u32 v196, v196, 2, s87
	v_cndmask_b32_e32 v196, v244, v196, vcc
	ds_read_b32 v196, v196
	v_subrev_u32_e32 v198, 32, v10
	v_cmp_gt_u32_e32 vcc, s85, v198
	v_min_u32_e32 v197, 0x7f, v198
	v_lshl_add_u32 v197, v197, 2, s87
	v_cndmask_b32_e32 v197, v244, v197, vcc
	ds_read_b32 v197, v197
	v_subrev_u32_e32 v200, 33, v10
	v_cmp_gt_u32_e32 vcc, s85, v200
	v_mov_b32_e32 v199, 0xff800000
	v_mov_b32_e32 v198, 0xff800000
	v_min_u32_e32 v198, 0x7f, v200
	v_lshl_add_u32 v198, v198, 2, s87
	v_cndmask_b32_e32 v198, v244, v198, vcc
	ds_read_b32 v198, v198
	v_subrev_u32_e32 v10, 34, v10
	v_cmp_gt_u32_e32 vcc, s85, v10
	v_min_u32_e32 v199, 0x7f, v10
	v_lshl_add_u32 v199, v199, 2, s87
	v_cndmask_b32_e32 v199, v244, v199, vcc
	ds_read_b32 v199, v199
	s_waitcnt lgkmcnt(0)
	v_add_f32_e32 v192, v170, v192
	v_mul_f32_e32 v192, 0x3fb8aa3b, v192
	v_add_f32_e32 v193, v171, v193
	v_mul_f32_e32 v193, 0x3fb8aa3b, v193
	v_add_f32_e32 v194, v172, v194
	v_mul_f32_e32 v194, 0x3fb8aa3b, v194
	v_add_f32_e32 v195, v173, v195
	v_mul_f32_e32 v195, 0x3fb8aa3b, v195
	v_add_f32_e32 v196, v166, v196
	v_mul_f32_e32 v196, 0x3fb8aa3b, v196
	v_add_f32_e32 v197, v167, v197
	v_mul_f32_e32 v197, 0x3fb8aa3b, v197
	v_add_f32_e32 v198, v168, v198
	v_mul_f32_e32 v198, 0x3fb8aa3b, v198
	v_add_f32_e32 v199, v169, v199
	v_mul_f32_e32 v199, 0x3fb8aa3b, v199
	v_max3_f32 v10, v192, s89, v193
	v_max3_f32 v10, v10, v194, v195
	v_max3_f32 v10, v10, v196, v197
	v_max3_f32 v10, v10, v198, v199
	s_mov_b64 s[8:9], 0

.LBB0_2111:
	s_nop 4
	v_mov_b32_e32 v166, v10
	s_nop 1
	v_permlane16_swap_b32 v10, v166
	s_nop 1
	s_xor_b64 s[8:9], s[6:7], -1
	v_max_f32_e32 v166, v166, v166
	v_max_f32_e32 v10, v10, v10
	v_max_f32_e32 v10, v10, v166
	v_mov_b32_e32 v166, v10
	s_nop 1
	v_permlane32_swap_b32 v10, v166
	s_nop 1
	s_mov_b64 s[10:11], -1
	v_max3_f32 v227, v222, v10, v166
	v_sub_f32_e32 v166, v192, v227
	v_exp_f32_e32 v166, v166
	v_sub_f32_e32 v168, v193, v227
	v_exp_f32_e32 v168, v168
	v_sub_f32_e32 v169, v194, v227
	v_exp_f32_e32 v169, v169
	v_sub_f32_e32 v170, v195, v227
	v_exp_f32_e32 v170, v170
	v_sub_f32_e32 v171, v196, v227
	v_add_f32_e32 v167, 0, v166
	v_exp_f32_e32 v171, v171
	v_sub_f32_e32 v172, v197, v227
	v_add_f32_e32 v167, v168, v167
	v_exp_f32_e32 v172, v172
	v_sub_f32_e32 v173, v198, v227
	v_add_f32_e32 v167, v169, v167
	v_exp_f32_e32 v173, v173
	v_sub_f32_e32 v192, v199, v227
	v_add_f32_e32 v167, v170, v167
	v_exp_f32_e32 v192, v192
	v_add_f32_e32 v167, v171, v167
	v_sub_f32_e32 v10, v222, v227
	v_add_f32_e32 v167, v172, v167
	v_add_f32_e32 v167, v173, v167
	v_exp_f32_e32 v10, v10
	v_add_f32_e32 v167, v192, v167
	v_mov_b32_e32 v193, v167
	s_nop 1
	v_permlane16_swap_b32 v167, v193
	s_nop 1
	v_cvt_pk_bf16_f32 v166, v166, v168
	v_cvt_pk_bf16_f32 v168, v171, v172
	v_pk_mul_f32 v[68:69], v[68:69], v[10:11] op_sel_hi:[1,0]
	v_add_f32_e32 v222, v167, v193
	v_cvt_pk_bf16_f32 v167, v169, v170
	v_cvt_pk_bf16_f32 v169, v173, v192
	v_pk_mul_f32 v[66:67], v[66:67], v[10:11] op_sel_hi:[1,0]
	v_pk_mul_f32 v[64:65], v[64:65], v[10:11] op_sel_hi:[1,0]
	v_pk_mul_f32 v[62:63], v[62:63], v[10:11] op_sel_hi:[1,0]
	v_pk_mul_f32 v[60:61], v[60:61], v[10:11] op_sel_hi:[1,0]
	v_pk_mul_f32 v[58:59], v[58:59], v[10:11] op_sel_hi:[1,0]
	v_pk_mul_f32 v[56:57], v[56:57], v[10:11] op_sel_hi:[1,0]
	v_pk_mul_f32 v[54:55], v[54:55], v[10:11] op_sel_hi:[1,0]
	v_mfma_f32_16x16x32_bf16 v[66:69], v[114:117], v[166:169], v[66:69]
	v_cndmask_b32_e64 v192, 0, 1, s[8:9]
	v_mov_b32_e32 v223, v222
	v_cmp_ne_u32_e64 s[6:7], 1, v192
	v_mfma_f32_16x16x32_bf16 v[62:65], v[106:109], v[166:169], v[62:65]
	s_andn2_b64 vcc, exec, s[8:9]
	s_nop 1
	v_permlane32_swap_b32 v222, v223
	s_nop 1
	v_mfma_f32_16x16x32_bf16 v[58:61], v[110:113], v[166:169], v[58:61]
	v_mfma_f32_16x16x32_bf16 v[54:57], v[102:105], v[166:169], v[54:57]
	v_mfma_f32_16x16x32_bf16 v[166:169], v[130:133], v[78:81], 0
	v_mfma_f32_16x16x32_bf16 v[170:173], v[122:125], v[78:81], 0
	v_mfma_f32_16x16x32_bf16 v[166:169], v[126:129], v[82:85], v[166:169]
	v_mfma_f32_16x16x32_bf16 v[170:173], v[118:121], v[82:85], v[170:173]
	s_cbranch_vccnz .LBB0_2129
	v_add_u32_e32 v200, s2, v214
	v_add_u32_e32 v194, -15, v200
	v_mov_b32_e32 v244, 0x25dfc
	v_cmp_gt_u32_e32 vcc, s85, v194
	v_mov_b32_e32 v193, 0xff800000
	v_mov_b32_e32 v192, 0xff800000
	ds_write_b32 v244, v192 offset:512
	v_min_u32_e32 v192, 0x7f, v194
	v_lshl_add_u32 v192, v192, 2, s87
	v_cndmask_b32_e32 v192, v244, v192, vcc
	ds_read_b32 v192, v192 offset:512
	v_add_u32_e32 v194, -16, v200
	v_cmp_gt_u32_e32 vcc, s85, v194
	v_min_u32_e32 v193, 0x7f, v194
	v_lshl_add_u32 v193, v193, 2, s87
	v_cndmask_b32_e32 v193, v244, v193, vcc
	ds_read_b32 v193, v193 offset:512
	v_subrev_u32_e32 v196, 17, v200
	v_cmp_gt_u32_e32 vcc, s85, v196
	v_mov_b32_e32 v195, 0xff800000
	v_mov_b32_e32 v194, 0xff800000
	v_min_u32_e32 v194, 0x7f, v196
	v_lshl_add_u32 v194, v194, 2, s87
	v_cndmask_b32_e32 v194, v244, v194, vcc
	ds_read_b32 v194, v194 offset:512
	v_subrev_u32_e32 v196, 18, v200
	v_cmp_gt_u32_e32 vcc, s85, v196
	v_min_u32_e32 v195, 0x7f, v196
	v_lshl_add_u32 v195, v195, 2, s87
	v_cndmask_b32_e32 v195, v244, v195, vcc
	ds_read_b32 v195, v195 offset:512
	v_subrev_u32_e32 v198, 31, v200
	v_cmp_gt_u32_e32 vcc, s85, v198
	v_mov_b32_e32 v197, 0xff800000
	v_mov_b32_e32 v196, 0xff800000
	v_min_u32_e32 v196, 0x7f, v198
	v_lshl_add_u32 v196, v196, 2, s87
	v_cndmask_b32_e32 v196, v244, v196, vcc
	ds_read_b32 v196, v196 offset:512
	v_subrev_u32_e32 v198, 32, v200
	v_cmp_gt_u32_e32 vcc, s85, v198
	v_min_u32_e32 v197, 0x7f, v198
	v_lshl_add_u32 v197, v197, 2, s87
	v_cndmask_b32_e32 v197, v244, v197, vcc
	ds_read_b32 v197, v197 offset:512
	v_subrev_u32_e32 v201, 33, v200
	v_cmp_gt_u32_e32 vcc, s85, v201
	v_mov_b32_e32 v199, 0xff800000
	v_mov_b32_e32 v198, 0xff800000
	v_min_u32_e32 v198, 0x7f, v201
	v_lshl_add_u32 v198, v198, 2, s87
	v_cndmask_b32_e32 v198, v244, v198, vcc
	ds_read_b32 v198, v198 offset:512
	v_subrev_u32_e32 v200, 34, v200
	v_cmp_gt_u32_e32 vcc, s85, v200
	v_min_u32_e32 v199, 0x7f, v200
	v_lshl_add_u32 v199, v199, 2, s87
	v_cndmask_b32_e32 v199, v244, v199, vcc
	ds_read_b32 v199, v199 offset:512
	s_waitcnt lgkmcnt(0)
	v_add_f32_e32 v192, v166, v192
	v_mul_f32_e32 v192, 0x3fb8aa3b, v192
	v_add_f32_e32 v193, v167, v193
	v_mul_f32_e32 v193, 0x3fb8aa3b, v193
	v_add_f32_e32 v194, v168, v194
	v_mul_f32_e32 v194, 0x3fb8aa3b, v194
	v_add_f32_e32 v195, v169, v195
	v_mul_f32_e32 v195, 0x3fb8aa3b, v195
	v_add_f32_e32 v196, v170, v196
	v_mul_f32_e32 v196, 0x3fb8aa3b, v196
	v_add_f32_e32 v197, v171, v197
	v_mul_f32_e32 v197, 0x3fb8aa3b, v197
	v_add_f32_e32 v198, v172, v198
	v_mul_f32_e32 v198, 0x3fb8aa3b, v198
	v_add_f32_e32 v199, v173, v199
	v_mul_f32_e32 v199, 0x3fb8aa3b, v199
	v_max3_f32 v200, v192, s89, v193
	v_max3_f32 v200, v200, v194, v195
	v_max3_f32 v200, v200, v196, v197
	v_max3_f32 v200, v200, v198, v199
	s_mov_b64 s[10:11], 0

.LBB0_2131:
	s_nop 3
	v_mov_b32_e32 v166, v200
	s_nop 1
	v_permlane16_swap_b32 v200, v166
	s_nop 1
	s_mov_b64 s[8:9], -1
	v_max_f32_e32 v166, v166, v166
	v_max_f32_e32 v167, v200, v200
	v_max_f32_e32 v166, v167, v166
	v_mov_b32_e32 v167, v166
	s_nop 1
	v_permlane32_swap_b32 v167, v166
	s_nop 1
	s_and_b64 vcc, exec, s[6:7]
	v_max3_f32 v228, v221, v167, v166
	v_sub_f32_e32 v167, v192, v228
	v_exp_f32_e32 v167, v167
	v_sub_f32_e32 v169, v193, v228
	v_exp_f32_e32 v169, v169
	v_sub_f32_e32 v170, v194, v228
	v_exp_f32_e32 v170, v170
	v_sub_f32_e32 v171, v195, v228
	v_exp_f32_e32 v171, v171
	v_sub_f32_e32 v172, v196, v228
	v_add_f32_e32 v168, 0, v167
	v_exp_f32_e32 v172, v172
	v_sub_f32_e32 v173, v197, v228
	v_add_f32_e32 v168, v169, v168
	v_exp_f32_e32 v173, v173
	v_sub_f32_e32 v192, v198, v228
	v_add_f32_e32 v168, v170, v168
	v_exp_f32_e32 v194, v192
	v_sub_f32_e32 v192, v199, v228
	v_add_f32_e32 v168, v171, v168
	v_exp_f32_e32 v195, v192
	v_add_f32_e32 v168, v172, v168
	v_add_f32_e32 v168, v173, v168
	v_sub_f32_e32 v166, v221, v228
	v_add_f32_e32 v168, v194, v168
	v_add_f32_e32 v168, v195, v168
	v_exp_f32_e32 v192, v166
	v_mov_b32_e32 v166, v168
	s_nop 1
	v_permlane16_swap_b32 v166, v168
	s_nop 1
	s_nop 0
	v_add_f32_e32 v193, v166, v168
	v_mov_b32_e32 v221, v193
	s_nop 1
	v_permlane32_swap_b32 v221, v193
	s_nop 1
	v_cvt_pk_bf16_f32 v166, v167, v169
	v_cvt_pk_bf16_f32 v167, v170, v171
	v_cvt_pk_bf16_f32 v168, v172, v173
	v_cvt_pk_bf16_f32 v169, v194, v195
	v_mfma_f32_16x16x32_bf16 v[170:173], v[122:125], v[86:89], 0
	v_mul_f32_e64 v52, v52, v192
	v_mul_f32_e64 v53, v53, v192
	v_pk_mul_f32 v[50:51], v[50:51], v[192:193] op_sel_hi:[1,0]
	v_pk_mul_f32 v[48:49], v[48:49], v[192:193] op_sel_hi:[1,0]
	v_pk_mul_f32 v[46:47], v[46:47], v[192:193] op_sel_hi:[1,0]
	v_pk_mul_f32 v[44:45], v[44:45], v[192:193] op_sel_hi:[1,0]
	v_pk_mul_f32 v[42:43], v[42:43], v[192:193] op_sel_hi:[1,0]
	v_pk_mul_f32 v[40:41], v[40:41], v[192:193] op_sel_hi:[1,0]
	v_pk_mul_f32 v[38:39], v[38:39], v[192:193] op_sel_hi:[1,0]
	v_mfma_f32_16x16x32_bf16 v[50:53], v[114:117], v[166:169], v[50:53]
	v_mfma_f32_16x16x32_bf16 v[46:49], v[106:109], v[166:169], v[46:49]
	v_mfma_f32_16x16x32_bf16 v[42:45], v[110:113], v[166:169], v[42:45]
	v_mfma_f32_16x16x32_bf16 v[38:41], v[102:105], v[166:169], v[38:41]
	v_mfma_f32_16x16x32_bf16 v[166:169], v[130:133], v[86:89], 0
	v_mfma_f32_16x16x32_bf16 v[166:169], v[126:129], v[90:93], v[166:169]
	v_mfma_f32_16x16x32_bf16 v[170:173], v[118:121], v[90:93], v[170:173]
	s_cbranch_vccnz .LBB0_2149
	v_add_u32_e32 v224, s2, v214
	v_add_u32_e32 v196, -15, v224
	v_mov_b32_e32 v244, 0x25bfc
	v_cmp_gt_u32_e32 vcc, s85, v196
	v_mov_b32_e32 v195, 0xff800000
	v_mov_b32_e32 v194, 0xff800000
	ds_write_b32 v244, v194 offset:1024
	v_min_u32_e32 v194, 0x7f, v196
	v_lshl_add_u32 v194, v194, 2, s87
	v_cndmask_b32_e32 v194, v244, v194, vcc
	ds_read_b32 v194, v194 offset:1024
	v_add_u32_e32 v196, -16, v224
	v_cmp_gt_u32_e32 vcc, s85, v196
	v_min_u32_e32 v195, 0x7f, v196
	v_lshl_add_u32 v195, v195, 2, s87
	v_cndmask_b32_e32 v195, v244, v195, vcc
	ds_read_b32 v195, v195 offset:1024
	v_subrev_u32_e32 v198, 17, v224
	v_cmp_gt_u32_e32 vcc, s85, v198
	v_mov_b32_e32 v197, 0xff800000
	v_mov_b32_e32 v196, 0xff800000
	v_min_u32_e32 v196, 0x7f, v198
	v_lshl_add_u32 v196, v196, 2, s87
	v_cndmask_b32_e32 v196, v244, v196, vcc
	ds_read_b32 v196, v196 offset:1024
	v_subrev_u32_e32 v198, 18, v224
	v_cmp_gt_u32_e32 vcc, s85, v198
	v_min_u32_e32 v197, 0x7f, v198
	v_lshl_add_u32 v197, v197, 2, s87
	v_cndmask_b32_e32 v197, v244, v197, vcc
	ds_read_b32 v197, v197 offset:1024
	v_subrev_u32_e32 v200, 31, v224
	v_cmp_gt_u32_e32 vcc, s85, v200
	v_mov_b32_e32 v199, 0xff800000
	v_mov_b32_e32 v198, 0xff800000
	v_min_u32_e32 v198, 0x7f, v200
	v_lshl_add_u32 v198, v198, 2, s87
	v_cndmask_b32_e32 v198, v244, v198, vcc
	ds_read_b32 v198, v198 offset:1024
	v_subrev_u32_e32 v200, 32, v224
	v_cmp_gt_u32_e32 vcc, s85, v200
	v_min_u32_e32 v199, 0x7f, v200
	v_lshl_add_u32 v199, v199, 2, s87
	v_cndmask_b32_e32 v199, v244, v199, vcc
	ds_read_b32 v199, v199 offset:1024
	v_subrev_u32_e32 v225, 33, v224
	v_cmp_gt_u32_e32 vcc, s85, v225
	v_mov_b32_e32 v201, 0xff800000
	v_mov_b32_e32 v200, 0xff800000
	v_min_u32_e32 v200, 0x7f, v225
	v_lshl_add_u32 v200, v200, 2, s87
	v_cndmask_b32_e32 v200, v244, v200, vcc
	ds_read_b32 v200, v200 offset:1024
	v_subrev_u32_e32 v224, 34, v224
	v_cmp_gt_u32_e32 vcc, s85, v224
	v_min_u32_e32 v201, 0x7f, v224
	v_lshl_add_u32 v201, v201, 2, s87
	v_cndmask_b32_e32 v201, v244, v201, vcc
	ds_read_b32 v201, v201 offset:1024
	s_waitcnt lgkmcnt(0)
	v_add_f32_e32 v194, v166, v194
	v_mul_f32_e32 v194, 0x3fb8aa3b, v194
	v_add_f32_e32 v195, v167, v195
	v_mul_f32_e32 v195, 0x3fb8aa3b, v195
	v_add_f32_e32 v196, v168, v196
	v_mul_f32_e32 v196, 0x3fb8aa3b, v196
	v_add_f32_e32 v197, v169, v197
	v_mul_f32_e32 v197, 0x3fb8aa3b, v197
	v_add_f32_e32 v198, v170, v198
	v_mul_f32_e32 v198, 0x3fb8aa3b, v198
	v_add_f32_e32 v199, v171, v199
	v_mul_f32_e32 v199, 0x3fb8aa3b, v199
	v_add_f32_e32 v200, v172, v200
	v_mul_f32_e32 v200, 0x3fb8aa3b, v200
	v_add_f32_e32 v201, v173, v201
	v_mul_f32_e32 v201, 0x3fb8aa3b, v201
	v_max3_f32 v224, v194, s89, v195
	v_max3_f32 v224, v224, v196, v197
	v_max3_f32 v224, v224, v198, v199
	v_max3_f32 v224, v224, v200, v201
	s_mov_b64 s[8:9], 0

.LBB0_2151:
	s_nop 3
	v_mov_b32_e32 v166, v224
	s_nop 1
	v_permlane16_swap_b32 v224, v166
	s_nop 1
	v_mfma_f32_16x16x32_bf16 v[130:133], v[130:133], v[94:97], 0
	v_max_f32_e32 v166, v166, v166
	v_max_f32_e32 v167, v224, v224
	v_max_f32_e32 v166, v167, v166
	v_mov_b32_e32 v167, v166
	s_nop 1
	v_permlane32_swap_b32 v166, v167
	s_nop 1
	v_mfma_f32_16x16x32_bf16 v[122:125], v[122:125], v[94:97], 0
	v_max3_f32 v229, v220, v166, v167
	v_sub_f32_e32 v168, v195, v229
	v_exp_f32_e32 v172, v168
	v_sub_f32_e32 v168, v196, v229
	v_sub_f32_e32 v166, v220, v229
	v_sub_f32_e32 v167, v194, v229
	v_exp_f32_e32 v173, v168
	v_sub_f32_e32 v168, v197, v229
	v_exp_f32_e32 v167, v167
	v_exp_f32_e32 v194, v168
	v_sub_f32_e32 v168, v198, v229
	v_exp_f32_e32 v166, v166
	v_exp_f32_e32 v195, v168
	v_sub_f32_e32 v168, v199, v229
	v_exp_f32_e32 v196, v168
	v_sub_f32_e32 v168, v200, v229
	v_exp_f32_e32 v197, v168
	v_sub_f32_e32 v168, v201, v229
	v_exp_f32_e32 v198, v168
	v_cvt_pk_bf16_f32 v168, v167, v172
	v_pk_mul_f32 v[36:37], v[36:37], v[166:167] op_sel_hi:[1,0]
	v_pk_mul_f32 v[34:35], v[34:35], v[166:167] op_sel_hi:[1,0]
	v_pk_mul_f32 v[32:33], v[32:33], v[166:167] op_sel_hi:[1,0]
	v_pk_mul_f32 v[30:31], v[30:31], v[166:167] op_sel_hi:[1,0]
	v_pk_mul_f32 v[28:29], v[28:29], v[166:167] op_sel_hi:[1,0]
	v_pk_mul_f32 v[26:27], v[26:27], v[166:167] op_sel_hi:[1,0]
	v_add_f32_e32 v167, 0, v167
	v_pk_mul_f32 v[24:25], v[24:25], v[166:167] op_sel_hi:[1,0]
	v_pk_mul_f32 v[22:23], v[22:23], v[166:167] op_sel_hi:[1,0]
	v_add_f32_e32 v167, v172, v167
	v_add_f32_e32 v167, v173, v167
	v_add_f32_e32 v167, v194, v167
	v_add_f32_e32 v167, v195, v167
	v_add_f32_e32 v167, v196, v167
	v_add_f32_e32 v167, v197, v167
	v_cvt_pk_bf16_f32 v169, v173, v194
	v_cvt_pk_bf16_f32 v170, v195, v196
	v_cvt_pk_bf16_f32 v171, v197, v198
	v_mfma_f32_16x16x32_bf16 v[126:129], v[126:129], v[98:101], v[130:133]
	s_and_b64 vcc, exec, s[6:7]
	s_mov_b64 s[6:7], -1
	v_mfma_f32_16x16x32_bf16 v[34:37], v[114:117], v[168:171], v[34:37]
	v_add_f32_e32 v130, v198, v167
	v_mov_b32_e32 v131, v130
	s_nop 1
	v_permlane16_swap_b32 v130, v131
	s_nop 1
	v_mfma_f32_16x16x32_bf16 v[30:33], v[106:109], v[168:171], v[30:33]
	v_add_f32_e32 v167, v130, v131
	v_mfma_f32_16x16x32_bf16 v[26:29], v[110:113], v[168:171], v[26:29]
	v_mfma_f32_16x16x32_bf16 v[22:25], v[102:105], v[168:171], v[22:25]
	v_mov_b32_e32 v168, v167
	s_nop 1
	v_permlane32_swap_b32 v167, v168
	s_nop 1
	v_mfma_f32_16x16x32_bf16 v[118:121], v[118:121], v[98:101], v[122:125]
	s_cbranch_vccnz .LBB0_2169
	v_add_u32_e32 v169, s2, v214
	s_nop 0
	v_add_u32_e32 v124, -15, v169
	v_mov_b32_e32 v244, 0x259fc
	v_cmp_gt_u32_e32 vcc, s85, v124
	v_mov_b32_e32 v123, 0xff800000
	v_mov_b32_e32 v122, 0xff800000
	ds_write_b32 v244, v122 offset:1536
	v_min_u32_e32 v122, 0x7f, v124
	v_lshl_add_u32 v122, v122, 2, s87
	v_cndmask_b32_e32 v122, v244, v122, vcc
	ds_read_b32 v122, v122 offset:1536
	v_add_u32_e32 v124, -16, v169
	v_cmp_gt_u32_e32 vcc, s85, v124
	v_min_u32_e32 v123, 0x7f, v124
	v_lshl_add_u32 v123, v123, 2, s87
	v_cndmask_b32_e32 v123, v244, v123, vcc
	ds_read_b32 v123, v123 offset:1536
	v_subrev_u32_e32 v130, 17, v169
	v_cmp_gt_u32_e32 vcc, s85, v130
	v_mov_b32_e32 v125, 0xff800000
	v_mov_b32_e32 v124, 0xff800000
	v_min_u32_e32 v124, 0x7f, v130
	v_lshl_add_u32 v124, v124, 2, s87
	v_cndmask_b32_e32 v124, v244, v124, vcc
	ds_read_b32 v124, v124 offset:1536
	v_subrev_u32_e32 v130, 18, v169
	v_cmp_gt_u32_e32 vcc, s85, v130
	v_min_u32_e32 v125, 0x7f, v130
	v_lshl_add_u32 v125, v125, 2, s87
	v_cndmask_b32_e32 v125, v244, v125, vcc
	ds_read_b32 v125, v125 offset:1536
	v_subrev_u32_e32 v132, 31, v169
	v_cmp_gt_u32_e32 vcc, s85, v132
	v_mov_b32_e32 v131, 0xff800000
	v_mov_b32_e32 v130, 0xff800000
	v_min_u32_e32 v130, 0x7f, v132
	v_lshl_add_u32 v130, v130, 2, s87
	v_cndmask_b32_e32 v130, v244, v130, vcc
	ds_read_b32 v130, v130 offset:1536
	v_subrev_u32_e32 v132, 32, v169
	v_cmp_gt_u32_e32 vcc, s85, v132
	v_min_u32_e32 v131, 0x7f, v132
	v_lshl_add_u32 v131, v131, 2, s87
	v_cndmask_b32_e32 v131, v244, v131, vcc
	ds_read_b32 v131, v131 offset:1536
	v_subrev_u32_e32 v170, 33, v169
	v_cmp_gt_u32_e32 vcc, s85, v170
	v_mov_b32_e32 v133, 0xff800000
	v_mov_b32_e32 v132, 0xff800000
	v_min_u32_e32 v132, 0x7f, v170
	v_lshl_add_u32 v132, v132, 2, s87
	v_cndmask_b32_e32 v132, v244, v132, vcc
	ds_read_b32 v132, v132 offset:1536
	v_subrev_u32_e32 v169, 34, v169
	v_cmp_gt_u32_e32 vcc, s85, v169
	v_min_u32_e32 v133, 0x7f, v169
	v_lshl_add_u32 v133, v133, 2, s87
	v_cndmask_b32_e32 v133, v244, v133, vcc
	ds_read_b32 v133, v133 offset:1536
	s_waitcnt lgkmcnt(0)
	v_add_f32_e32 v122, v126, v122
	v_mul_f32_e32 v122, 0x3fb8aa3b, v122
	v_add_f32_e32 v123, v127, v123
	v_mul_f32_e32 v123, 0x3fb8aa3b, v123
	v_add_f32_e32 v124, v128, v124
	v_mul_f32_e32 v124, 0x3fb8aa3b, v124
	v_add_f32_e32 v125, v129, v125
	v_mul_f32_e32 v125, 0x3fb8aa3b, v125
	v_add_f32_e32 v130, v118, v130
	v_mul_f32_e32 v130, 0x3fb8aa3b, v130
	v_add_f32_e32 v131, v119, v131
	v_mul_f32_e32 v131, 0x3fb8aa3b, v131
	v_add_f32_e32 v132, v120, v132
	v_mul_f32_e32 v132, 0x3fb8aa3b, v132
	v_add_f32_e32 v133, v121, v133
	v_mul_f32_e32 v133, 0x3fb8aa3b, v133
	v_max3_f32 v169, v122, s89, v123
	v_max3_f32 v169, v169, v124, v125
	v_max3_f32 v169, v169, v130, v131
	v_max3_f32 v169, v169, v132, v133
	s_mov_b64 s[6:7], 0

.LBB0_2171:
	v_add_f32_e32 v226, v222, v223
	v_fmac_f32_e32 v226, v219, v10
	v_mov_b32_e32 v10, v169
	s_nop 1
	v_permlane16_swap_b32 v169, v10
	s_nop 1
	v_add_f32_e32 v224, v167, v168
	v_max_f32_e32 v10, v10, v10
	v_max_f32_e32 v118, v169, v169
	v_max_f32_e32 v10, v118, v10
	v_mov_b32_e32 v118, v10
	s_nop 1
	v_permlane32_swap_b32 v10, v118
	s_nop 1
	v_add_f32_e32 v225, v221, v193
	v_max3_f32 v230, v216, v10, v118
	v_sub_f32_e32 v118, v122, v230
	v_exp_f32_e32 v118, v118
	v_sub_f32_e32 v119, v123, v230
	v_exp_f32_e32 v119, v119
	v_sub_f32_e32 v120, v124, v230
	v_exp_f32_e32 v120, v120
	v_sub_f32_e32 v121, v125, v230
	v_exp_f32_e32 v121, v121
	v_sub_f32_e32 v123, v130, v230
	v_add_f32_e32 v122, 0, v118
	v_exp_f32_e32 v123, v123
	v_sub_f32_e32 v124, v131, v230
	v_add_f32_e32 v122, v119, v122
	v_exp_f32_e32 v124, v124
	v_sub_f32_e32 v125, v132, v230
	v_add_f32_e32 v122, v120, v122
	v_exp_f32_e32 v125, v125
	v_sub_f32_e32 v126, v133, v230
	v_add_f32_e32 v122, v121, v122
	v_exp_f32_e32 v126, v126
	v_sub_f32_e32 v10, v216, v230
	v_add_f32_e32 v122, v123, v122
	v_add_f32_e32 v122, v124, v122
	v_exp_f32_e32 v10, v10
	v_add_f32_e32 v122, v125, v122
	v_add_f32_e32 v122, v126, v122
	v_mov_b32_e32 v127, v122
	s_nop 1
	v_permlane16_swap_b32 v122, v127
	s_nop 1
	v_pk_mul_f32 v[20:21], v[20:21], v[10:11] op_sel_hi:[1,0]
	v_pk_mul_f32 v[18:19], v[18:19], v[10:11] op_sel_hi:[1,0]
	v_pk_mul_f32 v[16:17], v[16:17], v[10:11] op_sel_hi:[1,0]
	v_pk_mul_f32 v[14:15], v[14:15], v[10:11] op_sel_hi:[1,0]
	v_pk_mul_f32 v[8:9], v[8:9], v[10:11] op_sel_hi:[1,0]
	v_pk_mul_f32 v[6:7], v[6:7], v[10:11] op_sel_hi:[1,0]
	v_pk_mul_f32 v[4:5], v[4:5], v[10:11] op_sel_hi:[1,0]
	v_pk_mul_f32 v[2:3], v[2:3], v[10:11] op_sel_hi:[1,0]
	v_add_f32_e32 v122, v122, v127
	v_cvt_pk_bf16_f32 v118, v118, v119
	v_cvt_pk_bf16_f32 v119, v120, v121
	v_cvt_pk_bf16_f32 v120, v123, v124
	v_cvt_pk_bf16_f32 v121, v125, v126
	v_mov_b32_e32 v127, v122
	v_mfma_f32_16x16x32_bf16 v[18:21], v[114:117], v[118:121], v[18:21]
	s_add_i32 s4, s13, -2
	s_nop 1
	v_permlane32_swap_b32 v122, v127
	s_nop 1
	v_fmac_f32_e32 v224, v217, v166
	v_mfma_f32_16x16x32_bf16 v[14:17], v[106:109], v[118:121], v[14:17]
	v_add_f32_e32 v223, v122, v127
	v_fmac_f32_e32 v225, v218, v192
	v_fmac_f32_e32 v223, v215, v10
	v_mfma_f32_16x16x32_bf16 v[6:9], v[110:113], v[118:121], v[6:9]
	s_cmp_ge_i32 s4, s12
	s_mov_b64 s[6:7], -1
	v_mfma_f32_16x16x32_bf16 v[2:5], v[102:105], v[118:121], v[2:5]
	s_cbranch_scc1 .LBB0_2252
	s_min_i32 s4, s13, s12
	s_ashr_i32 s5, s4, 31
	s_lshl_b64 s[4:5], s[4:5], 12
	v_lshl_add_u64 v[102:103], v[12:13], 0, s[4:5]
	global_load_dwordx4 v[130:133], v[102:103], off
	global_load_dwordx4 v[126:129], v[102:103], off offset:1024
	global_load_dwordx4 v[122:125], v[102:103], off offset:2048
	global_load_dwordx4 v[118:121], v[102:103], off offset:3072
	v_lshl_add_u64 v[102:103], v[182:183], 0, s[4:5]
	global_load_dwordx4 v[114:117], v[102:103], off
	global_load_dwordx4 v[106:109], v[102:103], off offset:1024
	global_load_dwordx4 v[110:113], v[102:103], off offset:2048
	s_nop 0
	global_load_dwordx4 v[102:105], v[102:103], off offset:3072
	s_waitcnt vmcnt(15)
	v_mfma_f32_16x16x32_bf16 v[166:169], v[162:165], v[70:73], 0
	s_add_i32 s4, s2, 0xffffffb2
	s_cmpk_gt_i32 s4, 0x7e
	s_cselect_b64 s[4:5], -1, 0
	s_waitcnt vmcnt(14)
	v_mfma_f32_16x16x32_bf16 v[170:173], v[158:161], v[74:77], v[166:169]
	s_sub_i32 s6, s2, 32
	s_cmpk_lt_i32 s6, 0x200
	s_cselect_b64 s[6:7], -1, 0
	s_waitcnt vmcnt(13)
	v_mfma_f32_16x16x32_bf16 v[166:169], v[154:157], v[70:73], 0
	s_and_b64 s[6:7], s[4:5], s[6:7]
	v_add_u32_e32 v215, s2, v214
	s_mov_b64 s[8:9], -1
	s_waitcnt vmcnt(12)
	v_mfma_f32_16x16x32_bf16 v[166:169], v[150:153], v[74:77], v[166:169]
	s_and_b64 vcc, exec, s[6:7]
	v_subrev_u32_e32 v216, 47, v215
	s_cbranch_vccnz .LBB0_2190
	v_mov_b32_e32 v244, 0x25ffc
	v_cmp_gt_u32_e32 vcc, s85, v216
	v_mov_b32_e32 v193, 0xff800000
	v_mov_b32_e32 v192, 0xff800000
	ds_write_b32 v244, v192
	v_min_u32_e32 v192, 0x7f, v216
	v_lshl_add_u32 v192, v192, 2, s87
	v_cndmask_b32_e32 v192, v244, v192, vcc
	ds_read_b32 v192, v192
	v_subrev_u32_e32 v10, 48, v215
	v_cmp_gt_u32_e32 vcc, s85, v10
	v_min_u32_e32 v193, 0x7f, v10
	v_lshl_add_u32 v193, v193, 2, s87
	v_cndmask_b32_e32 v193, v244, v193, vcc
	ds_read_b32 v193, v193
	v_subrev_u32_e32 v10, 49, v215
	v_cmp_gt_u32_e32 vcc, s85, v10
	v_mov_b32_e32 v195, 0xff800000
	v_mov_b32_e32 v194, 0xff800000
	v_min_u32_e32 v194, 0x7f, v10
	v_lshl_add_u32 v194, v194, 2, s87
	v_cndmask_b32_e32 v194, v244, v194, vcc
	ds_read_b32 v194, v194
	v_subrev_u32_e32 v10, 50, v215
	v_cmp_gt_u32_e32 vcc, s85, v10
	v_min_u32_e32 v195, 0x7f, v10
	v_lshl_add_u32 v195, v195, 2, s87
	v_cndmask_b32_e32 v195, v244, v195, vcc
	ds_read_b32 v195, v195
	v_subrev_u32_e32 v10, 63, v215
	v_cmp_gt_u32_e32 vcc, s85, v10
	v_mov_b32_e32 v197, 0xff800000
	v_mov_b32_e32 v196, 0xff800000
	v_min_u32_e32 v196, 0x7f, v10
	v_lshl_add_u32 v196, v196, 2, s87
	v_cndmask_b32_e32 v196, v244, v196, vcc
	ds_read_b32 v196, v196
	v_subrev_u32_e32 v10, 64, v215
	v_cmp_gt_u32_e32 vcc, s85, v10
	v_min_u32_e32 v197, 0x7f, v10
	v_lshl_add_u32 v197, v197, 2, s87
	v_cndmask_b32_e32 v197, v244, v197, vcc
	ds_read_b32 v197, v197
	v_add_u32_e32 v10, 0xffffffbf, v215
	v_cmp_gt_u32_e32 vcc, s85, v10
	v_mov_b32_e32 v199, 0xff800000
	v_mov_b32_e32 v198, 0xff800000
	v_min_u32_e32 v198, 0x7f, v10
	v_lshl_add_u32 v198, v198, 2, s87
	v_cndmask_b32_e32 v198, v244, v198, vcc
	ds_read_b32 v198, v198
	v_add_u32_e32 v10, 0xffffffbe, v215
	v_cmp_gt_u32_e32 vcc, s85, v10
	v_min_u32_e32 v199, 0x7f, v10
	v_lshl_add_u32 v199, v199, 2, s87
	v_cndmask_b32_e32 v199, v244, v199, vcc
	ds_read_b32 v199, v199
	s_waitcnt lgkmcnt(0)
	v_add_f32_e32 v192, v170, v192
	v_mul_f32_e32 v192, 0x3fb8aa3b, v192
	v_add_f32_e32 v193, v171, v193
	v_mul_f32_e32 v193, 0x3fb8aa3b, v193
	v_add_f32_e32 v194, v172, v194
	v_mul_f32_e32 v194, 0x3fb8aa3b, v194
	v_add_f32_e32 v195, v173, v195
	v_mul_f32_e32 v195, 0x3fb8aa3b, v195
	v_add_f32_e32 v196, v166, v196
	v_mul_f32_e32 v196, 0x3fb8aa3b, v196
	v_add_f32_e32 v197, v167, v197
	v_mul_f32_e32 v197, 0x3fb8aa3b, v197
	v_add_f32_e32 v198, v168, v198
	v_mul_f32_e32 v198, 0x3fb8aa3b, v198
	v_add_f32_e32 v199, v169, v199
	v_mul_f32_e32 v199, 0x3fb8aa3b, v199
	v_max3_f32 v10, v192, s89, v193
	v_max3_f32 v10, v10, v194, v195
	v_max3_f32 v10, v10, v196, v197
	v_max3_f32 v10, v10, v198, v199
	s_mov_b64 s[8:9], 0

.LBB0_2192:
	s_nop 2
	v_mov_b32_e32 v166, v10
	s_nop 1
	v_permlane16_swap_b32 v10, v166
	s_nop 1
	s_xor_b64 s[8:9], s[6:7], -1
	v_max_f32_e32 v166, v166, v166
	v_max_f32_e32 v10, v10, v10
	v_max_f32_e32 v10, v10, v166
	v_mov_b32_e32 v166, v10
	s_nop 1
	v_permlane32_swap_b32 v10, v166
	s_nop 1
	s_mov_b64 s[10:11], -1
	v_max3_f32 v222, v227, v10, v166
	v_sub_f32_e32 v166, v192, v222
	v_exp_f32_e32 v166, v166
	v_sub_f32_e32 v168, v193, v222
	v_exp_f32_e32 v168, v168
	v_sub_f32_e32 v169, v194, v222
	v_exp_f32_e32 v169, v169
	v_sub_f32_e32 v170, v195, v222
	v_exp_f32_e32 v170, v170
	v_sub_f32_e32 v171, v196, v222
	v_add_f32_e32 v167, 0, v166
	v_exp_f32_e32 v171, v171
	v_sub_f32_e32 v172, v197, v222
	v_add_f32_e32 v167, v168, v167
	v_exp_f32_e32 v172, v172
	v_sub_f32_e32 v173, v198, v222
	v_add_f32_e32 v167, v169, v167
	v_exp_f32_e32 v173, v173
	v_sub_f32_e32 v192, v199, v222
	v_add_f32_e32 v167, v170, v167
	v_exp_f32_e32 v192, v192
	v_add_f32_e32 v167, v171, v167
	v_sub_f32_e32 v10, v227, v222
	v_add_f32_e32 v167, v172, v167
	v_add_f32_e32 v167, v173, v167
	v_exp_f32_e32 v10, v10
	v_add_f32_e32 v167, v192, v167
	v_mov_b32_e32 v193, v167
	s_nop 1
	v_permlane16_swap_b32 v167, v193
	s_nop 1
	v_cvt_pk_bf16_f32 v166, v166, v168
	v_cvt_pk_bf16_f32 v168, v171, v172
	v_pk_mul_f32 v[68:69], v[68:69], v[10:11] op_sel_hi:[1,0]
	v_add_f32_e32 v219, v167, v193
	v_cvt_pk_bf16_f32 v167, v169, v170
	v_cvt_pk_bf16_f32 v169, v173, v192
	v_pk_mul_f32 v[66:67], v[66:67], v[10:11] op_sel_hi:[1,0]
	v_pk_mul_f32 v[64:65], v[64:65], v[10:11] op_sel_hi:[1,0]
	v_pk_mul_f32 v[62:63], v[62:63], v[10:11] op_sel_hi:[1,0]
	v_pk_mul_f32 v[60:61], v[60:61], v[10:11] op_sel_hi:[1,0]
	v_pk_mul_f32 v[58:59], v[58:59], v[10:11] op_sel_hi:[1,0]
	v_pk_mul_f32 v[56:57], v[56:57], v[10:11] op_sel_hi:[1,0]
	v_pk_mul_f32 v[54:55], v[54:55], v[10:11] op_sel_hi:[1,0]
	s_waitcnt vmcnt(11)
	v_mfma_f32_16x16x32_bf16 v[66:69], v[146:149], v[166:169], v[66:69]
	v_cndmask_b32_e64 v192, 0, 1, s[8:9]
	v_mov_b32_e32 v227, v219
	v_cmp_ne_u32_e64 s[6:7], 1, v192
	s_waitcnt vmcnt(10)
	v_mfma_f32_16x16x32_bf16 v[62:65], v[138:141], v[166:169], v[62:65]
	s_andn2_b64 vcc, exec, s[8:9]
	s_nop 1
	v_permlane32_swap_b32 v219, v227
	s_nop 1
	s_waitcnt vmcnt(9)
	v_mfma_f32_16x16x32_bf16 v[58:61], v[142:145], v[166:169], v[58:61]
	s_waitcnt vmcnt(8)
	v_mfma_f32_16x16x32_bf16 v[54:57], v[134:137], v[166:169], v[54:57]
	v_mfma_f32_16x16x32_bf16 v[166:169], v[162:165], v[78:81], 0
	v_mfma_f32_16x16x32_bf16 v[170:173], v[154:157], v[78:81], 0
	v_mfma_f32_16x16x32_bf16 v[166:169], v[158:161], v[82:85], v[166:169]
	v_mfma_f32_16x16x32_bf16 v[170:173], v[150:153], v[82:85], v[170:173]
	s_cbranch_vccnz .LBB0_2210
	v_mov_b32_e32 v244, 0x25dfc
	v_cmp_gt_u32_e32 vcc, s85, v216
	v_mov_b32_e32 v193, 0xff800000
	v_mov_b32_e32 v192, 0xff800000
	ds_write_b32 v244, v192 offset:512
	v_min_u32_e32 v192, 0x7f, v216
	v_lshl_add_u32 v192, v192, 2, s87
	v_cndmask_b32_e32 v192, v244, v192, vcc
	ds_read_b32 v192, v192 offset:512
	v_subrev_u32_e32 v194, 48, v215
	v_cmp_gt_u32_e32 vcc, s85, v194
	v_min_u32_e32 v193, 0x7f, v194
	v_lshl_add_u32 v193, v193, 2, s87
	v_cndmask_b32_e32 v193, v244, v193, vcc
	ds_read_b32 v193, v193 offset:512
	v_subrev_u32_e32 v196, 49, v215
	v_cmp_gt_u32_e32 vcc, s85, v196
	v_mov_b32_e32 v195, 0xff800000
	v_mov_b32_e32 v194, 0xff800000
	v_min_u32_e32 v194, 0x7f, v196
	v_lshl_add_u32 v194, v194, 2, s87
	v_cndmask_b32_e32 v194, v244, v194, vcc
	ds_read_b32 v194, v194 offset:512
	v_subrev_u32_e32 v196, 50, v215
	v_cmp_gt_u32_e32 vcc, s85, v196
	v_min_u32_e32 v195, 0x7f, v196
	v_lshl_add_u32 v195, v195, 2, s87
	v_cndmask_b32_e32 v195, v244, v195, vcc
	ds_read_b32 v195, v195 offset:512
	v_subrev_u32_e32 v198, 63, v215
	v_cmp_gt_u32_e32 vcc, s85, v198
	v_mov_b32_e32 v197, 0xff800000
	v_mov_b32_e32 v196, 0xff800000
	v_min_u32_e32 v196, 0x7f, v198
	v_lshl_add_u32 v196, v196, 2, s87
	v_cndmask_b32_e32 v196, v244, v196, vcc
	ds_read_b32 v196, v196 offset:512
	v_subrev_u32_e32 v198, 64, v215
	v_cmp_gt_u32_e32 vcc, s85, v198
	v_min_u32_e32 v197, 0x7f, v198
	v_lshl_add_u32 v197, v197, 2, s87
	v_cndmask_b32_e32 v197, v244, v197, vcc
	ds_read_b32 v197, v197 offset:512
	v_add_u32_e32 v200, 0xffffffbf, v215
	v_cmp_gt_u32_e32 vcc, s85, v200
	v_mov_b32_e32 v199, 0xff800000
	v_mov_b32_e32 v198, 0xff800000
	v_min_u32_e32 v198, 0x7f, v200
	v_lshl_add_u32 v198, v198, 2, s87
	v_cndmask_b32_e32 v198, v244, v198, vcc
	ds_read_b32 v198, v198 offset:512
	v_add_u32_e32 v200, 0xffffffbe, v215
	v_cmp_gt_u32_e32 vcc, s85, v200
	v_min_u32_e32 v199, 0x7f, v200
	v_lshl_add_u32 v199, v199, 2, s87
	v_cndmask_b32_e32 v199, v244, v199, vcc
	ds_read_b32 v199, v199 offset:512
	s_waitcnt lgkmcnt(0)
	v_add_f32_e32 v192, v166, v192
	v_mul_f32_e32 v192, 0x3fb8aa3b, v192
	v_add_f32_e32 v193, v167, v193
	v_mul_f32_e32 v193, 0x3fb8aa3b, v193
	v_add_f32_e32 v194, v168, v194
	v_mul_f32_e32 v194, 0x3fb8aa3b, v194
	v_add_f32_e32 v195, v169, v195
	v_mul_f32_e32 v195, 0x3fb8aa3b, v195
	v_add_f32_e32 v196, v170, v196
	v_mul_f32_e32 v196, 0x3fb8aa3b, v196
	v_add_f32_e32 v197, v171, v197
	v_mul_f32_e32 v197, 0x3fb8aa3b, v197
	v_add_f32_e32 v198, v172, v198
	v_mul_f32_e32 v198, 0x3fb8aa3b, v198
	v_add_f32_e32 v199, v173, v199
	v_mul_f32_e32 v199, 0x3fb8aa3b, v199
	v_max3_f32 v200, v192, s89, v193
	v_max3_f32 v200, v200, v194, v195
	v_max3_f32 v200, v200, v196, v197
	v_max3_f32 v200, v200, v198, v199
	s_mov_b64 s[10:11], 0

.LBB0_2212:
	s_nop 3
	v_mov_b32_e32 v166, v200
	s_nop 1
	v_permlane16_swap_b32 v200, v166
	s_nop 1
	s_mov_b64 s[8:9], -1
	v_max_f32_e32 v166, v166, v166
	v_max_f32_e32 v167, v200, v200
	v_max_f32_e32 v166, v167, v166
	v_mov_b32_e32 v167, v166
	s_nop 1
	v_permlane32_swap_b32 v166, v167
	s_nop 1
	s_and_b64 vcc, exec, s[6:7]
	v_max3_f32 v221, v228, v166, v167
	v_sub_f32_e32 v167, v192, v221
	v_exp_f32_e32 v167, v167
	v_sub_f32_e32 v169, v193, v221
	v_exp_f32_e32 v169, v169
	v_sub_f32_e32 v170, v194, v221
	v_exp_f32_e32 v170, v170
	v_sub_f32_e32 v171, v195, v221
	v_exp_f32_e32 v171, v171
	v_sub_f32_e32 v172, v196, v221
	v_add_f32_e32 v168, 0, v167
	v_exp_f32_e32 v172, v172
	v_sub_f32_e32 v173, v197, v221
	v_add_f32_e32 v168, v169, v168
	v_exp_f32_e32 v173, v173
	v_sub_f32_e32 v192, v198, v221
	v_add_f32_e32 v168, v170, v168
	v_exp_f32_e32 v194, v192
	v_sub_f32_e32 v192, v199, v221
	v_add_f32_e32 v168, v171, v168
	v_exp_f32_e32 v195, v192
	v_add_f32_e32 v168, v172, v168
	v_add_f32_e32 v168, v173, v168
	v_sub_f32_e32 v166, v228, v221
	v_add_f32_e32 v168, v194, v168
	v_add_f32_e32 v168, v195, v168
	v_exp_f32_e32 v192, v166
	v_mov_b32_e32 v166, v168
	s_nop 1
	v_permlane16_swap_b32 v168, v166
	s_nop 1
	s_nop 0
	v_add_f32_e32 v193, v168, v166
	v_mov_b32_e32 v218, v193
	s_nop 1
	v_permlane32_swap_b32 v193, v218
	s_nop 1
	v_cvt_pk_bf16_f32 v166, v167, v169
	v_cvt_pk_bf16_f32 v167, v170, v171
	v_cvt_pk_bf16_f32 v168, v172, v173
	v_cvt_pk_bf16_f32 v169, v194, v195
	v_mfma_f32_16x16x32_bf16 v[170:173], v[154:157], v[86:89], 0
	v_mul_f32_e64 v52, v52, v192
	v_mul_f32_e64 v53, v53, v192
	v_pk_mul_f32 v[50:51], v[50:51], v[192:193] op_sel_hi:[1,0]
	v_pk_mul_f32 v[48:49], v[48:49], v[192:193] op_sel_hi:[1,0]
	v_pk_mul_f32 v[46:47], v[46:47], v[192:193] op_sel_hi:[1,0]
	v_pk_mul_f32 v[44:45], v[44:45], v[192:193] op_sel_hi:[1,0]
	v_pk_mul_f32 v[42:43], v[42:43], v[192:193] op_sel_hi:[1,0]
	v_pk_mul_f32 v[40:41], v[40:41], v[192:193] op_sel_hi:[1,0]
	v_pk_mul_f32 v[38:39], v[38:39], v[192:193] op_sel_hi:[1,0]
	v_mfma_f32_16x16x32_bf16 v[50:53], v[146:149], v[166:169], v[50:53]
	v_mfma_f32_16x16x32_bf16 v[46:49], v[138:141], v[166:169], v[46:49]
	v_mfma_f32_16x16x32_bf16 v[42:45], v[142:145], v[166:169], v[42:45]
	v_mfma_f32_16x16x32_bf16 v[38:41], v[134:137], v[166:169], v[38:41]
	v_mfma_f32_16x16x32_bf16 v[166:169], v[162:165], v[86:89], 0
	v_mfma_f32_16x16x32_bf16 v[166:169], v[158:161], v[90:93], v[166:169]
	v_mfma_f32_16x16x32_bf16 v[170:173], v[150:153], v[90:93], v[170:173]
	s_cbranch_vccnz .LBB0_2230
	v_mov_b32_e32 v244, 0x25bfc
	v_cmp_gt_u32_e32 vcc, s85, v216
	v_mov_b32_e32 v195, 0xff800000
	v_mov_b32_e32 v194, 0xff800000
	ds_write_b32 v244, v194 offset:1024
	v_min_u32_e32 v194, 0x7f, v216
	v_lshl_add_u32 v194, v194, 2, s87
	v_cndmask_b32_e32 v194, v244, v194, vcc
	ds_read_b32 v194, v194 offset:1024
	v_subrev_u32_e32 v196, 48, v215
	v_cmp_gt_u32_e32 vcc, s85, v196
	v_min_u32_e32 v195, 0x7f, v196
	v_lshl_add_u32 v195, v195, 2, s87
	v_cndmask_b32_e32 v195, v244, v195, vcc
	ds_read_b32 v195, v195 offset:1024
	v_subrev_u32_e32 v198, 49, v215
	v_cmp_gt_u32_e32 vcc, s85, v198
	v_mov_b32_e32 v197, 0xff800000
	v_mov_b32_e32 v196, 0xff800000
	v_min_u32_e32 v196, 0x7f, v198
	v_lshl_add_u32 v196, v196, 2, s87
	v_cndmask_b32_e32 v196, v244, v196, vcc
	ds_read_b32 v196, v196 offset:1024
	v_subrev_u32_e32 v198, 50, v215
	v_cmp_gt_u32_e32 vcc, s85, v198
	v_min_u32_e32 v197, 0x7f, v198
	v_lshl_add_u32 v197, v197, 2, s87
	v_cndmask_b32_e32 v197, v244, v197, vcc
	ds_read_b32 v197, v197 offset:1024
	v_subrev_u32_e32 v200, 63, v215
	v_cmp_gt_u32_e32 vcc, s85, v200
	v_mov_b32_e32 v199, 0xff800000
	v_mov_b32_e32 v198, 0xff800000
	v_min_u32_e32 v198, 0x7f, v200
	v_lshl_add_u32 v198, v198, 2, s87
	v_cndmask_b32_e32 v198, v244, v198, vcc
	ds_read_b32 v198, v198 offset:1024
	v_subrev_u32_e32 v200, 64, v215
	v_cmp_gt_u32_e32 vcc, s85, v200
	v_min_u32_e32 v199, 0x7f, v200
	v_lshl_add_u32 v199, v199, 2, s87
	v_cndmask_b32_e32 v199, v244, v199, vcc
	ds_read_b32 v199, v199 offset:1024
	v_add_u32_e32 v217, 0xffffffbf, v215
	v_cmp_gt_u32_e32 vcc, s85, v217
	v_mov_b32_e32 v201, 0xff800000
	v_mov_b32_e32 v200, 0xff800000
	v_min_u32_e32 v200, 0x7f, v217
	v_lshl_add_u32 v200, v200, 2, s87
	v_cndmask_b32_e32 v200, v244, v200, vcc
	ds_read_b32 v200, v200 offset:1024
	v_add_u32_e32 v217, 0xffffffbe, v215
	v_cmp_gt_u32_e32 vcc, s85, v217
	v_min_u32_e32 v201, 0x7f, v217
	v_lshl_add_u32 v201, v201, 2, s87
	v_cndmask_b32_e32 v201, v244, v201, vcc
	ds_read_b32 v201, v201 offset:1024
	s_waitcnt lgkmcnt(0)
	v_add_f32_e32 v194, v166, v194
	v_mul_f32_e32 v194, 0x3fb8aa3b, v194
	v_add_f32_e32 v195, v167, v195
	v_mul_f32_e32 v195, 0x3fb8aa3b, v195
	v_add_f32_e32 v196, v168, v196
	v_mul_f32_e32 v196, 0x3fb8aa3b, v196
	v_add_f32_e32 v197, v169, v197
	v_mul_f32_e32 v197, 0x3fb8aa3b, v197
	v_add_f32_e32 v198, v170, v198
	v_mul_f32_e32 v198, 0x3fb8aa3b, v198
	v_add_f32_e32 v199, v171, v199
	v_mul_f32_e32 v199, 0x3fb8aa3b, v199
	v_add_f32_e32 v200, v172, v200
	v_mul_f32_e32 v200, 0x3fb8aa3b, v200
	v_add_f32_e32 v201, v173, v201
	v_mul_f32_e32 v201, 0x3fb8aa3b, v201
	v_max3_f32 v217, v194, s89, v195
	v_max3_f32 v217, v217, v196, v197
	v_max3_f32 v217, v217, v198, v199
	v_max3_f32 v217, v217, v200, v201
	s_mov_b64 s[8:9], 0

.LBB0_2232:
	s_nop 3
	v_mov_b32_e32 v166, v217
	s_nop 1
	v_permlane16_swap_b32 v217, v166
	s_nop 1
	v_mfma_f32_16x16x32_bf16 v[162:165], v[162:165], v[94:97], 0
	v_max_f32_e32 v166, v166, v166
	v_max_f32_e32 v167, v217, v217
	v_max_f32_e32 v166, v167, v166
	v_mov_b32_e32 v167, v166
	s_nop 1
	v_permlane32_swap_b32 v166, v167
	s_nop 1
	v_mfma_f32_16x16x32_bf16 v[154:157], v[154:157], v[94:97], 0
	v_max3_f32 v220, v229, v166, v167
	v_sub_f32_e32 v168, v195, v220
	v_exp_f32_e32 v172, v168
	v_sub_f32_e32 v168, v196, v220
	v_sub_f32_e32 v166, v229, v220
	v_sub_f32_e32 v167, v194, v220
	v_exp_f32_e32 v173, v168
	v_sub_f32_e32 v168, v197, v220
	v_exp_f32_e32 v167, v167
	v_exp_f32_e32 v194, v168
	v_sub_f32_e32 v168, v198, v220
	v_exp_f32_e32 v166, v166
	v_exp_f32_e32 v195, v168
	v_sub_f32_e32 v168, v199, v220
	v_exp_f32_e32 v196, v168
	v_sub_f32_e32 v168, v200, v220
	v_exp_f32_e32 v197, v168
	v_sub_f32_e32 v168, v201, v220
	v_exp_f32_e32 v198, v168
	v_cvt_pk_bf16_f32 v168, v167, v172
	v_pk_mul_f32 v[36:37], v[36:37], v[166:167] op_sel_hi:[1,0]
	v_pk_mul_f32 v[34:35], v[34:35], v[166:167] op_sel_hi:[1,0]
	v_pk_mul_f32 v[32:33], v[32:33], v[166:167] op_sel_hi:[1,0]
	v_pk_mul_f32 v[30:31], v[30:31], v[166:167] op_sel_hi:[1,0]
	v_pk_mul_f32 v[28:29], v[28:29], v[166:167] op_sel_hi:[1,0]
	v_pk_mul_f32 v[26:27], v[26:27], v[166:167] op_sel_hi:[1,0]
	v_add_f32_e32 v167, 0, v167
	v_pk_mul_f32 v[24:25], v[24:25], v[166:167] op_sel_hi:[1,0]
	v_pk_mul_f32 v[22:23], v[22:23], v[166:167] op_sel_hi:[1,0]
	v_add_f32_e32 v167, v172, v167
	v_add_f32_e32 v167, v173, v167
	v_add_f32_e32 v167, v194, v167
	v_add_f32_e32 v167, v195, v167
	v_add_f32_e32 v167, v196, v167
	v_add_f32_e32 v167, v197, v167
	v_cvt_pk_bf16_f32 v169, v173, v194
	v_cvt_pk_bf16_f32 v170, v195, v196
	v_cvt_pk_bf16_f32 v171, v197, v198
	v_mfma_f32_16x16x32_bf16 v[158:161], v[158:161], v[98:101], v[162:165]
	s_and_b64 vcc, exec, s[6:7]
	s_mov_b64 s[6:7], -1
	v_mfma_f32_16x16x32_bf16 v[34:37], v[146:149], v[168:171], v[34:37]
	v_add_f32_e32 v162, v198, v167
	v_mov_b32_e32 v163, v162
	s_nop 1
	v_permlane16_swap_b32 v162, v163
	s_nop 1
	v_mfma_f32_16x16x32_bf16 v[30:33], v[138:141], v[168:171], v[30:33]
	v_add_f32_e32 v167, v162, v163
	v_mfma_f32_16x16x32_bf16 v[26:29], v[142:145], v[168:171], v[26:29]
	v_mfma_f32_16x16x32_bf16 v[22:25], v[134:137], v[168:171], v[22:25]
	v_mov_b32_e32 v168, v167
	s_nop 1
	v_permlane32_swap_b32 v167, v168
	s_nop 1
	v_mfma_f32_16x16x32_bf16 v[150:153], v[150:153], v[98:101], v[154:157]
	s_cbranch_vccnz .LBB0_2250
	v_mov_b32_e32 v244, 0x259fc
	v_cmp_gt_u32_e32 vcc, s85, v216
	s_nop 0
	v_mov_b32_e32 v155, 0xff800000
	v_mov_b32_e32 v154, 0xff800000
	ds_write_b32 v244, v154 offset:1536
	v_min_u32_e32 v154, 0x7f, v216
	v_lshl_add_u32 v154, v154, 2, s87
	v_cndmask_b32_e32 v154, v244, v154, vcc
	ds_read_b32 v154, v154 offset:1536
	v_subrev_u32_e32 v156, 48, v215
	v_cmp_gt_u32_e32 vcc, s85, v156
	v_min_u32_e32 v155, 0x7f, v156
	v_lshl_add_u32 v155, v155, 2, s87
	v_cndmask_b32_e32 v155, v244, v155, vcc
	ds_read_b32 v155, v155 offset:1536
	v_subrev_u32_e32 v162, 49, v215
	v_cmp_gt_u32_e32 vcc, s85, v162
	v_mov_b32_e32 v157, 0xff800000
	v_mov_b32_e32 v156, 0xff800000
	v_min_u32_e32 v156, 0x7f, v162
	v_lshl_add_u32 v156, v156, 2, s87
	v_cndmask_b32_e32 v156, v244, v156, vcc
	ds_read_b32 v156, v156 offset:1536
	v_subrev_u32_e32 v162, 50, v215
	v_cmp_gt_u32_e32 vcc, s85, v162
	v_min_u32_e32 v157, 0x7f, v162
	v_lshl_add_u32 v157, v157, 2, s87
	v_cndmask_b32_e32 v157, v244, v157, vcc
	ds_read_b32 v157, v157 offset:1536
	v_subrev_u32_e32 v164, 63, v215
	v_cmp_gt_u32_e32 vcc, s85, v164
	v_mov_b32_e32 v163, 0xff800000
	v_mov_b32_e32 v162, 0xff800000
	v_min_u32_e32 v162, 0x7f, v164
	v_lshl_add_u32 v162, v162, 2, s87
	v_cndmask_b32_e32 v162, v244, v162, vcc
	ds_read_b32 v162, v162 offset:1536
	v_subrev_u32_e32 v164, 64, v215
	v_cmp_gt_u32_e32 vcc, s85, v164
	v_min_u32_e32 v163, 0x7f, v164
	v_lshl_add_u32 v163, v163, 2, s87
	v_cndmask_b32_e32 v163, v244, v163, vcc
	ds_read_b32 v163, v163 offset:1536
	v_add_u32_e32 v169, 0xffffffbf, v215
	v_cmp_gt_u32_e32 vcc, s85, v169
	v_mov_b32_e32 v165, 0xff800000
	v_mov_b32_e32 v164, 0xff800000
	v_min_u32_e32 v164, 0x7f, v169
	v_lshl_add_u32 v164, v164, 2, s87
	v_cndmask_b32_e32 v164, v244, v164, vcc
	ds_read_b32 v164, v164 offset:1536
	v_add_u32_e32 v169, 0xffffffbe, v215
	v_cmp_gt_u32_e32 vcc, s85, v169
	v_min_u32_e32 v165, 0x7f, v169
	v_lshl_add_u32 v165, v165, 2, s87
	v_cndmask_b32_e32 v165, v244, v165, vcc
	ds_read_b32 v165, v165 offset:1536
	s_waitcnt lgkmcnt(0)
	v_add_f32_e32 v154, v158, v154
	v_mul_f32_e32 v154, 0x3fb8aa3b, v154
	v_add_f32_e32 v155, v159, v155
	v_mul_f32_e32 v155, 0x3fb8aa3b, v155
	v_add_f32_e32 v156, v160, v156
	v_mul_f32_e32 v156, 0x3fb8aa3b, v156
	v_add_f32_e32 v157, v161, v157
	v_mul_f32_e32 v157, 0x3fb8aa3b, v157
	v_add_f32_e32 v162, v150, v162
	v_mul_f32_e32 v162, 0x3fb8aa3b, v162
	v_add_f32_e32 v163, v151, v163
	v_mul_f32_e32 v163, 0x3fb8aa3b, v163
	v_add_f32_e32 v164, v152, v164
	v_mul_f32_e32 v164, 0x3fb8aa3b, v164
	v_add_f32_e32 v165, v153, v165
	v_mul_f32_e32 v165, 0x3fb8aa3b, v165
	v_max3_f32 v169, v154, s89, v155
	v_max3_f32 v169, v169, v156, v157
	v_max3_f32 v169, v169, v162, v163
	v_max3_f32 v169, v169, v164, v165
	s_mov_b64 s[6:7], 0

.LBB0_2465:
	s_endpgm
